# v55 + P0P: prologue adaLN GEMV streams its weight rows through a four-deep register ring (unrolled)
# baseline (speedup 1.0000x reference)
; __global__ void __launch_bounds__(NTHR, 2) trunk_fwd(Args a) {
;     ...
;         for (int unit = bx; unit < DEPTH * 48; unit += G) { const int l = unit / 48, n = (unit % 48) * 128 + 2 * lane;
;             const float* wp = a.w_ada + ((size_t)l * 1024 + wave * 128) * 6144 + n; float acc0[9], acc1[9];
; #pragma unroll
;             for (int q = 0; q < 9; ++q) { acc0[q] = 0.f; acc1[q] = 0.f; }
; #pragma unroll 1
;             for (int k0 = 0; k0 < 128; k0 += 8) { float2 wv[8];
; #pragma unroll
;                 for (int k = 0; k < 8; ++k) wv[k] = *(const float2*)(wp + (size_t)(k0 + k) * 6144);
; #pragma unroll
;                 for (int k = 0; k < 8; ++k)
; #pragma unroll
;                     for (int q = 0; q < 9; ++q) { const float sv = sS[q * 1024 + wave * 128 + k0 + k]; acc0[q] += sv * wv[k].x; acc1[q] += sv * wv[k].y; } }
.LBB0_22:
	s_mul_hi_i32 s4, s27, 0x2aaaaaab
	s_lshr_b32 s5, s4, 31
	s_ashr_i32 s4, s4, 3
	s_add_i32 s10, s4, s5
	s_mul_i32 s4, s10, 0x1800000
	v_lshl_or_b32 v6, s27, 7, v1
	s_mul_i32 s8, s10, 0x1800
	s_mul_hi_i32 s5, s10, 0x1800000
	v_subrev_u32_e32 v6, s8, v6
	s_add_u32 s4, s17, s4
	v_ashrrev_i32_e32 v7, 31, v6
	s_addc_u32 s5, s18, s5
	v_mov_b32_e32 v8, 0
	v_lshl_add_u64 v[6:7], v[6:7], 2, s[4:5]
	s_mov_b32 s8, -8
	s_mov_b32 s9, s15
	v_mov_b32_e32 v12, 0
	v_mov_b32_e32 v10, 0
	v_mov_b32_e32 v16, 0
	v_mov_b32_e32 v14, 0
	v_mov_b32_e32 v20, 0
	v_mov_b32_e32 v18, 0
	v_mov_b32_e32 v24, 0
	v_mov_b32_e32 v22, 0
	v_mov_b32_e32 v9, v8
	v_mov_b32_e32 v13, v8
	v_mov_b32_e32 v11, v8
	v_mov_b32_e32 v17, v8
	v_mov_b32_e32 v15, v8
	v_mov_b32_e32 v21, v8
	v_mov_b32_e32 v19, v8
	v_mov_b32_e32 v25, v8
	v_mov_b32_e32 v23, v8
	s_mov_b64 s[28:29], 0x6000
	v_add_co_u32_e64 v246, s[4:5], s19, v6
	s_nop 1
	v_addc_co_u32_e64 v247, s[4:5], -1, v7, s[4:5]
	global_load_dwordx2 v[100:101], v[246:247], off
	v_lshl_add_u64 v[248:249], v[246:247], 0, s[28:29]
	global_load_dwordx2 v[102:103], v[248:249], off
	v_lshl_add_u64 v[248:249], v[248:249], 0, s[28:29]
	global_load_dwordx2 v[104:105], v[248:249], off
	v_lshl_add_u64 v[248:249], v[248:249], 0, s[28:29]
	global_load_dwordx2 v[106:107], v[248:249], off
	v_lshl_add_u64 v[248:249], v[248:249], 0, s[28:29]
	global_load_dwordx2 v[108:109], v[248:249], off
	v_lshl_add_u64 v[248:249], v[248:249], 0, s[28:29]
	global_load_dwordx2 v[110:111], v[248:249], off
	v_lshl_add_u64 v[248:249], v[248:249], 0, s[28:29]
	global_load_dwordx2 v[112:113], v[248:249], off
	v_lshl_add_u64 v[248:249], v[248:249], 0, s[28:29]
	global_load_dwordx2 v[114:115], v[248:249], off
	v_lshl_add_u64 v[246:247], v[246:247], 0, s[6:7]
	global_load_dwordx2 v[194:195], v[246:247], off
	v_lshl_add_u64 v[248:249], v[246:247], 0, s[28:29]
	global_load_dwordx2 v[196:197], v[248:249], off
	v_lshl_add_u64 v[248:249], v[248:249], 0, s[28:29]
	global_load_dwordx2 v[198:199], v[248:249], off
	v_lshl_add_u64 v[248:249], v[248:249], 0, s[28:29]
	global_load_dwordx2 v[200:201], v[248:249], off
	v_lshl_add_u64 v[248:249], v[248:249], 0, s[28:29]
	global_load_dwordx2 v[202:203], v[248:249], off
	v_lshl_add_u64 v[248:249], v[248:249], 0, s[28:29]
	global_load_dwordx2 v[204:205], v[248:249], off
	v_lshl_add_u64 v[248:249], v[248:249], 0, s[28:29]
	global_load_dwordx2 v[206:207], v[248:249], off
	v_lshl_add_u64 v[248:249], v[248:249], 0, s[28:29]
	global_load_dwordx2 v[208:209], v[248:249], off
	v_lshl_add_u64 v[246:247], v[246:247], 0, s[6:7]
	global_load_dwordx2 v[214:215], v[246:247], off
	v_lshl_add_u64 v[248:249], v[246:247], 0, s[28:29]
	global_load_dwordx2 v[216:217], v[248:249], off
	v_lshl_add_u64 v[248:249], v[248:249], 0, s[28:29]
	global_load_dwordx2 v[218:219], v[248:249], off
	v_lshl_add_u64 v[248:249], v[248:249], 0, s[28:29]
	global_load_dwordx2 v[220:221], v[248:249], off
	v_lshl_add_u64 v[248:249], v[248:249], 0, s[28:29]
	global_load_dwordx2 v[222:223], v[248:249], off
	v_lshl_add_u64 v[248:249], v[248:249], 0, s[28:29]
	global_load_dwordx2 v[224:225], v[248:249], off
	v_lshl_add_u64 v[248:249], v[248:249], 0, s[28:29]
	global_load_dwordx2 v[226:227], v[248:249], off
	v_lshl_add_u64 v[248:249], v[248:249], 0, s[28:29]
	global_load_dwordx2 v[228:229], v[248:249], off
	v_lshl_add_u64 v[246:247], v[246:247], 0, s[6:7]
	global_load_dwordx2 v[230:231], v[246:247], off
	v_lshl_add_u64 v[248:249], v[246:247], 0, s[28:29]
	global_load_dwordx2 v[232:233], v[248:249], off
	v_lshl_add_u64 v[248:249], v[248:249], 0, s[28:29]
	global_load_dwordx2 v[234:235], v[248:249], off
	v_lshl_add_u64 v[248:249], v[248:249], 0, s[28:29]
	global_load_dwordx2 v[236:237], v[248:249], off
	v_lshl_add_u64 v[248:249], v[248:249], 0, s[28:29]
	global_load_dwordx2 v[238:239], v[248:249], off
	v_lshl_add_u64 v[248:249], v[248:249], 0, s[28:29]
	global_load_dwordx2 v[240:241], v[248:249], off
	v_lshl_add_u64 v[248:249], v[248:249], 0, s[28:29]
	global_load_dwordx2 v[242:243], v[248:249], off
	v_lshl_add_u64 v[248:249], v[248:249], 0, s[28:29]
	global_load_dwordx2 v[244:245], v[248:249], off
	v_lshl_add_u64 v[246:247], v[246:247], 0, s[6:7]
	v_mov_b32_e32 v27, s9
	s_add_i32 s9, s9, 32
	ds_read_b128 v[28:31], v27
	ds_read_b128 v[32:35], v27 offset:16
	ds_read_b128 v[36:39], v27 offset:4096
	ds_read_b128 v[40:43], v27 offset:4112
	ds_read_b128 v[44:47], v27 offset:8192
	ds_read_b128 v[48:51], v27 offset:8208
	ds_read_b128 v[52:55], v27 offset:12288
	ds_read_b128 v[56:59], v27 offset:12304
	ds_read_b128 v[60:63], v27 offset:16384
	ds_read_b128 v[64:67], v27 offset:16400
	ds_read_b128 v[68:71], v27 offset:20480
	ds_read_b128 v[72:75], v27 offset:20496
	ds_read_b128 v[76:79], v27 offset:24576
	ds_read_b128 v[80:83], v27 offset:24592
	ds_read_b128 v[84:87], v27 offset:28672
	ds_read_b128 v[88:91], v27 offset:28688
	ds_read_b128 v[92:95], v27 offset:32768
	ds_read_b128 v[96:99], v27 offset:32784
	s_waitcnt lgkmcnt(14)
	v_mov_b32_e32 v116, v31
	v_mov_b32_e32 v118, v39
	s_waitcnt lgkmcnt(13)
	v_mov_b32_e32 v120, v47
	s_waitcnt lgkmcnt(11)
	v_mov_b32_e32 v122, v55
	s_waitcnt lgkmcnt(9)
	v_mov_b32_e32 v124, v63
	s_waitcnt lgkmcnt(7)
	v_mov_b32_e32 v126, v71
	s_waitcnt lgkmcnt(5)
	v_mov_b32_e32 v128, v79
	s_waitcnt lgkmcnt(3)
	v_mov_b32_e32 v130, v87
	s_waitcnt lgkmcnt(1)
	v_mov_b32_e32 v138, v95
	v_mov_b32_e32 v132, v35
	v_mov_b32_e32 v134, v43
	v_mov_b32_e32 v136, v51
	v_mov_b32_e32 v140, v59
	v_mov_b32_e32 v142, v67
	v_mov_b32_e32 v144, v75
	v_mov_b32_e32 v146, v83
	v_mov_b32_e32 v148, v91
	s_waitcnt lgkmcnt(0)
	v_mov_b32_e32 v150, v99
	s_waitcnt vmcnt(31)
; __global__ void __launch_bounds__(NTHR, 2) trunk_fwd(Args a) {
;     ...
;             for (int k0 = 0; k0 < 128; k0 += 8) { float2 wv[8];
; #pragma unroll
;                 for (int k = 0; k < 8; ++k) wv[k] = *(const float2*)(wp + (size_t)(k0 + k) * 6144);
; #pragma unroll
;                 for (int k = 0; k < 8; ++k)
; #pragma unroll
;                     for (int q = 0; q < 9; ++q) { const float sv = sS[q * 1024 + wave * 128 + k0 + k]; acc0[q] += sv * wv[k].x; acc1[q] += sv * wv[k].y; } }
	v_pk_fma_f32 v[8:9], v[28:29], v[100:101], v[8:9] op_sel_hi:[0,1,1]
	v_pk_fma_f32 v[12:13], v[36:37], v[100:101], v[12:13] op_sel_hi:[0,1,1]
	v_pk_fma_f32 v[10:11], v[44:45], v[100:101], v[10:11] op_sel_hi:[0,1,1]
	v_pk_fma_f32 v[16:17], v[52:53], v[100:101], v[16:17] op_sel_hi:[0,1,1]
	v_pk_fma_f32 v[14:15], v[60:61], v[100:101], v[14:15] op_sel_hi:[0,1,1]
	v_pk_fma_f32 v[20:21], v[68:69], v[100:101], v[20:21] op_sel_hi:[0,1,1]
	v_pk_fma_f32 v[18:19], v[76:77], v[100:101], v[18:19] op_sel_hi:[0,1,1]
	v_pk_fma_f32 v[24:25], v[84:85], v[100:101], v[24:25] op_sel_hi:[0,1,1]
	v_pk_fma_f32 v[22:23], v[92:93], v[100:101], v[22:23] op_sel_hi:[0,1,1]
	s_waitcnt vmcnt(30)
	v_pk_fma_f32 v[8:9], v[28:29], v[102:103], v[8:9] op_sel:[1,0,0]
	v_pk_fma_f32 v[12:13], v[36:37], v[102:103], v[12:13] op_sel:[1,0,0]
	v_pk_fma_f32 v[10:11], v[44:45], v[102:103], v[10:11] op_sel:[1,0,0]
	v_pk_fma_f32 v[16:17], v[52:53], v[102:103], v[16:17] op_sel:[1,0,0]
	v_pk_fma_f32 v[14:15], v[60:61], v[102:103], v[14:15] op_sel:[1,0,0]
	v_pk_fma_f32 v[20:21], v[68:69], v[102:103], v[20:21] op_sel:[1,0,0]
	v_pk_fma_f32 v[18:19], v[76:77], v[102:103], v[18:19] op_sel:[1,0,0]
	v_pk_fma_f32 v[24:25], v[84:85], v[102:103], v[24:25] op_sel:[1,0,0]
	v_pk_fma_f32 v[22:23], v[92:93], v[102:103], v[22:23] op_sel:[1,0,0]
	s_waitcnt vmcnt(29)
	v_pk_fma_f32 v[8:9], v[30:31], v[104:105], v[8:9] op_sel_hi:[0,1,1]
	v_pk_fma_f32 v[12:13], v[38:39], v[104:105], v[12:13] op_sel_hi:[0,1,1]
	v_pk_fma_f32 v[10:11], v[46:47], v[104:105], v[10:11] op_sel_hi:[0,1,1]
	v_pk_fma_f32 v[16:17], v[54:55], v[104:105], v[16:17] op_sel_hi:[0,1,1]
	v_pk_fma_f32 v[14:15], v[62:63], v[104:105], v[14:15] op_sel_hi:[0,1,1]
	v_pk_fma_f32 v[20:21], v[70:71], v[104:105], v[20:21] op_sel_hi:[0,1,1]
	v_pk_fma_f32 v[18:19], v[78:79], v[104:105], v[18:19] op_sel_hi:[0,1,1]
	v_pk_fma_f32 v[24:25], v[86:87], v[104:105], v[24:25] op_sel_hi:[0,1,1]
	v_pk_fma_f32 v[22:23], v[94:95], v[104:105], v[22:23] op_sel_hi:[0,1,1]
	s_waitcnt vmcnt(28)
	v_pk_fma_f32 v[8:9], v[116:117], v[106:107], v[8:9] op_sel_hi:[0,1,1]
	v_pk_fma_f32 v[12:13], v[118:119], v[106:107], v[12:13] op_sel_hi:[0,1,1]
	v_pk_fma_f32 v[10:11], v[120:121], v[106:107], v[10:11] op_sel_hi:[0,1,1]
	v_pk_fma_f32 v[16:17], v[122:123], v[106:107], v[16:17] op_sel_hi:[0,1,1]
	v_pk_fma_f32 v[14:15], v[124:125], v[106:107], v[14:15] op_sel_hi:[0,1,1]
	v_pk_fma_f32 v[20:21], v[126:127], v[106:107], v[20:21] op_sel_hi:[0,1,1]
	v_pk_fma_f32 v[18:19], v[128:129], v[106:107], v[18:19] op_sel_hi:[0,1,1]
	v_pk_fma_f32 v[24:25], v[130:131], v[106:107], v[24:25] op_sel_hi:[0,1,1]
	v_pk_fma_f32 v[22:23], v[138:139], v[106:107], v[22:23] op_sel_hi:[0,1,1]
	s_waitcnt vmcnt(27)
	v_pk_fma_f32 v[8:9], v[32:33], v[108:109], v[8:9] op_sel_hi:[0,1,1]
	v_pk_fma_f32 v[12:13], v[40:41], v[108:109], v[12:13] op_sel_hi:[0,1,1]
	v_pk_fma_f32 v[10:11], v[48:49], v[108:109], v[10:11] op_sel_hi:[0,1,1]
	v_pk_fma_f32 v[16:17], v[56:57], v[108:109], v[16:17] op_sel_hi:[0,1,1]
	v_pk_fma_f32 v[14:15], v[64:65], v[108:109], v[14:15] op_sel_hi:[0,1,1]
	v_pk_fma_f32 v[20:21], v[72:73], v[108:109], v[20:21] op_sel_hi:[0,1,1]
	v_pk_fma_f32 v[18:19], v[80:81], v[108:109], v[18:19] op_sel_hi:[0,1,1]
	v_pk_fma_f32 v[24:25], v[88:89], v[108:109], v[24:25] op_sel_hi:[0,1,1]
	v_pk_fma_f32 v[22:23], v[96:97], v[108:109], v[22:23] op_sel_hi:[0,1,1]
	s_waitcnt vmcnt(26)
	v_pk_fma_f32 v[8:9], v[32:33], v[110:111], v[8:9] op_sel:[1,0,0]
	v_pk_fma_f32 v[12:13], v[40:41], v[110:111], v[12:13] op_sel:[1,0,0]
	v_pk_fma_f32 v[10:11], v[48:49], v[110:111], v[10:11] op_sel:[1,0,0]
	v_pk_fma_f32 v[16:17], v[56:57], v[110:111], v[16:17] op_sel:[1,0,0]
	v_pk_fma_f32 v[14:15], v[64:65], v[110:111], v[14:15] op_sel:[1,0,0]
	v_pk_fma_f32 v[20:21], v[72:73], v[110:111], v[20:21] op_sel:[1,0,0]
	v_pk_fma_f32 v[18:19], v[80:81], v[110:111], v[18:19] op_sel:[1,0,0]
	v_pk_fma_f32 v[24:25], v[88:89], v[110:111], v[24:25] op_sel:[1,0,0]
	v_pk_fma_f32 v[22:23], v[96:97], v[110:111], v[22:23] op_sel:[1,0,0]
	s_waitcnt vmcnt(25)
	v_pk_fma_f32 v[8:9], v[34:35], v[112:113], v[8:9] op_sel_hi:[0,1,1]
	v_pk_fma_f32 v[12:13], v[42:43], v[112:113], v[12:13] op_sel_hi:[0,1,1]
	v_pk_fma_f32 v[10:11], v[50:51], v[112:113], v[10:11] op_sel_hi:[0,1,1]
	v_pk_fma_f32 v[16:17], v[58:59], v[112:113], v[16:17] op_sel_hi:[0,1,1]
	v_pk_fma_f32 v[14:15], v[66:67], v[112:113], v[14:15] op_sel_hi:[0,1,1]
	v_pk_fma_f32 v[20:21], v[74:75], v[112:113], v[20:21] op_sel_hi:[0,1,1]
	v_pk_fma_f32 v[18:19], v[82:83], v[112:113], v[18:19] op_sel_hi:[0,1,1]
	v_pk_fma_f32 v[24:25], v[90:91], v[112:113], v[24:25] op_sel_hi:[0,1,1]
	v_pk_fma_f32 v[22:23], v[98:99], v[112:113], v[22:23] op_sel_hi:[0,1,1]
	s_waitcnt vmcnt(24)
; __global__ void __launch_bounds__(NTHR, 2) trunk_fwd(Args a) {
;     ...
;             for (int k0 = 0; k0 < 128; k0 += 8) { float2 wv[8];
; #pragma unroll
;                 for (int k = 0; k < 8; ++k) wv[k] = *(const float2*)(wp + (size_t)(k0 + k) * 6144);
; #pragma unroll
;                 for (int k = 0; k < 8; ++k)
; #pragma unroll
;                     for (int q = 0; q < 9; ++q) { const float sv = sS[q * 1024 + wave * 128 + k0 + k]; acc0[q] += sv * wv[k].x; acc1[q] += sv * wv[k].y; } }
	v_pk_fma_f32 v[8:9], v[132:133], v[114:115], v[8:9] op_sel_hi:[0,1,1]
	v_pk_fma_f32 v[12:13], v[134:135], v[114:115], v[12:13] op_sel_hi:[0,1,1]
	v_pk_fma_f32 v[10:11], v[136:137], v[114:115], v[10:11] op_sel_hi:[0,1,1]
	v_pk_fma_f32 v[16:17], v[140:141], v[114:115], v[16:17] op_sel_hi:[0,1,1]
	v_pk_fma_f32 v[14:15], v[142:143], v[114:115], v[14:15] op_sel_hi:[0,1,1]
	v_pk_fma_f32 v[20:21], v[144:145], v[114:115], v[20:21] op_sel_hi:[0,1,1]
	v_pk_fma_f32 v[18:19], v[146:147], v[114:115], v[18:19] op_sel_hi:[0,1,1]
	v_pk_fma_f32 v[24:25], v[148:149], v[114:115], v[24:25] op_sel_hi:[0,1,1]
	v_pk_fma_f32 v[22:23], v[150:151], v[114:115], v[22:23] op_sel_hi:[0,1,1]
	global_load_dwordx2 v[100:101], v[246:247], off
	v_lshl_add_u64 v[248:249], v[246:247], 0, s[28:29]
	global_load_dwordx2 v[102:103], v[248:249], off
	v_lshl_add_u64 v[248:249], v[248:249], 0, s[28:29]
	global_load_dwordx2 v[104:105], v[248:249], off
	v_lshl_add_u64 v[248:249], v[248:249], 0, s[28:29]
	global_load_dwordx2 v[106:107], v[248:249], off
	v_lshl_add_u64 v[248:249], v[248:249], 0, s[28:29]
	global_load_dwordx2 v[108:109], v[248:249], off
	v_lshl_add_u64 v[248:249], v[248:249], 0, s[28:29]
	global_load_dwordx2 v[110:111], v[248:249], off
	v_lshl_add_u64 v[248:249], v[248:249], 0, s[28:29]
	global_load_dwordx2 v[112:113], v[248:249], off
	v_lshl_add_u64 v[248:249], v[248:249], 0, s[28:29]
	global_load_dwordx2 v[114:115], v[248:249], off
	v_lshl_add_u64 v[246:247], v[246:247], 0, s[6:7]
	v_mov_b32_e32 v27, s9
	s_add_i32 s9, s9, 32
	ds_read_b128 v[28:31], v27
	ds_read_b128 v[32:35], v27 offset:16
	ds_read_b128 v[36:39], v27 offset:4096
	ds_read_b128 v[40:43], v27 offset:4112
	ds_read_b128 v[44:47], v27 offset:8192
	ds_read_b128 v[48:51], v27 offset:8208
	ds_read_b128 v[52:55], v27 offset:12288
	ds_read_b128 v[56:59], v27 offset:12304
	ds_read_b128 v[60:63], v27 offset:16384
	ds_read_b128 v[64:67], v27 offset:16400
	ds_read_b128 v[68:71], v27 offset:20480
	ds_read_b128 v[72:75], v27 offset:20496
	ds_read_b128 v[76:79], v27 offset:24576
	ds_read_b128 v[80:83], v27 offset:24592
	ds_read_b128 v[84:87], v27 offset:28672
	ds_read_b128 v[88:91], v27 offset:28688
	ds_read_b128 v[92:95], v27 offset:32768
	ds_read_b128 v[96:99], v27 offset:32784
	s_waitcnt lgkmcnt(14)
	v_mov_b32_e32 v116, v31
	v_mov_b32_e32 v118, v39
	s_waitcnt lgkmcnt(13)
	v_mov_b32_e32 v120, v47
	s_waitcnt lgkmcnt(11)
	v_mov_b32_e32 v122, v55
	s_waitcnt lgkmcnt(9)
	v_mov_b32_e32 v124, v63
	s_waitcnt lgkmcnt(7)
	v_mov_b32_e32 v126, v71
	s_waitcnt lgkmcnt(5)
	v_mov_b32_e32 v128, v79
	s_waitcnt lgkmcnt(3)
	v_mov_b32_e32 v130, v87
	s_waitcnt lgkmcnt(1)
	v_mov_b32_e32 v138, v95
	v_mov_b32_e32 v132, v35
	v_mov_b32_e32 v134, v43
	v_mov_b32_e32 v136, v51
	v_mov_b32_e32 v140, v59
	v_mov_b32_e32 v142, v67
	v_mov_b32_e32 v144, v75
	v_mov_b32_e32 v146, v83
	v_mov_b32_e32 v148, v91
	s_waitcnt lgkmcnt(0)
	v_mov_b32_e32 v150, v99
	s_waitcnt vmcnt(31)
	v_pk_fma_f32 v[8:9], v[28:29], v[194:195], v[8:9] op_sel_hi:[0,1,1]
	v_pk_fma_f32 v[12:13], v[36:37], v[194:195], v[12:13] op_sel_hi:[0,1,1]
	v_pk_fma_f32 v[10:11], v[44:45], v[194:195], v[10:11] op_sel_hi:[0,1,1]
	v_pk_fma_f32 v[16:17], v[52:53], v[194:195], v[16:17] op_sel_hi:[0,1,1]
	v_pk_fma_f32 v[14:15], v[60:61], v[194:195], v[14:15] op_sel_hi:[0,1,1]
	v_pk_fma_f32 v[20:21], v[68:69], v[194:195], v[20:21] op_sel_hi:[0,1,1]
	v_pk_fma_f32 v[18:19], v[76:77], v[194:195], v[18:19] op_sel_hi:[0,1,1]
	v_pk_fma_f32 v[24:25], v[84:85], v[194:195], v[24:25] op_sel_hi:[0,1,1]
	v_pk_fma_f32 v[22:23], v[92:93], v[194:195], v[22:23] op_sel_hi:[0,1,1]
	s_waitcnt vmcnt(30)
	v_pk_fma_f32 v[8:9], v[28:29], v[196:197], v[8:9] op_sel:[1,0,0]
	v_pk_fma_f32 v[12:13], v[36:37], v[196:197], v[12:13] op_sel:[1,0,0]
	v_pk_fma_f32 v[10:11], v[44:45], v[196:197], v[10:11] op_sel:[1,0,0]
	v_pk_fma_f32 v[16:17], v[52:53], v[196:197], v[16:17] op_sel:[1,0,0]
	v_pk_fma_f32 v[14:15], v[60:61], v[196:197], v[14:15] op_sel:[1,0,0]
	v_pk_fma_f32 v[20:21], v[68:69], v[196:197], v[20:21] op_sel:[1,0,0]
	v_pk_fma_f32 v[18:19], v[76:77], v[196:197], v[18:19] op_sel:[1,0,0]
	v_pk_fma_f32 v[24:25], v[84:85], v[196:197], v[24:25] op_sel:[1,0,0]
	v_pk_fma_f32 v[22:23], v[92:93], v[196:197], v[22:23] op_sel:[1,0,0]
	s_waitcnt vmcnt(29)
	v_pk_fma_f32 v[8:9], v[30:31], v[198:199], v[8:9] op_sel_hi:[0,1,1]
	v_pk_fma_f32 v[12:13], v[38:39], v[198:199], v[12:13] op_sel_hi:[0,1,1]
	v_pk_fma_f32 v[10:11], v[46:47], v[198:199], v[10:11] op_sel_hi:[0,1,1]
	v_pk_fma_f32 v[16:17], v[54:55], v[198:199], v[16:17] op_sel_hi:[0,1,1]
	v_pk_fma_f32 v[14:15], v[62:63], v[198:199], v[14:15] op_sel_hi:[0,1,1]
	v_pk_fma_f32 v[20:21], v[70:71], v[198:199], v[20:21] op_sel_hi:[0,1,1]
	v_pk_fma_f32 v[18:19], v[78:79], v[198:199], v[18:19] op_sel_hi:[0,1,1]
	v_pk_fma_f32 v[24:25], v[86:87], v[198:199], v[24:25] op_sel_hi:[0,1,1]
	v_pk_fma_f32 v[22:23], v[94:95], v[198:199], v[22:23] op_sel_hi:[0,1,1]
	s_waitcnt vmcnt(28)
	v_pk_fma_f32 v[8:9], v[116:117], v[200:201], v[8:9] op_sel_hi:[0,1,1]
	v_pk_fma_f32 v[12:13], v[118:119], v[200:201], v[12:13] op_sel_hi:[0,1,1]
	v_pk_fma_f32 v[10:11], v[120:121], v[200:201], v[10:11] op_sel_hi:[0,1,1]
	v_pk_fma_f32 v[16:17], v[122:123], v[200:201], v[16:17] op_sel_hi:[0,1,1]
	v_pk_fma_f32 v[14:15], v[124:125], v[200:201], v[14:15] op_sel_hi:[0,1,1]
	v_pk_fma_f32 v[20:21], v[126:127], v[200:201], v[20:21] op_sel_hi:[0,1,1]
	v_pk_fma_f32 v[18:19], v[128:129], v[200:201], v[18:19] op_sel_hi:[0,1,1]
	v_pk_fma_f32 v[24:25], v[130:131], v[200:201], v[24:25] op_sel_hi:[0,1,1]
	v_pk_fma_f32 v[22:23], v[138:139], v[200:201], v[22:23] op_sel_hi:[0,1,1]
	s_waitcnt vmcnt(27)
; __global__ void __launch_bounds__(NTHR, 2) trunk_fwd(Args a) {
;     ...
;             for (int k0 = 0; k0 < 128; k0 += 8) { float2 wv[8];
; #pragma unroll
;                 for (int k = 0; k < 8; ++k) wv[k] = *(const float2*)(wp + (size_t)(k0 + k) * 6144);
; #pragma unroll
;                 for (int k = 0; k < 8; ++k)
; #pragma unroll
;                     for (int q = 0; q < 9; ++q) { const float sv = sS[q * 1024 + wave * 128 + k0 + k]; acc0[q] += sv * wv[k].x; acc1[q] += sv * wv[k].y; } }
	v_pk_fma_f32 v[8:9], v[32:33], v[202:203], v[8:9] op_sel_hi:[0,1,1]
	v_pk_fma_f32 v[12:13], v[40:41], v[202:203], v[12:13] op_sel_hi:[0,1,1]
	v_pk_fma_f32 v[10:11], v[48:49], v[202:203], v[10:11] op_sel_hi:[0,1,1]
	v_pk_fma_f32 v[16:17], v[56:57], v[202:203], v[16:17] op_sel_hi:[0,1,1]
	v_pk_fma_f32 v[14:15], v[64:65], v[202:203], v[14:15] op_sel_hi:[0,1,1]
	v_pk_fma_f32 v[20:21], v[72:73], v[202:203], v[20:21] op_sel_hi:[0,1,1]
	v_pk_fma_f32 v[18:19], v[80:81], v[202:203], v[18:19] op_sel_hi:[0,1,1]
	v_pk_fma_f32 v[24:25], v[88:89], v[202:203], v[24:25] op_sel_hi:[0,1,1]
	v_pk_fma_f32 v[22:23], v[96:97], v[202:203], v[22:23] op_sel_hi:[0,1,1]
	s_waitcnt vmcnt(26)
	v_pk_fma_f32 v[8:9], v[32:33], v[204:205], v[8:9] op_sel:[1,0,0]
	v_pk_fma_f32 v[12:13], v[40:41], v[204:205], v[12:13] op_sel:[1,0,0]
	v_pk_fma_f32 v[10:11], v[48:49], v[204:205], v[10:11] op_sel:[1,0,0]
	v_pk_fma_f32 v[16:17], v[56:57], v[204:205], v[16:17] op_sel:[1,0,0]
	v_pk_fma_f32 v[14:15], v[64:65], v[204:205], v[14:15] op_sel:[1,0,0]
	v_pk_fma_f32 v[20:21], v[72:73], v[204:205], v[20:21] op_sel:[1,0,0]
	v_pk_fma_f32 v[18:19], v[80:81], v[204:205], v[18:19] op_sel:[1,0,0]
	v_pk_fma_f32 v[24:25], v[88:89], v[204:205], v[24:25] op_sel:[1,0,0]
	v_pk_fma_f32 v[22:23], v[96:97], v[204:205], v[22:23] op_sel:[1,0,0]
	s_waitcnt vmcnt(25)
	v_pk_fma_f32 v[8:9], v[34:35], v[206:207], v[8:9] op_sel_hi:[0,1,1]
	v_pk_fma_f32 v[12:13], v[42:43], v[206:207], v[12:13] op_sel_hi:[0,1,1]
	v_pk_fma_f32 v[10:11], v[50:51], v[206:207], v[10:11] op_sel_hi:[0,1,1]
	v_pk_fma_f32 v[16:17], v[58:59], v[206:207], v[16:17] op_sel_hi:[0,1,1]
	v_pk_fma_f32 v[14:15], v[66:67], v[206:207], v[14:15] op_sel_hi:[0,1,1]
	v_pk_fma_f32 v[20:21], v[74:75], v[206:207], v[20:21] op_sel_hi:[0,1,1]
	v_pk_fma_f32 v[18:19], v[82:83], v[206:207], v[18:19] op_sel_hi:[0,1,1]
	v_pk_fma_f32 v[24:25], v[90:91], v[206:207], v[24:25] op_sel_hi:[0,1,1]
	v_pk_fma_f32 v[22:23], v[98:99], v[206:207], v[22:23] op_sel_hi:[0,1,1]
	s_waitcnt vmcnt(24)
	v_pk_fma_f32 v[8:9], v[132:133], v[208:209], v[8:9] op_sel_hi:[0,1,1]
	v_pk_fma_f32 v[12:13], v[134:135], v[208:209], v[12:13] op_sel_hi:[0,1,1]
	v_pk_fma_f32 v[10:11], v[136:137], v[208:209], v[10:11] op_sel_hi:[0,1,1]
	v_pk_fma_f32 v[16:17], v[140:141], v[208:209], v[16:17] op_sel_hi:[0,1,1]
	v_pk_fma_f32 v[14:15], v[142:143], v[208:209], v[14:15] op_sel_hi:[0,1,1]
	v_pk_fma_f32 v[20:21], v[144:145], v[208:209], v[20:21] op_sel_hi:[0,1,1]
	v_pk_fma_f32 v[18:19], v[146:147], v[208:209], v[18:19] op_sel_hi:[0,1,1]
	v_pk_fma_f32 v[24:25], v[148:149], v[208:209], v[24:25] op_sel_hi:[0,1,1]
	v_pk_fma_f32 v[22:23], v[150:151], v[208:209], v[22:23] op_sel_hi:[0,1,1]
	global_load_dwordx2 v[194:195], v[246:247], off
	v_lshl_add_u64 v[248:249], v[246:247], 0, s[28:29]
	global_load_dwordx2 v[196:197], v[248:249], off
	v_lshl_add_u64 v[248:249], v[248:249], 0, s[28:29]
	global_load_dwordx2 v[198:199], v[248:249], off
	v_lshl_add_u64 v[248:249], v[248:249], 0, s[28:29]
	global_load_dwordx2 v[200:201], v[248:249], off
	v_lshl_add_u64 v[248:249], v[248:249], 0, s[28:29]
	global_load_dwordx2 v[202:203], v[248:249], off
	v_lshl_add_u64 v[248:249], v[248:249], 0, s[28:29]
	global_load_dwordx2 v[204:205], v[248:249], off
	v_lshl_add_u64 v[248:249], v[248:249], 0, s[28:29]
	global_load_dwordx2 v[206:207], v[248:249], off
	v_lshl_add_u64 v[248:249], v[248:249], 0, s[28:29]
	global_load_dwordx2 v[208:209], v[248:249], off
	v_lshl_add_u64 v[246:247], v[246:247], 0, s[6:7]
	v_mov_b32_e32 v27, s9
	s_add_i32 s9, s9, 32
	ds_read_b128 v[28:31], v27
	ds_read_b128 v[32:35], v27 offset:16
	ds_read_b128 v[36:39], v27 offset:4096
	ds_read_b128 v[40:43], v27 offset:4112
	ds_read_b128 v[44:47], v27 offset:8192
	ds_read_b128 v[48:51], v27 offset:8208
	ds_read_b128 v[52:55], v27 offset:12288
	ds_read_b128 v[56:59], v27 offset:12304
	ds_read_b128 v[60:63], v27 offset:16384
	ds_read_b128 v[64:67], v27 offset:16400
	ds_read_b128 v[68:71], v27 offset:20480
	ds_read_b128 v[72:75], v27 offset:20496
	ds_read_b128 v[76:79], v27 offset:24576
	ds_read_b128 v[80:83], v27 offset:24592
	ds_read_b128 v[84:87], v27 offset:28672
	ds_read_b128 v[88:91], v27 offset:28688
	ds_read_b128 v[92:95], v27 offset:32768
	ds_read_b128 v[96:99], v27 offset:32784
	s_waitcnt lgkmcnt(14)
	v_mov_b32_e32 v116, v31
	v_mov_b32_e32 v118, v39
	s_waitcnt lgkmcnt(13)
	v_mov_b32_e32 v120, v47
	s_waitcnt lgkmcnt(11)
	v_mov_b32_e32 v122, v55
	s_waitcnt lgkmcnt(9)
	v_mov_b32_e32 v124, v63
	s_waitcnt lgkmcnt(7)
	v_mov_b32_e32 v126, v71
	s_waitcnt lgkmcnt(5)
	v_mov_b32_e32 v128, v79
	s_waitcnt lgkmcnt(3)
	v_mov_b32_e32 v130, v87
	s_waitcnt lgkmcnt(1)
	v_mov_b32_e32 v138, v95
	v_mov_b32_e32 v132, v35
	v_mov_b32_e32 v134, v43
	v_mov_b32_e32 v136, v51
	v_mov_b32_e32 v140, v59
	v_mov_b32_e32 v142, v67
	v_mov_b32_e32 v144, v75
	v_mov_b32_e32 v146, v83
	v_mov_b32_e32 v148, v91
	s_waitcnt lgkmcnt(0)
	v_mov_b32_e32 v150, v99
	s_waitcnt vmcnt(31)
	v_pk_fma_f32 v[8:9], v[28:29], v[214:215], v[8:9] op_sel_hi:[0,1,1]
	v_pk_fma_f32 v[12:13], v[36:37], v[214:215], v[12:13] op_sel_hi:[0,1,1]
	v_pk_fma_f32 v[10:11], v[44:45], v[214:215], v[10:11] op_sel_hi:[0,1,1]
	v_pk_fma_f32 v[16:17], v[52:53], v[214:215], v[16:17] op_sel_hi:[0,1,1]
	v_pk_fma_f32 v[14:15], v[60:61], v[214:215], v[14:15] op_sel_hi:[0,1,1]
	v_pk_fma_f32 v[20:21], v[68:69], v[214:215], v[20:21] op_sel_hi:[0,1,1]
	v_pk_fma_f32 v[18:19], v[76:77], v[214:215], v[18:19] op_sel_hi:[0,1,1]
	v_pk_fma_f32 v[24:25], v[84:85], v[214:215], v[24:25] op_sel_hi:[0,1,1]
	v_pk_fma_f32 v[22:23], v[92:93], v[214:215], v[22:23] op_sel_hi:[0,1,1]
	s_waitcnt vmcnt(30)
; __global__ void __launch_bounds__(NTHR, 2) trunk_fwd(Args a) {
;     ...
;             for (int k0 = 0; k0 < 128; k0 += 8) { float2 wv[8];
; #pragma unroll
;                 for (int k = 0; k < 8; ++k) wv[k] = *(const float2*)(wp + (size_t)(k0 + k) * 6144);
; #pragma unroll
;                 for (int k = 0; k < 8; ++k)
; #pragma unroll
;                     for (int q = 0; q < 9; ++q) { const float sv = sS[q * 1024 + wave * 128 + k0 + k]; acc0[q] += sv * wv[k].x; acc1[q] += sv * wv[k].y; } }
	v_pk_fma_f32 v[8:9], v[28:29], v[216:217], v[8:9] op_sel:[1,0,0]
	v_pk_fma_f32 v[12:13], v[36:37], v[216:217], v[12:13] op_sel:[1,0,0]
	v_pk_fma_f32 v[10:11], v[44:45], v[216:217], v[10:11] op_sel:[1,0,0]
	v_pk_fma_f32 v[16:17], v[52:53], v[216:217], v[16:17] op_sel:[1,0,0]
	v_pk_fma_f32 v[14:15], v[60:61], v[216:217], v[14:15] op_sel:[1,0,0]
	v_pk_fma_f32 v[20:21], v[68:69], v[216:217], v[20:21] op_sel:[1,0,0]
	v_pk_fma_f32 v[18:19], v[76:77], v[216:217], v[18:19] op_sel:[1,0,0]
	v_pk_fma_f32 v[24:25], v[84:85], v[216:217], v[24:25] op_sel:[1,0,0]
	v_pk_fma_f32 v[22:23], v[92:93], v[216:217], v[22:23] op_sel:[1,0,0]
	s_waitcnt vmcnt(29)
	v_pk_fma_f32 v[8:9], v[30:31], v[218:219], v[8:9] op_sel_hi:[0,1,1]
	v_pk_fma_f32 v[12:13], v[38:39], v[218:219], v[12:13] op_sel_hi:[0,1,1]
	v_pk_fma_f32 v[10:11], v[46:47], v[218:219], v[10:11] op_sel_hi:[0,1,1]
	v_pk_fma_f32 v[16:17], v[54:55], v[218:219], v[16:17] op_sel_hi:[0,1,1]
	v_pk_fma_f32 v[14:15], v[62:63], v[218:219], v[14:15] op_sel_hi:[0,1,1]
	v_pk_fma_f32 v[20:21], v[70:71], v[218:219], v[20:21] op_sel_hi:[0,1,1]
	v_pk_fma_f32 v[18:19], v[78:79], v[218:219], v[18:19] op_sel_hi:[0,1,1]
	v_pk_fma_f32 v[24:25], v[86:87], v[218:219], v[24:25] op_sel_hi:[0,1,1]
	v_pk_fma_f32 v[22:23], v[94:95], v[218:219], v[22:23] op_sel_hi:[0,1,1]
	s_waitcnt vmcnt(28)
	v_pk_fma_f32 v[8:9], v[116:117], v[220:221], v[8:9] op_sel_hi:[0,1,1]
	v_pk_fma_f32 v[12:13], v[118:119], v[220:221], v[12:13] op_sel_hi:[0,1,1]
	v_pk_fma_f32 v[10:11], v[120:121], v[220:221], v[10:11] op_sel_hi:[0,1,1]
	v_pk_fma_f32 v[16:17], v[122:123], v[220:221], v[16:17] op_sel_hi:[0,1,1]
	v_pk_fma_f32 v[14:15], v[124:125], v[220:221], v[14:15] op_sel_hi:[0,1,1]
	v_pk_fma_f32 v[20:21], v[126:127], v[220:221], v[20:21] op_sel_hi:[0,1,1]
	v_pk_fma_f32 v[18:19], v[128:129], v[220:221], v[18:19] op_sel_hi:[0,1,1]
	v_pk_fma_f32 v[24:25], v[130:131], v[220:221], v[24:25] op_sel_hi:[0,1,1]
	v_pk_fma_f32 v[22:23], v[138:139], v[220:221], v[22:23] op_sel_hi:[0,1,1]
	s_waitcnt vmcnt(27)
	v_pk_fma_f32 v[8:9], v[32:33], v[222:223], v[8:9] op_sel_hi:[0,1,1]
	v_pk_fma_f32 v[12:13], v[40:41], v[222:223], v[12:13] op_sel_hi:[0,1,1]
	v_pk_fma_f32 v[10:11], v[48:49], v[222:223], v[10:11] op_sel_hi:[0,1,1]
	v_pk_fma_f32 v[16:17], v[56:57], v[222:223], v[16:17] op_sel_hi:[0,1,1]
	v_pk_fma_f32 v[14:15], v[64:65], v[222:223], v[14:15] op_sel_hi:[0,1,1]
	v_pk_fma_f32 v[20:21], v[72:73], v[222:223], v[20:21] op_sel_hi:[0,1,1]
	v_pk_fma_f32 v[18:19], v[80:81], v[222:223], v[18:19] op_sel_hi:[0,1,1]
	v_pk_fma_f32 v[24:25], v[88:89], v[222:223], v[24:25] op_sel_hi:[0,1,1]
	v_pk_fma_f32 v[22:23], v[96:97], v[222:223], v[22:23] op_sel_hi:[0,1,1]
	s_waitcnt vmcnt(26)
	v_pk_fma_f32 v[8:9], v[32:33], v[224:225], v[8:9] op_sel:[1,0,0]
	v_pk_fma_f32 v[12:13], v[40:41], v[224:225], v[12:13] op_sel:[1,0,0]
	v_pk_fma_f32 v[10:11], v[48:49], v[224:225], v[10:11] op_sel:[1,0,0]
	v_pk_fma_f32 v[16:17], v[56:57], v[224:225], v[16:17] op_sel:[1,0,0]
	v_pk_fma_f32 v[14:15], v[64:65], v[224:225], v[14:15] op_sel:[1,0,0]
	v_pk_fma_f32 v[20:21], v[72:73], v[224:225], v[20:21] op_sel:[1,0,0]
	v_pk_fma_f32 v[18:19], v[80:81], v[224:225], v[18:19] op_sel:[1,0,0]
	v_pk_fma_f32 v[24:25], v[88:89], v[224:225], v[24:25] op_sel:[1,0,0]
	v_pk_fma_f32 v[22:23], v[96:97], v[224:225], v[22:23] op_sel:[1,0,0]
	s_waitcnt vmcnt(25)
	v_pk_fma_f32 v[8:9], v[34:35], v[226:227], v[8:9] op_sel_hi:[0,1,1]
	v_pk_fma_f32 v[12:13], v[42:43], v[226:227], v[12:13] op_sel_hi:[0,1,1]
	v_pk_fma_f32 v[10:11], v[50:51], v[226:227], v[10:11] op_sel_hi:[0,1,1]
	v_pk_fma_f32 v[16:17], v[58:59], v[226:227], v[16:17] op_sel_hi:[0,1,1]
	v_pk_fma_f32 v[14:15], v[66:67], v[226:227], v[14:15] op_sel_hi:[0,1,1]
	v_pk_fma_f32 v[20:21], v[74:75], v[226:227], v[20:21] op_sel_hi:[0,1,1]
	v_pk_fma_f32 v[18:19], v[82:83], v[226:227], v[18:19] op_sel_hi:[0,1,1]
	v_pk_fma_f32 v[24:25], v[90:91], v[226:227], v[24:25] op_sel_hi:[0,1,1]
	v_pk_fma_f32 v[22:23], v[98:99], v[226:227], v[22:23] op_sel_hi:[0,1,1]
	s_waitcnt vmcnt(24)
	v_pk_fma_f32 v[8:9], v[132:133], v[228:229], v[8:9] op_sel_hi:[0,1,1]
	v_pk_fma_f32 v[12:13], v[134:135], v[228:229], v[12:13] op_sel_hi:[0,1,1]
	v_pk_fma_f32 v[10:11], v[136:137], v[228:229], v[10:11] op_sel_hi:[0,1,1]
	v_pk_fma_f32 v[16:17], v[140:141], v[228:229], v[16:17] op_sel_hi:[0,1,1]
	v_pk_fma_f32 v[14:15], v[142:143], v[228:229], v[14:15] op_sel_hi:[0,1,1]
	v_pk_fma_f32 v[20:21], v[144:145], v[228:229], v[20:21] op_sel_hi:[0,1,1]
	v_pk_fma_f32 v[18:19], v[146:147], v[228:229], v[18:19] op_sel_hi:[0,1,1]
	v_pk_fma_f32 v[24:25], v[148:149], v[228:229], v[24:25] op_sel_hi:[0,1,1]
	v_pk_fma_f32 v[22:23], v[150:151], v[228:229], v[22:23] op_sel_hi:[0,1,1]
	global_load_dwordx2 v[214:215], v[246:247], off
	v_lshl_add_u64 v[248:249], v[246:247], 0, s[28:29]
	global_load_dwordx2 v[216:217], v[248:249], off
	v_lshl_add_u64 v[248:249], v[248:249], 0, s[28:29]
	global_load_dwordx2 v[218:219], v[248:249], off
	v_lshl_add_u64 v[248:249], v[248:249], 0, s[28:29]
	global_load_dwordx2 v[220:221], v[248:249], off
	v_lshl_add_u64 v[248:249], v[248:249], 0, s[28:29]
	global_load_dwordx2 v[222:223], v[248:249], off
	v_lshl_add_u64 v[248:249], v[248:249], 0, s[28:29]
	global_load_dwordx2 v[224:225], v[248:249], off
	v_lshl_add_u64 v[248:249], v[248:249], 0, s[28:29]
	global_load_dwordx2 v[226:227], v[248:249], off
	v_lshl_add_u64 v[248:249], v[248:249], 0, s[28:29]
	global_load_dwordx2 v[228:229], v[248:249], off
	v_lshl_add_u64 v[246:247], v[246:247], 0, s[6:7]
	v_mov_b32_e32 v27, s9
	s_add_i32 s9, s9, 32
	ds_read_b128 v[28:31], v27
	ds_read_b128 v[32:35], v27 offset:16
	ds_read_b128 v[36:39], v27 offset:4096
	ds_read_b128 v[40:43], v27 offset:4112
	ds_read_b128 v[44:47], v27 offset:8192
	ds_read_b128 v[48:51], v27 offset:8208
	ds_read_b128 v[52:55], v27 offset:12288
	ds_read_b128 v[56:59], v27 offset:12304
	ds_read_b128 v[60:63], v27 offset:16384
	ds_read_b128 v[64:67], v27 offset:16400
	ds_read_b128 v[68:71], v27 offset:20480
	ds_read_b128 v[72:75], v27 offset:20496
	ds_read_b128 v[76:79], v27 offset:24576
	ds_read_b128 v[80:83], v27 offset:24592
	ds_read_b128 v[84:87], v27 offset:28672
	ds_read_b128 v[88:91], v27 offset:28688
	ds_read_b128 v[92:95], v27 offset:32768
	ds_read_b128 v[96:99], v27 offset:32784
	s_waitcnt lgkmcnt(14)
; __global__ void __launch_bounds__(NTHR, 2) trunk_fwd(Args a) {
;     ...
;             for (int k0 = 0; k0 < 128; k0 += 8) { float2 wv[8];
; #pragma unroll
;                 for (int k = 0; k < 8; ++k) wv[k] = *(const float2*)(wp + (size_t)(k0 + k) * 6144);
; #pragma unroll
;                 for (int k = 0; k < 8; ++k)
; #pragma unroll
;                     for (int q = 0; q < 9; ++q) { const float sv = sS[q * 1024 + wave * 128 + k0 + k]; acc0[q] += sv * wv[k].x; acc1[q] += sv * wv[k].y; } }
	v_mov_b32_e32 v116, v31
	v_mov_b32_e32 v118, v39
	s_waitcnt lgkmcnt(13)
	v_mov_b32_e32 v120, v47
	s_waitcnt lgkmcnt(11)
	v_mov_b32_e32 v122, v55
	s_waitcnt lgkmcnt(9)
	v_mov_b32_e32 v124, v63
	s_waitcnt lgkmcnt(7)
	v_mov_b32_e32 v126, v71
	s_waitcnt lgkmcnt(5)
	v_mov_b32_e32 v128, v79
	s_waitcnt lgkmcnt(3)
	v_mov_b32_e32 v130, v87
	s_waitcnt lgkmcnt(1)
	v_mov_b32_e32 v138, v95
	v_mov_b32_e32 v132, v35
	v_mov_b32_e32 v134, v43
	v_mov_b32_e32 v136, v51
	v_mov_b32_e32 v140, v59
	v_mov_b32_e32 v142, v67
	v_mov_b32_e32 v144, v75
	v_mov_b32_e32 v146, v83
	v_mov_b32_e32 v148, v91
	s_waitcnt lgkmcnt(0)
	v_mov_b32_e32 v150, v99
	s_waitcnt vmcnt(31)
	v_pk_fma_f32 v[8:9], v[28:29], v[230:231], v[8:9] op_sel_hi:[0,1,1]
	v_pk_fma_f32 v[12:13], v[36:37], v[230:231], v[12:13] op_sel_hi:[0,1,1]
	v_pk_fma_f32 v[10:11], v[44:45], v[230:231], v[10:11] op_sel_hi:[0,1,1]
	v_pk_fma_f32 v[16:17], v[52:53], v[230:231], v[16:17] op_sel_hi:[0,1,1]
	v_pk_fma_f32 v[14:15], v[60:61], v[230:231], v[14:15] op_sel_hi:[0,1,1]
	v_pk_fma_f32 v[20:21], v[68:69], v[230:231], v[20:21] op_sel_hi:[0,1,1]
	v_pk_fma_f32 v[18:19], v[76:77], v[230:231], v[18:19] op_sel_hi:[0,1,1]
	v_pk_fma_f32 v[24:25], v[84:85], v[230:231], v[24:25] op_sel_hi:[0,1,1]
	v_pk_fma_f32 v[22:23], v[92:93], v[230:231], v[22:23] op_sel_hi:[0,1,1]
	s_waitcnt vmcnt(30)
	v_pk_fma_f32 v[8:9], v[28:29], v[232:233], v[8:9] op_sel:[1,0,0]
	v_pk_fma_f32 v[12:13], v[36:37], v[232:233], v[12:13] op_sel:[1,0,0]
	v_pk_fma_f32 v[10:11], v[44:45], v[232:233], v[10:11] op_sel:[1,0,0]
	v_pk_fma_f32 v[16:17], v[52:53], v[232:233], v[16:17] op_sel:[1,0,0]
	v_pk_fma_f32 v[14:15], v[60:61], v[232:233], v[14:15] op_sel:[1,0,0]
	v_pk_fma_f32 v[20:21], v[68:69], v[232:233], v[20:21] op_sel:[1,0,0]
	v_pk_fma_f32 v[18:19], v[76:77], v[232:233], v[18:19] op_sel:[1,0,0]
	v_pk_fma_f32 v[24:25], v[84:85], v[232:233], v[24:25] op_sel:[1,0,0]
	v_pk_fma_f32 v[22:23], v[92:93], v[232:233], v[22:23] op_sel:[1,0,0]
	s_waitcnt vmcnt(29)
	v_pk_fma_f32 v[8:9], v[30:31], v[234:235], v[8:9] op_sel_hi:[0,1,1]
	v_pk_fma_f32 v[12:13], v[38:39], v[234:235], v[12:13] op_sel_hi:[0,1,1]
	v_pk_fma_f32 v[10:11], v[46:47], v[234:235], v[10:11] op_sel_hi:[0,1,1]
	v_pk_fma_f32 v[16:17], v[54:55], v[234:235], v[16:17] op_sel_hi:[0,1,1]
	v_pk_fma_f32 v[14:15], v[62:63], v[234:235], v[14:15] op_sel_hi:[0,1,1]
	v_pk_fma_f32 v[20:21], v[70:71], v[234:235], v[20:21] op_sel_hi:[0,1,1]
	v_pk_fma_f32 v[18:19], v[78:79], v[234:235], v[18:19] op_sel_hi:[0,1,1]
	v_pk_fma_f32 v[24:25], v[86:87], v[234:235], v[24:25] op_sel_hi:[0,1,1]
	v_pk_fma_f32 v[22:23], v[94:95], v[234:235], v[22:23] op_sel_hi:[0,1,1]
	s_waitcnt vmcnt(28)
	v_pk_fma_f32 v[8:9], v[116:117], v[236:237], v[8:9] op_sel_hi:[0,1,1]
	v_pk_fma_f32 v[12:13], v[118:119], v[236:237], v[12:13] op_sel_hi:[0,1,1]
	v_pk_fma_f32 v[10:11], v[120:121], v[236:237], v[10:11] op_sel_hi:[0,1,1]
	v_pk_fma_f32 v[16:17], v[122:123], v[236:237], v[16:17] op_sel_hi:[0,1,1]
	v_pk_fma_f32 v[14:15], v[124:125], v[236:237], v[14:15] op_sel_hi:[0,1,1]
	v_pk_fma_f32 v[20:21], v[126:127], v[236:237], v[20:21] op_sel_hi:[0,1,1]
	v_pk_fma_f32 v[18:19], v[128:129], v[236:237], v[18:19] op_sel_hi:[0,1,1]
	v_pk_fma_f32 v[24:25], v[130:131], v[236:237], v[24:25] op_sel_hi:[0,1,1]
	v_pk_fma_f32 v[22:23], v[138:139], v[236:237], v[22:23] op_sel_hi:[0,1,1]
	s_waitcnt vmcnt(27)
	v_pk_fma_f32 v[8:9], v[32:33], v[238:239], v[8:9] op_sel_hi:[0,1,1]
	v_pk_fma_f32 v[12:13], v[40:41], v[238:239], v[12:13] op_sel_hi:[0,1,1]
	v_pk_fma_f32 v[10:11], v[48:49], v[238:239], v[10:11] op_sel_hi:[0,1,1]
	v_pk_fma_f32 v[16:17], v[56:57], v[238:239], v[16:17] op_sel_hi:[0,1,1]
	v_pk_fma_f32 v[14:15], v[64:65], v[238:239], v[14:15] op_sel_hi:[0,1,1]
	v_pk_fma_f32 v[20:21], v[72:73], v[238:239], v[20:21] op_sel_hi:[0,1,1]
	v_pk_fma_f32 v[18:19], v[80:81], v[238:239], v[18:19] op_sel_hi:[0,1,1]
	v_pk_fma_f32 v[24:25], v[88:89], v[238:239], v[24:25] op_sel_hi:[0,1,1]
	v_pk_fma_f32 v[22:23], v[96:97], v[238:239], v[22:23] op_sel_hi:[0,1,1]
	s_waitcnt vmcnt(26)
	v_pk_fma_f32 v[8:9], v[32:33], v[240:241], v[8:9] op_sel:[1,0,0]
	v_pk_fma_f32 v[12:13], v[40:41], v[240:241], v[12:13] op_sel:[1,0,0]
	v_pk_fma_f32 v[10:11], v[48:49], v[240:241], v[10:11] op_sel:[1,0,0]
	v_pk_fma_f32 v[16:17], v[56:57], v[240:241], v[16:17] op_sel:[1,0,0]
	v_pk_fma_f32 v[14:15], v[64:65], v[240:241], v[14:15] op_sel:[1,0,0]
	v_pk_fma_f32 v[20:21], v[72:73], v[240:241], v[20:21] op_sel:[1,0,0]
	v_pk_fma_f32 v[18:19], v[80:81], v[240:241], v[18:19] op_sel:[1,0,0]
	v_pk_fma_f32 v[24:25], v[88:89], v[240:241], v[24:25] op_sel:[1,0,0]
	v_pk_fma_f32 v[22:23], v[96:97], v[240:241], v[22:23] op_sel:[1,0,0]
	s_waitcnt vmcnt(25)
	v_pk_fma_f32 v[8:9], v[34:35], v[242:243], v[8:9] op_sel_hi:[0,1,1]
	v_pk_fma_f32 v[12:13], v[42:43], v[242:243], v[12:13] op_sel_hi:[0,1,1]
	v_pk_fma_f32 v[10:11], v[50:51], v[242:243], v[10:11] op_sel_hi:[0,1,1]
	v_pk_fma_f32 v[16:17], v[58:59], v[242:243], v[16:17] op_sel_hi:[0,1,1]
	v_pk_fma_f32 v[14:15], v[66:67], v[242:243], v[14:15] op_sel_hi:[0,1,1]
	v_pk_fma_f32 v[20:21], v[74:75], v[242:243], v[20:21] op_sel_hi:[0,1,1]
	v_pk_fma_f32 v[18:19], v[82:83], v[242:243], v[18:19] op_sel_hi:[0,1,1]
	v_pk_fma_f32 v[24:25], v[90:91], v[242:243], v[24:25] op_sel_hi:[0,1,1]
	v_pk_fma_f32 v[22:23], v[98:99], v[242:243], v[22:23] op_sel_hi:[0,1,1]
	s_waitcnt vmcnt(24)
; __global__ void __launch_bounds__(NTHR, 2) trunk_fwd(Args a) {
;     ...
;             for (int k0 = 0; k0 < 128; k0 += 8) { float2 wv[8];
; #pragma unroll
;                 for (int k = 0; k < 8; ++k) wv[k] = *(const float2*)(wp + (size_t)(k0 + k) * 6144);
; #pragma unroll
;                 for (int k = 0; k < 8; ++k)
; #pragma unroll
;                     for (int q = 0; q < 9; ++q) { const float sv = sS[q * 1024 + wave * 128 + k0 + k]; acc0[q] += sv * wv[k].x; acc1[q] += sv * wv[k].y; } }
	v_pk_fma_f32 v[8:9], v[132:133], v[244:245], v[8:9] op_sel_hi:[0,1,1]
	v_pk_fma_f32 v[12:13], v[134:135], v[244:245], v[12:13] op_sel_hi:[0,1,1]
	v_pk_fma_f32 v[10:11], v[136:137], v[244:245], v[10:11] op_sel_hi:[0,1,1]
	v_pk_fma_f32 v[16:17], v[140:141], v[244:245], v[16:17] op_sel_hi:[0,1,1]
	v_pk_fma_f32 v[14:15], v[142:143], v[244:245], v[14:15] op_sel_hi:[0,1,1]
	v_pk_fma_f32 v[20:21], v[144:145], v[244:245], v[20:21] op_sel_hi:[0,1,1]
	v_pk_fma_f32 v[18:19], v[146:147], v[244:245], v[18:19] op_sel_hi:[0,1,1]
	v_pk_fma_f32 v[24:25], v[148:149], v[244:245], v[24:25] op_sel_hi:[0,1,1]
	v_pk_fma_f32 v[22:23], v[150:151], v[244:245], v[22:23] op_sel_hi:[0,1,1]
	global_load_dwordx2 v[230:231], v[246:247], off
	v_lshl_add_u64 v[248:249], v[246:247], 0, s[28:29]
	global_load_dwordx2 v[232:233], v[248:249], off
	v_lshl_add_u64 v[248:249], v[248:249], 0, s[28:29]
	global_load_dwordx2 v[234:235], v[248:249], off
	v_lshl_add_u64 v[248:249], v[248:249], 0, s[28:29]
	global_load_dwordx2 v[236:237], v[248:249], off
	v_lshl_add_u64 v[248:249], v[248:249], 0, s[28:29]
	global_load_dwordx2 v[238:239], v[248:249], off
	v_lshl_add_u64 v[248:249], v[248:249], 0, s[28:29]
	global_load_dwordx2 v[240:241], v[248:249], off
	v_lshl_add_u64 v[248:249], v[248:249], 0, s[28:29]
	global_load_dwordx2 v[242:243], v[248:249], off
	v_lshl_add_u64 v[248:249], v[248:249], 0, s[28:29]
	global_load_dwordx2 v[244:245], v[248:249], off
	v_lshl_add_u64 v[246:247], v[246:247], 0, s[6:7]
	v_mov_b32_e32 v27, s9
	s_add_i32 s9, s9, 32
	ds_read_b128 v[28:31], v27
	ds_read_b128 v[32:35], v27 offset:16
	ds_read_b128 v[36:39], v27 offset:4096
	ds_read_b128 v[40:43], v27 offset:4112
	ds_read_b128 v[44:47], v27 offset:8192
	ds_read_b128 v[48:51], v27 offset:8208
	ds_read_b128 v[52:55], v27 offset:12288
	ds_read_b128 v[56:59], v27 offset:12304
	ds_read_b128 v[60:63], v27 offset:16384
	ds_read_b128 v[64:67], v27 offset:16400
	ds_read_b128 v[68:71], v27 offset:20480
	ds_read_b128 v[72:75], v27 offset:20496
	ds_read_b128 v[76:79], v27 offset:24576
	ds_read_b128 v[80:83], v27 offset:24592
	ds_read_b128 v[84:87], v27 offset:28672
	ds_read_b128 v[88:91], v27 offset:28688
	ds_read_b128 v[92:95], v27 offset:32768
	ds_read_b128 v[96:99], v27 offset:32784
	s_waitcnt lgkmcnt(14)
	v_mov_b32_e32 v116, v31
	v_mov_b32_e32 v118, v39
	s_waitcnt lgkmcnt(13)
	v_mov_b32_e32 v120, v47
	s_waitcnt lgkmcnt(11)
	v_mov_b32_e32 v122, v55
	s_waitcnt lgkmcnt(9)
	v_mov_b32_e32 v124, v63
	s_waitcnt lgkmcnt(7)
	v_mov_b32_e32 v126, v71
	s_waitcnt lgkmcnt(5)
	v_mov_b32_e32 v128, v79
	s_waitcnt lgkmcnt(3)
	v_mov_b32_e32 v130, v87
	s_waitcnt lgkmcnt(1)
	v_mov_b32_e32 v138, v95
	v_mov_b32_e32 v132, v35
	v_mov_b32_e32 v134, v43
	v_mov_b32_e32 v136, v51
	v_mov_b32_e32 v140, v59
	v_mov_b32_e32 v142, v67
	v_mov_b32_e32 v144, v75
	v_mov_b32_e32 v146, v83
	v_mov_b32_e32 v148, v91
	s_waitcnt lgkmcnt(0)
	v_mov_b32_e32 v150, v99
	s_waitcnt vmcnt(31)
	v_pk_fma_f32 v[8:9], v[28:29], v[100:101], v[8:9] op_sel_hi:[0,1,1]
	v_pk_fma_f32 v[12:13], v[36:37], v[100:101], v[12:13] op_sel_hi:[0,1,1]
	v_pk_fma_f32 v[10:11], v[44:45], v[100:101], v[10:11] op_sel_hi:[0,1,1]
	v_pk_fma_f32 v[16:17], v[52:53], v[100:101], v[16:17] op_sel_hi:[0,1,1]
	v_pk_fma_f32 v[14:15], v[60:61], v[100:101], v[14:15] op_sel_hi:[0,1,1]
	v_pk_fma_f32 v[20:21], v[68:69], v[100:101], v[20:21] op_sel_hi:[0,1,1]
	v_pk_fma_f32 v[18:19], v[76:77], v[100:101], v[18:19] op_sel_hi:[0,1,1]
	v_pk_fma_f32 v[24:25], v[84:85], v[100:101], v[24:25] op_sel_hi:[0,1,1]
	v_pk_fma_f32 v[22:23], v[92:93], v[100:101], v[22:23] op_sel_hi:[0,1,1]
	s_waitcnt vmcnt(30)
	v_pk_fma_f32 v[8:9], v[28:29], v[102:103], v[8:9] op_sel:[1,0,0]
	v_pk_fma_f32 v[12:13], v[36:37], v[102:103], v[12:13] op_sel:[1,0,0]
	v_pk_fma_f32 v[10:11], v[44:45], v[102:103], v[10:11] op_sel:[1,0,0]
	v_pk_fma_f32 v[16:17], v[52:53], v[102:103], v[16:17] op_sel:[1,0,0]
	v_pk_fma_f32 v[14:15], v[60:61], v[102:103], v[14:15] op_sel:[1,0,0]
	v_pk_fma_f32 v[20:21], v[68:69], v[102:103], v[20:21] op_sel:[1,0,0]
	v_pk_fma_f32 v[18:19], v[76:77], v[102:103], v[18:19] op_sel:[1,0,0]
	v_pk_fma_f32 v[24:25], v[84:85], v[102:103], v[24:25] op_sel:[1,0,0]
	v_pk_fma_f32 v[22:23], v[92:93], v[102:103], v[22:23] op_sel:[1,0,0]
	s_waitcnt vmcnt(29)
	v_pk_fma_f32 v[8:9], v[30:31], v[104:105], v[8:9] op_sel_hi:[0,1,1]
	v_pk_fma_f32 v[12:13], v[38:39], v[104:105], v[12:13] op_sel_hi:[0,1,1]
	v_pk_fma_f32 v[10:11], v[46:47], v[104:105], v[10:11] op_sel_hi:[0,1,1]
	v_pk_fma_f32 v[16:17], v[54:55], v[104:105], v[16:17] op_sel_hi:[0,1,1]
	v_pk_fma_f32 v[14:15], v[62:63], v[104:105], v[14:15] op_sel_hi:[0,1,1]
	v_pk_fma_f32 v[20:21], v[70:71], v[104:105], v[20:21] op_sel_hi:[0,1,1]
	v_pk_fma_f32 v[18:19], v[78:79], v[104:105], v[18:19] op_sel_hi:[0,1,1]
	v_pk_fma_f32 v[24:25], v[86:87], v[104:105], v[24:25] op_sel_hi:[0,1,1]
	v_pk_fma_f32 v[22:23], v[94:95], v[104:105], v[22:23] op_sel_hi:[0,1,1]
	s_waitcnt vmcnt(28)
	v_pk_fma_f32 v[8:9], v[116:117], v[106:107], v[8:9] op_sel_hi:[0,1,1]
	v_pk_fma_f32 v[12:13], v[118:119], v[106:107], v[12:13] op_sel_hi:[0,1,1]
	v_pk_fma_f32 v[10:11], v[120:121], v[106:107], v[10:11] op_sel_hi:[0,1,1]
	v_pk_fma_f32 v[16:17], v[122:123], v[106:107], v[16:17] op_sel_hi:[0,1,1]
	v_pk_fma_f32 v[14:15], v[124:125], v[106:107], v[14:15] op_sel_hi:[0,1,1]
	v_pk_fma_f32 v[20:21], v[126:127], v[106:107], v[20:21] op_sel_hi:[0,1,1]
	v_pk_fma_f32 v[18:19], v[128:129], v[106:107], v[18:19] op_sel_hi:[0,1,1]
	v_pk_fma_f32 v[24:25], v[130:131], v[106:107], v[24:25] op_sel_hi:[0,1,1]
	v_pk_fma_f32 v[22:23], v[138:139], v[106:107], v[22:23] op_sel_hi:[0,1,1]
	s_waitcnt vmcnt(27)
; __global__ void __launch_bounds__(NTHR, 2) trunk_fwd(Args a) {
;     ...
;             for (int k0 = 0; k0 < 128; k0 += 8) { float2 wv[8];
; #pragma unroll
;                 for (int k = 0; k < 8; ++k) wv[k] = *(const float2*)(wp + (size_t)(k0 + k) * 6144);
; #pragma unroll
;                 for (int k = 0; k < 8; ++k)
; #pragma unroll
;                     for (int q = 0; q < 9; ++q) { const float sv = sS[q * 1024 + wave * 128 + k0 + k]; acc0[q] += sv * wv[k].x; acc1[q] += sv * wv[k].y; } }
	v_pk_fma_f32 v[8:9], v[32:33], v[108:109], v[8:9] op_sel_hi:[0,1,1]
	v_pk_fma_f32 v[12:13], v[40:41], v[108:109], v[12:13] op_sel_hi:[0,1,1]
	v_pk_fma_f32 v[10:11], v[48:49], v[108:109], v[10:11] op_sel_hi:[0,1,1]
	v_pk_fma_f32 v[16:17], v[56:57], v[108:109], v[16:17] op_sel_hi:[0,1,1]
	v_pk_fma_f32 v[14:15], v[64:65], v[108:109], v[14:15] op_sel_hi:[0,1,1]
	v_pk_fma_f32 v[20:21], v[72:73], v[108:109], v[20:21] op_sel_hi:[0,1,1]
	v_pk_fma_f32 v[18:19], v[80:81], v[108:109], v[18:19] op_sel_hi:[0,1,1]
	v_pk_fma_f32 v[24:25], v[88:89], v[108:109], v[24:25] op_sel_hi:[0,1,1]
	v_pk_fma_f32 v[22:23], v[96:97], v[108:109], v[22:23] op_sel_hi:[0,1,1]
	s_waitcnt vmcnt(26)
	v_pk_fma_f32 v[8:9], v[32:33], v[110:111], v[8:9] op_sel:[1,0,0]
	v_pk_fma_f32 v[12:13], v[40:41], v[110:111], v[12:13] op_sel:[1,0,0]
	v_pk_fma_f32 v[10:11], v[48:49], v[110:111], v[10:11] op_sel:[1,0,0]
	v_pk_fma_f32 v[16:17], v[56:57], v[110:111], v[16:17] op_sel:[1,0,0]
	v_pk_fma_f32 v[14:15], v[64:65], v[110:111], v[14:15] op_sel:[1,0,0]
	v_pk_fma_f32 v[20:21], v[72:73], v[110:111], v[20:21] op_sel:[1,0,0]
	v_pk_fma_f32 v[18:19], v[80:81], v[110:111], v[18:19] op_sel:[1,0,0]
	v_pk_fma_f32 v[24:25], v[88:89], v[110:111], v[24:25] op_sel:[1,0,0]
	v_pk_fma_f32 v[22:23], v[96:97], v[110:111], v[22:23] op_sel:[1,0,0]
	s_waitcnt vmcnt(25)
	v_pk_fma_f32 v[8:9], v[34:35], v[112:113], v[8:9] op_sel_hi:[0,1,1]
	v_pk_fma_f32 v[12:13], v[42:43], v[112:113], v[12:13] op_sel_hi:[0,1,1]
	v_pk_fma_f32 v[10:11], v[50:51], v[112:113], v[10:11] op_sel_hi:[0,1,1]
	v_pk_fma_f32 v[16:17], v[58:59], v[112:113], v[16:17] op_sel_hi:[0,1,1]
	v_pk_fma_f32 v[14:15], v[66:67], v[112:113], v[14:15] op_sel_hi:[0,1,1]
	v_pk_fma_f32 v[20:21], v[74:75], v[112:113], v[20:21] op_sel_hi:[0,1,1]
	v_pk_fma_f32 v[18:19], v[82:83], v[112:113], v[18:19] op_sel_hi:[0,1,1]
	v_pk_fma_f32 v[24:25], v[90:91], v[112:113], v[24:25] op_sel_hi:[0,1,1]
	v_pk_fma_f32 v[22:23], v[98:99], v[112:113], v[22:23] op_sel_hi:[0,1,1]
	s_waitcnt vmcnt(24)
	v_pk_fma_f32 v[8:9], v[132:133], v[114:115], v[8:9] op_sel_hi:[0,1,1]
	v_pk_fma_f32 v[12:13], v[134:135], v[114:115], v[12:13] op_sel_hi:[0,1,1]
	v_pk_fma_f32 v[10:11], v[136:137], v[114:115], v[10:11] op_sel_hi:[0,1,1]
	v_pk_fma_f32 v[16:17], v[140:141], v[114:115], v[16:17] op_sel_hi:[0,1,1]
	v_pk_fma_f32 v[14:15], v[142:143], v[114:115], v[14:15] op_sel_hi:[0,1,1]
	v_pk_fma_f32 v[20:21], v[144:145], v[114:115], v[20:21] op_sel_hi:[0,1,1]
	v_pk_fma_f32 v[18:19], v[146:147], v[114:115], v[18:19] op_sel_hi:[0,1,1]
	v_pk_fma_f32 v[24:25], v[148:149], v[114:115], v[24:25] op_sel_hi:[0,1,1]
	v_pk_fma_f32 v[22:23], v[150:151], v[114:115], v[22:23] op_sel_hi:[0,1,1]
	global_load_dwordx2 v[100:101], v[246:247], off
	v_lshl_add_u64 v[248:249], v[246:247], 0, s[28:29]
	global_load_dwordx2 v[102:103], v[248:249], off
	v_lshl_add_u64 v[248:249], v[248:249], 0, s[28:29]
	global_load_dwordx2 v[104:105], v[248:249], off
	v_lshl_add_u64 v[248:249], v[248:249], 0, s[28:29]
	global_load_dwordx2 v[106:107], v[248:249], off
	v_lshl_add_u64 v[248:249], v[248:249], 0, s[28:29]
	global_load_dwordx2 v[108:109], v[248:249], off
	v_lshl_add_u64 v[248:249], v[248:249], 0, s[28:29]
	global_load_dwordx2 v[110:111], v[248:249], off
	v_lshl_add_u64 v[248:249], v[248:249], 0, s[28:29]
	global_load_dwordx2 v[112:113], v[248:249], off
	v_lshl_add_u64 v[248:249], v[248:249], 0, s[28:29]
	global_load_dwordx2 v[114:115], v[248:249], off
	v_lshl_add_u64 v[246:247], v[246:247], 0, s[6:7]
	v_mov_b32_e32 v27, s9
	s_add_i32 s9, s9, 32
	ds_read_b128 v[28:31], v27
	ds_read_b128 v[32:35], v27 offset:16
	ds_read_b128 v[36:39], v27 offset:4096
	ds_read_b128 v[40:43], v27 offset:4112
	ds_read_b128 v[44:47], v27 offset:8192
	ds_read_b128 v[48:51], v27 offset:8208
	ds_read_b128 v[52:55], v27 offset:12288
	ds_read_b128 v[56:59], v27 offset:12304
	ds_read_b128 v[60:63], v27 offset:16384
	ds_read_b128 v[64:67], v27 offset:16400
	ds_read_b128 v[68:71], v27 offset:20480
	ds_read_b128 v[72:75], v27 offset:20496
	ds_read_b128 v[76:79], v27 offset:24576
	ds_read_b128 v[80:83], v27 offset:24592
	ds_read_b128 v[84:87], v27 offset:28672
	ds_read_b128 v[88:91], v27 offset:28688
	ds_read_b128 v[92:95], v27 offset:32768
	ds_read_b128 v[96:99], v27 offset:32784
	s_waitcnt lgkmcnt(14)
	v_mov_b32_e32 v116, v31
	v_mov_b32_e32 v118, v39
	s_waitcnt lgkmcnt(13)
	v_mov_b32_e32 v120, v47
	s_waitcnt lgkmcnt(11)
	v_mov_b32_e32 v122, v55
	s_waitcnt lgkmcnt(9)
	v_mov_b32_e32 v124, v63
	s_waitcnt lgkmcnt(7)
	v_mov_b32_e32 v126, v71
	s_waitcnt lgkmcnt(5)
	v_mov_b32_e32 v128, v79
	s_waitcnt lgkmcnt(3)
	v_mov_b32_e32 v130, v87
	s_waitcnt lgkmcnt(1)
	v_mov_b32_e32 v138, v95
	v_mov_b32_e32 v132, v35
	v_mov_b32_e32 v134, v43
	v_mov_b32_e32 v136, v51
	v_mov_b32_e32 v140, v59
	v_mov_b32_e32 v142, v67
	v_mov_b32_e32 v144, v75
	v_mov_b32_e32 v146, v83
	v_mov_b32_e32 v148, v91
	s_waitcnt lgkmcnt(0)
	v_mov_b32_e32 v150, v99
	s_waitcnt vmcnt(31)
	v_pk_fma_f32 v[8:9], v[28:29], v[194:195], v[8:9] op_sel_hi:[0,1,1]
	v_pk_fma_f32 v[12:13], v[36:37], v[194:195], v[12:13] op_sel_hi:[0,1,1]
	v_pk_fma_f32 v[10:11], v[44:45], v[194:195], v[10:11] op_sel_hi:[0,1,1]
	v_pk_fma_f32 v[16:17], v[52:53], v[194:195], v[16:17] op_sel_hi:[0,1,1]
	v_pk_fma_f32 v[14:15], v[60:61], v[194:195], v[14:15] op_sel_hi:[0,1,1]
	v_pk_fma_f32 v[20:21], v[68:69], v[194:195], v[20:21] op_sel_hi:[0,1,1]
	v_pk_fma_f32 v[18:19], v[76:77], v[194:195], v[18:19] op_sel_hi:[0,1,1]
	v_pk_fma_f32 v[24:25], v[84:85], v[194:195], v[24:25] op_sel_hi:[0,1,1]
	v_pk_fma_f32 v[22:23], v[92:93], v[194:195], v[22:23] op_sel_hi:[0,1,1]
	s_waitcnt vmcnt(30)
; __global__ void __launch_bounds__(NTHR, 2) trunk_fwd(Args a) {
;     ...
;             for (int k0 = 0; k0 < 128; k0 += 8) { float2 wv[8];
; #pragma unroll
;                 for (int k = 0; k < 8; ++k) wv[k] = *(const float2*)(wp + (size_t)(k0 + k) * 6144);
; #pragma unroll
;                 for (int k = 0; k < 8; ++k)
; #pragma unroll
;                     for (int q = 0; q < 9; ++q) { const float sv = sS[q * 1024 + wave * 128 + k0 + k]; acc0[q] += sv * wv[k].x; acc1[q] += sv * wv[k].y; } }
	v_pk_fma_f32 v[8:9], v[28:29], v[196:197], v[8:9] op_sel:[1,0,0]
	v_pk_fma_f32 v[12:13], v[36:37], v[196:197], v[12:13] op_sel:[1,0,0]
	v_pk_fma_f32 v[10:11], v[44:45], v[196:197], v[10:11] op_sel:[1,0,0]
	v_pk_fma_f32 v[16:17], v[52:53], v[196:197], v[16:17] op_sel:[1,0,0]
	v_pk_fma_f32 v[14:15], v[60:61], v[196:197], v[14:15] op_sel:[1,0,0]
	v_pk_fma_f32 v[20:21], v[68:69], v[196:197], v[20:21] op_sel:[1,0,0]
	v_pk_fma_f32 v[18:19], v[76:77], v[196:197], v[18:19] op_sel:[1,0,0]
	v_pk_fma_f32 v[24:25], v[84:85], v[196:197], v[24:25] op_sel:[1,0,0]
	v_pk_fma_f32 v[22:23], v[92:93], v[196:197], v[22:23] op_sel:[1,0,0]
	s_waitcnt vmcnt(29)
	v_pk_fma_f32 v[8:9], v[30:31], v[198:199], v[8:9] op_sel_hi:[0,1,1]
	v_pk_fma_f32 v[12:13], v[38:39], v[198:199], v[12:13] op_sel_hi:[0,1,1]
	v_pk_fma_f32 v[10:11], v[46:47], v[198:199], v[10:11] op_sel_hi:[0,1,1]
	v_pk_fma_f32 v[16:17], v[54:55], v[198:199], v[16:17] op_sel_hi:[0,1,1]
	v_pk_fma_f32 v[14:15], v[62:63], v[198:199], v[14:15] op_sel_hi:[0,1,1]
	v_pk_fma_f32 v[20:21], v[70:71], v[198:199], v[20:21] op_sel_hi:[0,1,1]
	v_pk_fma_f32 v[18:19], v[78:79], v[198:199], v[18:19] op_sel_hi:[0,1,1]
	v_pk_fma_f32 v[24:25], v[86:87], v[198:199], v[24:25] op_sel_hi:[0,1,1]
	v_pk_fma_f32 v[22:23], v[94:95], v[198:199], v[22:23] op_sel_hi:[0,1,1]
	s_waitcnt vmcnt(28)
	v_pk_fma_f32 v[8:9], v[116:117], v[200:201], v[8:9] op_sel_hi:[0,1,1]
	v_pk_fma_f32 v[12:13], v[118:119], v[200:201], v[12:13] op_sel_hi:[0,1,1]
	v_pk_fma_f32 v[10:11], v[120:121], v[200:201], v[10:11] op_sel_hi:[0,1,1]
	v_pk_fma_f32 v[16:17], v[122:123], v[200:201], v[16:17] op_sel_hi:[0,1,1]
	v_pk_fma_f32 v[14:15], v[124:125], v[200:201], v[14:15] op_sel_hi:[0,1,1]
	v_pk_fma_f32 v[20:21], v[126:127], v[200:201], v[20:21] op_sel_hi:[0,1,1]
	v_pk_fma_f32 v[18:19], v[128:129], v[200:201], v[18:19] op_sel_hi:[0,1,1]
	v_pk_fma_f32 v[24:25], v[130:131], v[200:201], v[24:25] op_sel_hi:[0,1,1]
	v_pk_fma_f32 v[22:23], v[138:139], v[200:201], v[22:23] op_sel_hi:[0,1,1]
	s_waitcnt vmcnt(27)
	v_pk_fma_f32 v[8:9], v[32:33], v[202:203], v[8:9] op_sel_hi:[0,1,1]
	v_pk_fma_f32 v[12:13], v[40:41], v[202:203], v[12:13] op_sel_hi:[0,1,1]
	v_pk_fma_f32 v[10:11], v[48:49], v[202:203], v[10:11] op_sel_hi:[0,1,1]
	v_pk_fma_f32 v[16:17], v[56:57], v[202:203], v[16:17] op_sel_hi:[0,1,1]
	v_pk_fma_f32 v[14:15], v[64:65], v[202:203], v[14:15] op_sel_hi:[0,1,1]
	v_pk_fma_f32 v[20:21], v[72:73], v[202:203], v[20:21] op_sel_hi:[0,1,1]
	v_pk_fma_f32 v[18:19], v[80:81], v[202:203], v[18:19] op_sel_hi:[0,1,1]
	v_pk_fma_f32 v[24:25], v[88:89], v[202:203], v[24:25] op_sel_hi:[0,1,1]
	v_pk_fma_f32 v[22:23], v[96:97], v[202:203], v[22:23] op_sel_hi:[0,1,1]
	s_waitcnt vmcnt(26)
	v_pk_fma_f32 v[8:9], v[32:33], v[204:205], v[8:9] op_sel:[1,0,0]
	v_pk_fma_f32 v[12:13], v[40:41], v[204:205], v[12:13] op_sel:[1,0,0]
	v_pk_fma_f32 v[10:11], v[48:49], v[204:205], v[10:11] op_sel:[1,0,0]
	v_pk_fma_f32 v[16:17], v[56:57], v[204:205], v[16:17] op_sel:[1,0,0]
	v_pk_fma_f32 v[14:15], v[64:65], v[204:205], v[14:15] op_sel:[1,0,0]
	v_pk_fma_f32 v[20:21], v[72:73], v[204:205], v[20:21] op_sel:[1,0,0]
	v_pk_fma_f32 v[18:19], v[80:81], v[204:205], v[18:19] op_sel:[1,0,0]
	v_pk_fma_f32 v[24:25], v[88:89], v[204:205], v[24:25] op_sel:[1,0,0]
	v_pk_fma_f32 v[22:23], v[96:97], v[204:205], v[22:23] op_sel:[1,0,0]
	s_waitcnt vmcnt(25)
	v_pk_fma_f32 v[8:9], v[34:35], v[206:207], v[8:9] op_sel_hi:[0,1,1]
	v_pk_fma_f32 v[12:13], v[42:43], v[206:207], v[12:13] op_sel_hi:[0,1,1]
	v_pk_fma_f32 v[10:11], v[50:51], v[206:207], v[10:11] op_sel_hi:[0,1,1]
	v_pk_fma_f32 v[16:17], v[58:59], v[206:207], v[16:17] op_sel_hi:[0,1,1]
	v_pk_fma_f32 v[14:15], v[66:67], v[206:207], v[14:15] op_sel_hi:[0,1,1]
	v_pk_fma_f32 v[20:21], v[74:75], v[206:207], v[20:21] op_sel_hi:[0,1,1]
	v_pk_fma_f32 v[18:19], v[82:83], v[206:207], v[18:19] op_sel_hi:[0,1,1]
	v_pk_fma_f32 v[24:25], v[90:91], v[206:207], v[24:25] op_sel_hi:[0,1,1]
	v_pk_fma_f32 v[22:23], v[98:99], v[206:207], v[22:23] op_sel_hi:[0,1,1]
	s_waitcnt vmcnt(24)
	v_pk_fma_f32 v[8:9], v[132:133], v[208:209], v[8:9] op_sel_hi:[0,1,1]
	v_pk_fma_f32 v[12:13], v[134:135], v[208:209], v[12:13] op_sel_hi:[0,1,1]
	v_pk_fma_f32 v[10:11], v[136:137], v[208:209], v[10:11] op_sel_hi:[0,1,1]
	v_pk_fma_f32 v[16:17], v[140:141], v[208:209], v[16:17] op_sel_hi:[0,1,1]
	v_pk_fma_f32 v[14:15], v[142:143], v[208:209], v[14:15] op_sel_hi:[0,1,1]
	v_pk_fma_f32 v[20:21], v[144:145], v[208:209], v[20:21] op_sel_hi:[0,1,1]
	v_pk_fma_f32 v[18:19], v[146:147], v[208:209], v[18:19] op_sel_hi:[0,1,1]
	v_pk_fma_f32 v[24:25], v[148:149], v[208:209], v[24:25] op_sel_hi:[0,1,1]
	v_pk_fma_f32 v[22:23], v[150:151], v[208:209], v[22:23] op_sel_hi:[0,1,1]
	global_load_dwordx2 v[194:195], v[246:247], off
	v_lshl_add_u64 v[248:249], v[246:247], 0, s[28:29]
	global_load_dwordx2 v[196:197], v[248:249], off
	v_lshl_add_u64 v[248:249], v[248:249], 0, s[28:29]
	global_load_dwordx2 v[198:199], v[248:249], off
	v_lshl_add_u64 v[248:249], v[248:249], 0, s[28:29]
	global_load_dwordx2 v[200:201], v[248:249], off
	v_lshl_add_u64 v[248:249], v[248:249], 0, s[28:29]
	global_load_dwordx2 v[202:203], v[248:249], off
	v_lshl_add_u64 v[248:249], v[248:249], 0, s[28:29]
	global_load_dwordx2 v[204:205], v[248:249], off
	v_lshl_add_u64 v[248:249], v[248:249], 0, s[28:29]
	global_load_dwordx2 v[206:207], v[248:249], off
	v_lshl_add_u64 v[248:249], v[248:249], 0, s[28:29]
	global_load_dwordx2 v[208:209], v[248:249], off
	v_lshl_add_u64 v[246:247], v[246:247], 0, s[6:7]
	v_mov_b32_e32 v27, s9
	s_add_i32 s9, s9, 32
	ds_read_b128 v[28:31], v27
	ds_read_b128 v[32:35], v27 offset:16
	ds_read_b128 v[36:39], v27 offset:4096
	ds_read_b128 v[40:43], v27 offset:4112
	ds_read_b128 v[44:47], v27 offset:8192
	ds_read_b128 v[48:51], v27 offset:8208
	ds_read_b128 v[52:55], v27 offset:12288
	ds_read_b128 v[56:59], v27 offset:12304
	ds_read_b128 v[60:63], v27 offset:16384
	ds_read_b128 v[64:67], v27 offset:16400
	ds_read_b128 v[68:71], v27 offset:20480
	ds_read_b128 v[72:75], v27 offset:20496
	ds_read_b128 v[76:79], v27 offset:24576
	ds_read_b128 v[80:83], v27 offset:24592
	ds_read_b128 v[84:87], v27 offset:28672
	ds_read_b128 v[88:91], v27 offset:28688
	ds_read_b128 v[92:95], v27 offset:32768
	ds_read_b128 v[96:99], v27 offset:32784
	s_waitcnt lgkmcnt(14)
; __global__ void __launch_bounds__(NTHR, 2) trunk_fwd(Args a) {
;     ...
;             for (int k0 = 0; k0 < 128; k0 += 8) { float2 wv[8];
; #pragma unroll
;                 for (int k = 0; k < 8; ++k) wv[k] = *(const float2*)(wp + (size_t)(k0 + k) * 6144);
; #pragma unroll
;                 for (int k = 0; k < 8; ++k)
; #pragma unroll
;                     for (int q = 0; q < 9; ++q) { const float sv = sS[q * 1024 + wave * 128 + k0 + k]; acc0[q] += sv * wv[k].x; acc1[q] += sv * wv[k].y; } }
	v_mov_b32_e32 v116, v31
	v_mov_b32_e32 v118, v39
	s_waitcnt lgkmcnt(13)
	v_mov_b32_e32 v120, v47
	s_waitcnt lgkmcnt(11)
	v_mov_b32_e32 v122, v55
	s_waitcnt lgkmcnt(9)
	v_mov_b32_e32 v124, v63
	s_waitcnt lgkmcnt(7)
	v_mov_b32_e32 v126, v71
	s_waitcnt lgkmcnt(5)
	v_mov_b32_e32 v128, v79
	s_waitcnt lgkmcnt(3)
	v_mov_b32_e32 v130, v87
	s_waitcnt lgkmcnt(1)
	v_mov_b32_e32 v138, v95
	v_mov_b32_e32 v132, v35
	v_mov_b32_e32 v134, v43
	v_mov_b32_e32 v136, v51
	v_mov_b32_e32 v140, v59
	v_mov_b32_e32 v142, v67
	v_mov_b32_e32 v144, v75
	v_mov_b32_e32 v146, v83
	v_mov_b32_e32 v148, v91
	s_waitcnt lgkmcnt(0)
	v_mov_b32_e32 v150, v99
	s_waitcnt vmcnt(31)
	v_pk_fma_f32 v[8:9], v[28:29], v[214:215], v[8:9] op_sel_hi:[0,1,1]
	v_pk_fma_f32 v[12:13], v[36:37], v[214:215], v[12:13] op_sel_hi:[0,1,1]
	v_pk_fma_f32 v[10:11], v[44:45], v[214:215], v[10:11] op_sel_hi:[0,1,1]
	v_pk_fma_f32 v[16:17], v[52:53], v[214:215], v[16:17] op_sel_hi:[0,1,1]
	v_pk_fma_f32 v[14:15], v[60:61], v[214:215], v[14:15] op_sel_hi:[0,1,1]
	v_pk_fma_f32 v[20:21], v[68:69], v[214:215], v[20:21] op_sel_hi:[0,1,1]
	v_pk_fma_f32 v[18:19], v[76:77], v[214:215], v[18:19] op_sel_hi:[0,1,1]
	v_pk_fma_f32 v[24:25], v[84:85], v[214:215], v[24:25] op_sel_hi:[0,1,1]
	v_pk_fma_f32 v[22:23], v[92:93], v[214:215], v[22:23] op_sel_hi:[0,1,1]
	s_waitcnt vmcnt(30)
	v_pk_fma_f32 v[8:9], v[28:29], v[216:217], v[8:9] op_sel:[1,0,0]
	v_pk_fma_f32 v[12:13], v[36:37], v[216:217], v[12:13] op_sel:[1,0,0]
	v_pk_fma_f32 v[10:11], v[44:45], v[216:217], v[10:11] op_sel:[1,0,0]
	v_pk_fma_f32 v[16:17], v[52:53], v[216:217], v[16:17] op_sel:[1,0,0]
	v_pk_fma_f32 v[14:15], v[60:61], v[216:217], v[14:15] op_sel:[1,0,0]
	v_pk_fma_f32 v[20:21], v[68:69], v[216:217], v[20:21] op_sel:[1,0,0]
	v_pk_fma_f32 v[18:19], v[76:77], v[216:217], v[18:19] op_sel:[1,0,0]
	v_pk_fma_f32 v[24:25], v[84:85], v[216:217], v[24:25] op_sel:[1,0,0]
	v_pk_fma_f32 v[22:23], v[92:93], v[216:217], v[22:23] op_sel:[1,0,0]
	s_waitcnt vmcnt(29)
	v_pk_fma_f32 v[8:9], v[30:31], v[218:219], v[8:9] op_sel_hi:[0,1,1]
	v_pk_fma_f32 v[12:13], v[38:39], v[218:219], v[12:13] op_sel_hi:[0,1,1]
	v_pk_fma_f32 v[10:11], v[46:47], v[218:219], v[10:11] op_sel_hi:[0,1,1]
	v_pk_fma_f32 v[16:17], v[54:55], v[218:219], v[16:17] op_sel_hi:[0,1,1]
	v_pk_fma_f32 v[14:15], v[62:63], v[218:219], v[14:15] op_sel_hi:[0,1,1]
	v_pk_fma_f32 v[20:21], v[70:71], v[218:219], v[20:21] op_sel_hi:[0,1,1]
	v_pk_fma_f32 v[18:19], v[78:79], v[218:219], v[18:19] op_sel_hi:[0,1,1]
	v_pk_fma_f32 v[24:25], v[86:87], v[218:219], v[24:25] op_sel_hi:[0,1,1]
	v_pk_fma_f32 v[22:23], v[94:95], v[218:219], v[22:23] op_sel_hi:[0,1,1]
	s_waitcnt vmcnt(28)
	v_pk_fma_f32 v[8:9], v[116:117], v[220:221], v[8:9] op_sel_hi:[0,1,1]
	v_pk_fma_f32 v[12:13], v[118:119], v[220:221], v[12:13] op_sel_hi:[0,1,1]
	v_pk_fma_f32 v[10:11], v[120:121], v[220:221], v[10:11] op_sel_hi:[0,1,1]
	v_pk_fma_f32 v[16:17], v[122:123], v[220:221], v[16:17] op_sel_hi:[0,1,1]
	v_pk_fma_f32 v[14:15], v[124:125], v[220:221], v[14:15] op_sel_hi:[0,1,1]
	v_pk_fma_f32 v[20:21], v[126:127], v[220:221], v[20:21] op_sel_hi:[0,1,1]
	v_pk_fma_f32 v[18:19], v[128:129], v[220:221], v[18:19] op_sel_hi:[0,1,1]
	v_pk_fma_f32 v[24:25], v[130:131], v[220:221], v[24:25] op_sel_hi:[0,1,1]
	v_pk_fma_f32 v[22:23], v[138:139], v[220:221], v[22:23] op_sel_hi:[0,1,1]
	s_waitcnt vmcnt(27)
	v_pk_fma_f32 v[8:9], v[32:33], v[222:223], v[8:9] op_sel_hi:[0,1,1]
	v_pk_fma_f32 v[12:13], v[40:41], v[222:223], v[12:13] op_sel_hi:[0,1,1]
	v_pk_fma_f32 v[10:11], v[48:49], v[222:223], v[10:11] op_sel_hi:[0,1,1]
	v_pk_fma_f32 v[16:17], v[56:57], v[222:223], v[16:17] op_sel_hi:[0,1,1]
	v_pk_fma_f32 v[14:15], v[64:65], v[222:223], v[14:15] op_sel_hi:[0,1,1]
	v_pk_fma_f32 v[20:21], v[72:73], v[222:223], v[20:21] op_sel_hi:[0,1,1]
	v_pk_fma_f32 v[18:19], v[80:81], v[222:223], v[18:19] op_sel_hi:[0,1,1]
	v_pk_fma_f32 v[24:25], v[88:89], v[222:223], v[24:25] op_sel_hi:[0,1,1]
	v_pk_fma_f32 v[22:23], v[96:97], v[222:223], v[22:23] op_sel_hi:[0,1,1]
	s_waitcnt vmcnt(26)
	v_pk_fma_f32 v[8:9], v[32:33], v[224:225], v[8:9] op_sel:[1,0,0]
	v_pk_fma_f32 v[12:13], v[40:41], v[224:225], v[12:13] op_sel:[1,0,0]
	v_pk_fma_f32 v[10:11], v[48:49], v[224:225], v[10:11] op_sel:[1,0,0]
	v_pk_fma_f32 v[16:17], v[56:57], v[224:225], v[16:17] op_sel:[1,0,0]
	v_pk_fma_f32 v[14:15], v[64:65], v[224:225], v[14:15] op_sel:[1,0,0]
	v_pk_fma_f32 v[20:21], v[72:73], v[224:225], v[20:21] op_sel:[1,0,0]
	v_pk_fma_f32 v[18:19], v[80:81], v[224:225], v[18:19] op_sel:[1,0,0]
	v_pk_fma_f32 v[24:25], v[88:89], v[224:225], v[24:25] op_sel:[1,0,0]
	v_pk_fma_f32 v[22:23], v[96:97], v[224:225], v[22:23] op_sel:[1,0,0]
	s_waitcnt vmcnt(25)
	v_pk_fma_f32 v[8:9], v[34:35], v[226:227], v[8:9] op_sel_hi:[0,1,1]
	v_pk_fma_f32 v[12:13], v[42:43], v[226:227], v[12:13] op_sel_hi:[0,1,1]
	v_pk_fma_f32 v[10:11], v[50:51], v[226:227], v[10:11] op_sel_hi:[0,1,1]
	v_pk_fma_f32 v[16:17], v[58:59], v[226:227], v[16:17] op_sel_hi:[0,1,1]
	v_pk_fma_f32 v[14:15], v[66:67], v[226:227], v[14:15] op_sel_hi:[0,1,1]
	v_pk_fma_f32 v[20:21], v[74:75], v[226:227], v[20:21] op_sel_hi:[0,1,1]
	v_pk_fma_f32 v[18:19], v[82:83], v[226:227], v[18:19] op_sel_hi:[0,1,1]
	v_pk_fma_f32 v[24:25], v[90:91], v[226:227], v[24:25] op_sel_hi:[0,1,1]
	v_pk_fma_f32 v[22:23], v[98:99], v[226:227], v[22:23] op_sel_hi:[0,1,1]
	s_waitcnt vmcnt(24)
; __global__ void __launch_bounds__(NTHR, 2) trunk_fwd(Args a) {
;     ...
;             for (int k0 = 0; k0 < 128; k0 += 8) { float2 wv[8];
; #pragma unroll
;                 for (int k = 0; k < 8; ++k) wv[k] = *(const float2*)(wp + (size_t)(k0 + k) * 6144);
; #pragma unroll
;                 for (int k = 0; k < 8; ++k)
; #pragma unroll
;                     for (int q = 0; q < 9; ++q) { const float sv = sS[q * 1024 + wave * 128 + k0 + k]; acc0[q] += sv * wv[k].x; acc1[q] += sv * wv[k].y; } }
	v_pk_fma_f32 v[8:9], v[132:133], v[228:229], v[8:9] op_sel_hi:[0,1,1]
	v_pk_fma_f32 v[12:13], v[134:135], v[228:229], v[12:13] op_sel_hi:[0,1,1]
	v_pk_fma_f32 v[10:11], v[136:137], v[228:229], v[10:11] op_sel_hi:[0,1,1]
	v_pk_fma_f32 v[16:17], v[140:141], v[228:229], v[16:17] op_sel_hi:[0,1,1]
	v_pk_fma_f32 v[14:15], v[142:143], v[228:229], v[14:15] op_sel_hi:[0,1,1]
	v_pk_fma_f32 v[20:21], v[144:145], v[228:229], v[20:21] op_sel_hi:[0,1,1]
	v_pk_fma_f32 v[18:19], v[146:147], v[228:229], v[18:19] op_sel_hi:[0,1,1]
	v_pk_fma_f32 v[24:25], v[148:149], v[228:229], v[24:25] op_sel_hi:[0,1,1]
	v_pk_fma_f32 v[22:23], v[150:151], v[228:229], v[22:23] op_sel_hi:[0,1,1]
	global_load_dwordx2 v[214:215], v[246:247], off
	v_lshl_add_u64 v[248:249], v[246:247], 0, s[28:29]
	global_load_dwordx2 v[216:217], v[248:249], off
	v_lshl_add_u64 v[248:249], v[248:249], 0, s[28:29]
	global_load_dwordx2 v[218:219], v[248:249], off
	v_lshl_add_u64 v[248:249], v[248:249], 0, s[28:29]
	global_load_dwordx2 v[220:221], v[248:249], off
	v_lshl_add_u64 v[248:249], v[248:249], 0, s[28:29]
	global_load_dwordx2 v[222:223], v[248:249], off
	v_lshl_add_u64 v[248:249], v[248:249], 0, s[28:29]
	global_load_dwordx2 v[224:225], v[248:249], off
	v_lshl_add_u64 v[248:249], v[248:249], 0, s[28:29]
	global_load_dwordx2 v[226:227], v[248:249], off
	v_lshl_add_u64 v[248:249], v[248:249], 0, s[28:29]
	global_load_dwordx2 v[228:229], v[248:249], off
	v_lshl_add_u64 v[246:247], v[246:247], 0, s[6:7]
	v_mov_b32_e32 v27, s9
	s_add_i32 s9, s9, 32
	ds_read_b128 v[28:31], v27
	ds_read_b128 v[32:35], v27 offset:16
	ds_read_b128 v[36:39], v27 offset:4096
	ds_read_b128 v[40:43], v27 offset:4112
	ds_read_b128 v[44:47], v27 offset:8192
	ds_read_b128 v[48:51], v27 offset:8208
	ds_read_b128 v[52:55], v27 offset:12288
	ds_read_b128 v[56:59], v27 offset:12304
	ds_read_b128 v[60:63], v27 offset:16384
	ds_read_b128 v[64:67], v27 offset:16400
	ds_read_b128 v[68:71], v27 offset:20480
	ds_read_b128 v[72:75], v27 offset:20496
	ds_read_b128 v[76:79], v27 offset:24576
	ds_read_b128 v[80:83], v27 offset:24592
	ds_read_b128 v[84:87], v27 offset:28672
	ds_read_b128 v[88:91], v27 offset:28688
	ds_read_b128 v[92:95], v27 offset:32768
	ds_read_b128 v[96:99], v27 offset:32784
	s_waitcnt lgkmcnt(14)
	v_mov_b32_e32 v116, v31
	v_mov_b32_e32 v118, v39
	s_waitcnt lgkmcnt(13)
	v_mov_b32_e32 v120, v47
	s_waitcnt lgkmcnt(11)
	v_mov_b32_e32 v122, v55
	s_waitcnt lgkmcnt(9)
	v_mov_b32_e32 v124, v63
	s_waitcnt lgkmcnt(7)
	v_mov_b32_e32 v126, v71
	s_waitcnt lgkmcnt(5)
	v_mov_b32_e32 v128, v79
	s_waitcnt lgkmcnt(3)
	v_mov_b32_e32 v130, v87
	s_waitcnt lgkmcnt(1)
	v_mov_b32_e32 v138, v95
	v_mov_b32_e32 v132, v35
	v_mov_b32_e32 v134, v43
	v_mov_b32_e32 v136, v51
	v_mov_b32_e32 v140, v59
	v_mov_b32_e32 v142, v67
	v_mov_b32_e32 v144, v75
	v_mov_b32_e32 v146, v83
	v_mov_b32_e32 v148, v91
	s_waitcnt lgkmcnt(0)
	v_mov_b32_e32 v150, v99
	s_waitcnt vmcnt(31)
	v_pk_fma_f32 v[8:9], v[28:29], v[230:231], v[8:9] op_sel_hi:[0,1,1]
	v_pk_fma_f32 v[12:13], v[36:37], v[230:231], v[12:13] op_sel_hi:[0,1,1]
	v_pk_fma_f32 v[10:11], v[44:45], v[230:231], v[10:11] op_sel_hi:[0,1,1]
	v_pk_fma_f32 v[16:17], v[52:53], v[230:231], v[16:17] op_sel_hi:[0,1,1]
	v_pk_fma_f32 v[14:15], v[60:61], v[230:231], v[14:15] op_sel_hi:[0,1,1]
	v_pk_fma_f32 v[20:21], v[68:69], v[230:231], v[20:21] op_sel_hi:[0,1,1]
	v_pk_fma_f32 v[18:19], v[76:77], v[230:231], v[18:19] op_sel_hi:[0,1,1]
	v_pk_fma_f32 v[24:25], v[84:85], v[230:231], v[24:25] op_sel_hi:[0,1,1]
	v_pk_fma_f32 v[22:23], v[92:93], v[230:231], v[22:23] op_sel_hi:[0,1,1]
	s_waitcnt vmcnt(30)
	v_pk_fma_f32 v[8:9], v[28:29], v[232:233], v[8:9] op_sel:[1,0,0]
	v_pk_fma_f32 v[12:13], v[36:37], v[232:233], v[12:13] op_sel:[1,0,0]
	v_pk_fma_f32 v[10:11], v[44:45], v[232:233], v[10:11] op_sel:[1,0,0]
	v_pk_fma_f32 v[16:17], v[52:53], v[232:233], v[16:17] op_sel:[1,0,0]
	v_pk_fma_f32 v[14:15], v[60:61], v[232:233], v[14:15] op_sel:[1,0,0]
	v_pk_fma_f32 v[20:21], v[68:69], v[232:233], v[20:21] op_sel:[1,0,0]
	v_pk_fma_f32 v[18:19], v[76:77], v[232:233], v[18:19] op_sel:[1,0,0]
	v_pk_fma_f32 v[24:25], v[84:85], v[232:233], v[24:25] op_sel:[1,0,0]
	v_pk_fma_f32 v[22:23], v[92:93], v[232:233], v[22:23] op_sel:[1,0,0]
	s_waitcnt vmcnt(29)
	v_pk_fma_f32 v[8:9], v[30:31], v[234:235], v[8:9] op_sel_hi:[0,1,1]
	v_pk_fma_f32 v[12:13], v[38:39], v[234:235], v[12:13] op_sel_hi:[0,1,1]
	v_pk_fma_f32 v[10:11], v[46:47], v[234:235], v[10:11] op_sel_hi:[0,1,1]
	v_pk_fma_f32 v[16:17], v[54:55], v[234:235], v[16:17] op_sel_hi:[0,1,1]
	v_pk_fma_f32 v[14:15], v[62:63], v[234:235], v[14:15] op_sel_hi:[0,1,1]
	v_pk_fma_f32 v[20:21], v[70:71], v[234:235], v[20:21] op_sel_hi:[0,1,1]
	v_pk_fma_f32 v[18:19], v[78:79], v[234:235], v[18:19] op_sel_hi:[0,1,1]
	v_pk_fma_f32 v[24:25], v[86:87], v[234:235], v[24:25] op_sel_hi:[0,1,1]
	v_pk_fma_f32 v[22:23], v[94:95], v[234:235], v[22:23] op_sel_hi:[0,1,1]
	s_waitcnt vmcnt(28)
	v_pk_fma_f32 v[8:9], v[116:117], v[236:237], v[8:9] op_sel_hi:[0,1,1]
	v_pk_fma_f32 v[12:13], v[118:119], v[236:237], v[12:13] op_sel_hi:[0,1,1]
	v_pk_fma_f32 v[10:11], v[120:121], v[236:237], v[10:11] op_sel_hi:[0,1,1]
	v_pk_fma_f32 v[16:17], v[122:123], v[236:237], v[16:17] op_sel_hi:[0,1,1]
	v_pk_fma_f32 v[14:15], v[124:125], v[236:237], v[14:15] op_sel_hi:[0,1,1]
	v_pk_fma_f32 v[20:21], v[126:127], v[236:237], v[20:21] op_sel_hi:[0,1,1]
	v_pk_fma_f32 v[18:19], v[128:129], v[236:237], v[18:19] op_sel_hi:[0,1,1]
	v_pk_fma_f32 v[24:25], v[130:131], v[236:237], v[24:25] op_sel_hi:[0,1,1]
	v_pk_fma_f32 v[22:23], v[138:139], v[236:237], v[22:23] op_sel_hi:[0,1,1]
	s_waitcnt vmcnt(27)
; __global__ void __launch_bounds__(NTHR, 2) trunk_fwd(Args a) {
;     ...
;             for (int k0 = 0; k0 < 128; k0 += 8) { float2 wv[8];
; #pragma unroll
;                 for (int k = 0; k < 8; ++k) wv[k] = *(const float2*)(wp + (size_t)(k0 + k) * 6144);
; #pragma unroll
;                 for (int k = 0; k < 8; ++k)
; #pragma unroll
;                     for (int q = 0; q < 9; ++q) { const float sv = sS[q * 1024 + wave * 128 + k0 + k]; acc0[q] += sv * wv[k].x; acc1[q] += sv * wv[k].y; } }
	v_pk_fma_f32 v[8:9], v[32:33], v[238:239], v[8:9] op_sel_hi:[0,1,1]
	v_pk_fma_f32 v[12:13], v[40:41], v[238:239], v[12:13] op_sel_hi:[0,1,1]
	v_pk_fma_f32 v[10:11], v[48:49], v[238:239], v[10:11] op_sel_hi:[0,1,1]
	v_pk_fma_f32 v[16:17], v[56:57], v[238:239], v[16:17] op_sel_hi:[0,1,1]
	v_pk_fma_f32 v[14:15], v[64:65], v[238:239], v[14:15] op_sel_hi:[0,1,1]
	v_pk_fma_f32 v[20:21], v[72:73], v[238:239], v[20:21] op_sel_hi:[0,1,1]
	v_pk_fma_f32 v[18:19], v[80:81], v[238:239], v[18:19] op_sel_hi:[0,1,1]
	v_pk_fma_f32 v[24:25], v[88:89], v[238:239], v[24:25] op_sel_hi:[0,1,1]
	v_pk_fma_f32 v[22:23], v[96:97], v[238:239], v[22:23] op_sel_hi:[0,1,1]
	s_waitcnt vmcnt(26)
	v_pk_fma_f32 v[8:9], v[32:33], v[240:241], v[8:9] op_sel:[1,0,0]
	v_pk_fma_f32 v[12:13], v[40:41], v[240:241], v[12:13] op_sel:[1,0,0]
	v_pk_fma_f32 v[10:11], v[48:49], v[240:241], v[10:11] op_sel:[1,0,0]
	v_pk_fma_f32 v[16:17], v[56:57], v[240:241], v[16:17] op_sel:[1,0,0]
	v_pk_fma_f32 v[14:15], v[64:65], v[240:241], v[14:15] op_sel:[1,0,0]
	v_pk_fma_f32 v[20:21], v[72:73], v[240:241], v[20:21] op_sel:[1,0,0]
	v_pk_fma_f32 v[18:19], v[80:81], v[240:241], v[18:19] op_sel:[1,0,0]
	v_pk_fma_f32 v[24:25], v[88:89], v[240:241], v[24:25] op_sel:[1,0,0]
	v_pk_fma_f32 v[22:23], v[96:97], v[240:241], v[22:23] op_sel:[1,0,0]
	s_waitcnt vmcnt(25)
	v_pk_fma_f32 v[8:9], v[34:35], v[242:243], v[8:9] op_sel_hi:[0,1,1]
	v_pk_fma_f32 v[12:13], v[42:43], v[242:243], v[12:13] op_sel_hi:[0,1,1]
	v_pk_fma_f32 v[10:11], v[50:51], v[242:243], v[10:11] op_sel_hi:[0,1,1]
	v_pk_fma_f32 v[16:17], v[58:59], v[242:243], v[16:17] op_sel_hi:[0,1,1]
	v_pk_fma_f32 v[14:15], v[66:67], v[242:243], v[14:15] op_sel_hi:[0,1,1]
	v_pk_fma_f32 v[20:21], v[74:75], v[242:243], v[20:21] op_sel_hi:[0,1,1]
	v_pk_fma_f32 v[18:19], v[82:83], v[242:243], v[18:19] op_sel_hi:[0,1,1]
	v_pk_fma_f32 v[24:25], v[90:91], v[242:243], v[24:25] op_sel_hi:[0,1,1]
	v_pk_fma_f32 v[22:23], v[98:99], v[242:243], v[22:23] op_sel_hi:[0,1,1]
	s_waitcnt vmcnt(24)
	v_pk_fma_f32 v[8:9], v[132:133], v[244:245], v[8:9] op_sel_hi:[0,1,1]
	v_pk_fma_f32 v[12:13], v[134:135], v[244:245], v[12:13] op_sel_hi:[0,1,1]
	v_pk_fma_f32 v[10:11], v[136:137], v[244:245], v[10:11] op_sel_hi:[0,1,1]
	v_pk_fma_f32 v[16:17], v[140:141], v[244:245], v[16:17] op_sel_hi:[0,1,1]
	v_pk_fma_f32 v[14:15], v[142:143], v[244:245], v[14:15] op_sel_hi:[0,1,1]
	v_pk_fma_f32 v[20:21], v[144:145], v[244:245], v[20:21] op_sel_hi:[0,1,1]
	v_pk_fma_f32 v[18:19], v[146:147], v[244:245], v[18:19] op_sel_hi:[0,1,1]
	v_pk_fma_f32 v[24:25], v[148:149], v[244:245], v[24:25] op_sel_hi:[0,1,1]
	v_pk_fma_f32 v[22:23], v[150:151], v[244:245], v[22:23] op_sel_hi:[0,1,1]
	global_load_dwordx2 v[230:231], v[246:247], off
	v_lshl_add_u64 v[248:249], v[246:247], 0, s[28:29]
	global_load_dwordx2 v[232:233], v[248:249], off
	v_lshl_add_u64 v[248:249], v[248:249], 0, s[28:29]
	global_load_dwordx2 v[234:235], v[248:249], off
	v_lshl_add_u64 v[248:249], v[248:249], 0, s[28:29]
	global_load_dwordx2 v[236:237], v[248:249], off
	v_lshl_add_u64 v[248:249], v[248:249], 0, s[28:29]
	global_load_dwordx2 v[238:239], v[248:249], off
	v_lshl_add_u64 v[248:249], v[248:249], 0, s[28:29]
	global_load_dwordx2 v[240:241], v[248:249], off
	v_lshl_add_u64 v[248:249], v[248:249], 0, s[28:29]
	global_load_dwordx2 v[242:243], v[248:249], off
	v_lshl_add_u64 v[248:249], v[248:249], 0, s[28:29]
	global_load_dwordx2 v[244:245], v[248:249], off
	v_lshl_add_u64 v[246:247], v[246:247], 0, s[6:7]
	v_mov_b32_e32 v27, s9
	s_add_i32 s9, s9, 32
	ds_read_b128 v[28:31], v27
	ds_read_b128 v[32:35], v27 offset:16
	ds_read_b128 v[36:39], v27 offset:4096
	ds_read_b128 v[40:43], v27 offset:4112
	ds_read_b128 v[44:47], v27 offset:8192
	ds_read_b128 v[48:51], v27 offset:8208
	ds_read_b128 v[52:55], v27 offset:12288
	ds_read_b128 v[56:59], v27 offset:12304
	ds_read_b128 v[60:63], v27 offset:16384
	ds_read_b128 v[64:67], v27 offset:16400
	ds_read_b128 v[68:71], v27 offset:20480
	ds_read_b128 v[72:75], v27 offset:20496
	ds_read_b128 v[76:79], v27 offset:24576
	ds_read_b128 v[80:83], v27 offset:24592
	ds_read_b128 v[84:87], v27 offset:28672
	ds_read_b128 v[88:91], v27 offset:28688
	ds_read_b128 v[92:95], v27 offset:32768
	ds_read_b128 v[96:99], v27 offset:32784
	s_waitcnt lgkmcnt(14)
	v_mov_b32_e32 v116, v31
	v_mov_b32_e32 v118, v39
	s_waitcnt lgkmcnt(13)
	v_mov_b32_e32 v120, v47
	s_waitcnt lgkmcnt(11)
	v_mov_b32_e32 v122, v55
	s_waitcnt lgkmcnt(9)
	v_mov_b32_e32 v124, v63
	s_waitcnt lgkmcnt(7)
	v_mov_b32_e32 v126, v71
	s_waitcnt lgkmcnt(5)
	v_mov_b32_e32 v128, v79
	s_waitcnt lgkmcnt(3)
	v_mov_b32_e32 v130, v87
	s_waitcnt lgkmcnt(1)
	v_mov_b32_e32 v138, v95
	v_mov_b32_e32 v132, v35
	v_mov_b32_e32 v134, v43
	v_mov_b32_e32 v136, v51
	v_mov_b32_e32 v140, v59
	v_mov_b32_e32 v142, v67
	v_mov_b32_e32 v144, v75
	v_mov_b32_e32 v146, v83
	v_mov_b32_e32 v148, v91
	s_waitcnt lgkmcnt(0)
	v_mov_b32_e32 v150, v99
	s_waitcnt vmcnt(31)
	v_pk_fma_f32 v[8:9], v[28:29], v[100:101], v[8:9] op_sel_hi:[0,1,1]
	v_pk_fma_f32 v[12:13], v[36:37], v[100:101], v[12:13] op_sel_hi:[0,1,1]
	v_pk_fma_f32 v[10:11], v[44:45], v[100:101], v[10:11] op_sel_hi:[0,1,1]
	v_pk_fma_f32 v[16:17], v[52:53], v[100:101], v[16:17] op_sel_hi:[0,1,1]
	v_pk_fma_f32 v[14:15], v[60:61], v[100:101], v[14:15] op_sel_hi:[0,1,1]
	v_pk_fma_f32 v[20:21], v[68:69], v[100:101], v[20:21] op_sel_hi:[0,1,1]
	v_pk_fma_f32 v[18:19], v[76:77], v[100:101], v[18:19] op_sel_hi:[0,1,1]
	v_pk_fma_f32 v[24:25], v[84:85], v[100:101], v[24:25] op_sel_hi:[0,1,1]
	v_pk_fma_f32 v[22:23], v[92:93], v[100:101], v[22:23] op_sel_hi:[0,1,1]
	s_waitcnt vmcnt(30)
; __global__ void __launch_bounds__(NTHR, 2) trunk_fwd(Args a) {
;     ...
;             for (int k0 = 0; k0 < 128; k0 += 8) { float2 wv[8];
; #pragma unroll
;                 for (int k = 0; k < 8; ++k) wv[k] = *(const float2*)(wp + (size_t)(k0 + k) * 6144);
; #pragma unroll
;                 for (int k = 0; k < 8; ++k)
; #pragma unroll
;                     for (int q = 0; q < 9; ++q) { const float sv = sS[q * 1024 + wave * 128 + k0 + k]; acc0[q] += sv * wv[k].x; acc1[q] += sv * wv[k].y; } }
	v_pk_fma_f32 v[8:9], v[28:29], v[102:103], v[8:9] op_sel:[1,0,0]
	v_pk_fma_f32 v[12:13], v[36:37], v[102:103], v[12:13] op_sel:[1,0,0]
	v_pk_fma_f32 v[10:11], v[44:45], v[102:103], v[10:11] op_sel:[1,0,0]
	v_pk_fma_f32 v[16:17], v[52:53], v[102:103], v[16:17] op_sel:[1,0,0]
	v_pk_fma_f32 v[14:15], v[60:61], v[102:103], v[14:15] op_sel:[1,0,0]
	v_pk_fma_f32 v[20:21], v[68:69], v[102:103], v[20:21] op_sel:[1,0,0]
	v_pk_fma_f32 v[18:19], v[76:77], v[102:103], v[18:19] op_sel:[1,0,0]
	v_pk_fma_f32 v[24:25], v[84:85], v[102:103], v[24:25] op_sel:[1,0,0]
	v_pk_fma_f32 v[22:23], v[92:93], v[102:103], v[22:23] op_sel:[1,0,0]
	s_waitcnt vmcnt(29)
	v_pk_fma_f32 v[8:9], v[30:31], v[104:105], v[8:9] op_sel_hi:[0,1,1]
	v_pk_fma_f32 v[12:13], v[38:39], v[104:105], v[12:13] op_sel_hi:[0,1,1]
	v_pk_fma_f32 v[10:11], v[46:47], v[104:105], v[10:11] op_sel_hi:[0,1,1]
	v_pk_fma_f32 v[16:17], v[54:55], v[104:105], v[16:17] op_sel_hi:[0,1,1]
	v_pk_fma_f32 v[14:15], v[62:63], v[104:105], v[14:15] op_sel_hi:[0,1,1]
	v_pk_fma_f32 v[20:21], v[70:71], v[104:105], v[20:21] op_sel_hi:[0,1,1]
	v_pk_fma_f32 v[18:19], v[78:79], v[104:105], v[18:19] op_sel_hi:[0,1,1]
	v_pk_fma_f32 v[24:25], v[86:87], v[104:105], v[24:25] op_sel_hi:[0,1,1]
	v_pk_fma_f32 v[22:23], v[94:95], v[104:105], v[22:23] op_sel_hi:[0,1,1]
	s_waitcnt vmcnt(28)
	v_pk_fma_f32 v[8:9], v[116:117], v[106:107], v[8:9] op_sel_hi:[0,1,1]
	v_pk_fma_f32 v[12:13], v[118:119], v[106:107], v[12:13] op_sel_hi:[0,1,1]
	v_pk_fma_f32 v[10:11], v[120:121], v[106:107], v[10:11] op_sel_hi:[0,1,1]
	v_pk_fma_f32 v[16:17], v[122:123], v[106:107], v[16:17] op_sel_hi:[0,1,1]
	v_pk_fma_f32 v[14:15], v[124:125], v[106:107], v[14:15] op_sel_hi:[0,1,1]
	v_pk_fma_f32 v[20:21], v[126:127], v[106:107], v[20:21] op_sel_hi:[0,1,1]
	v_pk_fma_f32 v[18:19], v[128:129], v[106:107], v[18:19] op_sel_hi:[0,1,1]
	v_pk_fma_f32 v[24:25], v[130:131], v[106:107], v[24:25] op_sel_hi:[0,1,1]
	v_pk_fma_f32 v[22:23], v[138:139], v[106:107], v[22:23] op_sel_hi:[0,1,1]
	s_waitcnt vmcnt(27)
	v_pk_fma_f32 v[8:9], v[32:33], v[108:109], v[8:9] op_sel_hi:[0,1,1]
	v_pk_fma_f32 v[12:13], v[40:41], v[108:109], v[12:13] op_sel_hi:[0,1,1]
	v_pk_fma_f32 v[10:11], v[48:49], v[108:109], v[10:11] op_sel_hi:[0,1,1]
	v_pk_fma_f32 v[16:17], v[56:57], v[108:109], v[16:17] op_sel_hi:[0,1,1]
	v_pk_fma_f32 v[14:15], v[64:65], v[108:109], v[14:15] op_sel_hi:[0,1,1]
	v_pk_fma_f32 v[20:21], v[72:73], v[108:109], v[20:21] op_sel_hi:[0,1,1]
	v_pk_fma_f32 v[18:19], v[80:81], v[108:109], v[18:19] op_sel_hi:[0,1,1]
	v_pk_fma_f32 v[24:25], v[88:89], v[108:109], v[24:25] op_sel_hi:[0,1,1]
	v_pk_fma_f32 v[22:23], v[96:97], v[108:109], v[22:23] op_sel_hi:[0,1,1]
	s_waitcnt vmcnt(26)
	v_pk_fma_f32 v[8:9], v[32:33], v[110:111], v[8:9] op_sel:[1,0,0]
	v_pk_fma_f32 v[12:13], v[40:41], v[110:111], v[12:13] op_sel:[1,0,0]
	v_pk_fma_f32 v[10:11], v[48:49], v[110:111], v[10:11] op_sel:[1,0,0]
	v_pk_fma_f32 v[16:17], v[56:57], v[110:111], v[16:17] op_sel:[1,0,0]
	v_pk_fma_f32 v[14:15], v[64:65], v[110:111], v[14:15] op_sel:[1,0,0]
	v_pk_fma_f32 v[20:21], v[72:73], v[110:111], v[20:21] op_sel:[1,0,0]
	v_pk_fma_f32 v[18:19], v[80:81], v[110:111], v[18:19] op_sel:[1,0,0]
	v_pk_fma_f32 v[24:25], v[88:89], v[110:111], v[24:25] op_sel:[1,0,0]
	v_pk_fma_f32 v[22:23], v[96:97], v[110:111], v[22:23] op_sel:[1,0,0]
	s_waitcnt vmcnt(25)
	v_pk_fma_f32 v[8:9], v[34:35], v[112:113], v[8:9] op_sel_hi:[0,1,1]
	v_pk_fma_f32 v[12:13], v[42:43], v[112:113], v[12:13] op_sel_hi:[0,1,1]
	v_pk_fma_f32 v[10:11], v[50:51], v[112:113], v[10:11] op_sel_hi:[0,1,1]
	v_pk_fma_f32 v[16:17], v[58:59], v[112:113], v[16:17] op_sel_hi:[0,1,1]
	v_pk_fma_f32 v[14:15], v[66:67], v[112:113], v[14:15] op_sel_hi:[0,1,1]
	v_pk_fma_f32 v[20:21], v[74:75], v[112:113], v[20:21] op_sel_hi:[0,1,1]
	v_pk_fma_f32 v[18:19], v[82:83], v[112:113], v[18:19] op_sel_hi:[0,1,1]
	v_pk_fma_f32 v[24:25], v[90:91], v[112:113], v[24:25] op_sel_hi:[0,1,1]
	v_pk_fma_f32 v[22:23], v[98:99], v[112:113], v[22:23] op_sel_hi:[0,1,1]
	s_waitcnt vmcnt(24)
	v_pk_fma_f32 v[8:9], v[132:133], v[114:115], v[8:9] op_sel_hi:[0,1,1]
	v_pk_fma_f32 v[12:13], v[134:135], v[114:115], v[12:13] op_sel_hi:[0,1,1]
	v_pk_fma_f32 v[10:11], v[136:137], v[114:115], v[10:11] op_sel_hi:[0,1,1]
	v_pk_fma_f32 v[16:17], v[140:141], v[114:115], v[16:17] op_sel_hi:[0,1,1]
	v_pk_fma_f32 v[14:15], v[142:143], v[114:115], v[14:15] op_sel_hi:[0,1,1]
	v_pk_fma_f32 v[20:21], v[144:145], v[114:115], v[20:21] op_sel_hi:[0,1,1]
	v_pk_fma_f32 v[18:19], v[146:147], v[114:115], v[18:19] op_sel_hi:[0,1,1]
	v_pk_fma_f32 v[24:25], v[148:149], v[114:115], v[24:25] op_sel_hi:[0,1,1]
	v_pk_fma_f32 v[22:23], v[150:151], v[114:115], v[22:23] op_sel_hi:[0,1,1]
	global_load_dwordx2 v[100:101], v[246:247], off
	v_lshl_add_u64 v[248:249], v[246:247], 0, s[28:29]
	global_load_dwordx2 v[102:103], v[248:249], off
	v_lshl_add_u64 v[248:249], v[248:249], 0, s[28:29]
	global_load_dwordx2 v[104:105], v[248:249], off
	v_lshl_add_u64 v[248:249], v[248:249], 0, s[28:29]
	global_load_dwordx2 v[106:107], v[248:249], off
	v_lshl_add_u64 v[248:249], v[248:249], 0, s[28:29]
	global_load_dwordx2 v[108:109], v[248:249], off
	v_lshl_add_u64 v[248:249], v[248:249], 0, s[28:29]
	global_load_dwordx2 v[110:111], v[248:249], off
	v_lshl_add_u64 v[248:249], v[248:249], 0, s[28:29]
	global_load_dwordx2 v[112:113], v[248:249], off
	v_lshl_add_u64 v[248:249], v[248:249], 0, s[28:29]
	global_load_dwordx2 v[114:115], v[248:249], off
	v_lshl_add_u64 v[246:247], v[246:247], 0, s[6:7]
	v_mov_b32_e32 v27, s9
	s_add_i32 s9, s9, 32
	ds_read_b128 v[28:31], v27
	ds_read_b128 v[32:35], v27 offset:16
	ds_read_b128 v[36:39], v27 offset:4096
	ds_read_b128 v[40:43], v27 offset:4112
	ds_read_b128 v[44:47], v27 offset:8192
	ds_read_b128 v[48:51], v27 offset:8208
	ds_read_b128 v[52:55], v27 offset:12288
	ds_read_b128 v[56:59], v27 offset:12304
	ds_read_b128 v[60:63], v27 offset:16384
	ds_read_b128 v[64:67], v27 offset:16400
	ds_read_b128 v[68:71], v27 offset:20480
	ds_read_b128 v[72:75], v27 offset:20496
	ds_read_b128 v[76:79], v27 offset:24576
	ds_read_b128 v[80:83], v27 offset:24592
	ds_read_b128 v[84:87], v27 offset:28672
	ds_read_b128 v[88:91], v27 offset:28688
	ds_read_b128 v[92:95], v27 offset:32768
	ds_read_b128 v[96:99], v27 offset:32784
	s_waitcnt lgkmcnt(14)
; __global__ void __launch_bounds__(NTHR, 2) trunk_fwd(Args a) {
;     ...
;             for (int k0 = 0; k0 < 128; k0 += 8) { float2 wv[8];
; #pragma unroll
;                 for (int k = 0; k < 8; ++k) wv[k] = *(const float2*)(wp + (size_t)(k0 + k) * 6144);
; #pragma unroll
;                 for (int k = 0; k < 8; ++k)
; #pragma unroll
;                     for (int q = 0; q < 9; ++q) { const float sv = sS[q * 1024 + wave * 128 + k0 + k]; acc0[q] += sv * wv[k].x; acc1[q] += sv * wv[k].y; } }
	v_mov_b32_e32 v116, v31
	v_mov_b32_e32 v118, v39
	s_waitcnt lgkmcnt(13)
	v_mov_b32_e32 v120, v47
	s_waitcnt lgkmcnt(11)
	v_mov_b32_e32 v122, v55
	s_waitcnt lgkmcnt(9)
	v_mov_b32_e32 v124, v63
	s_waitcnt lgkmcnt(7)
	v_mov_b32_e32 v126, v71
	s_waitcnt lgkmcnt(5)
	v_mov_b32_e32 v128, v79
	s_waitcnt lgkmcnt(3)
	v_mov_b32_e32 v130, v87
	s_waitcnt lgkmcnt(1)
	v_mov_b32_e32 v138, v95
	v_mov_b32_e32 v132, v35
	v_mov_b32_e32 v134, v43
	v_mov_b32_e32 v136, v51
	v_mov_b32_e32 v140, v59
	v_mov_b32_e32 v142, v67
	v_mov_b32_e32 v144, v75
	v_mov_b32_e32 v146, v83
	v_mov_b32_e32 v148, v91
	s_waitcnt lgkmcnt(0)
	v_mov_b32_e32 v150, v99
	s_waitcnt vmcnt(31)
	v_pk_fma_f32 v[8:9], v[28:29], v[194:195], v[8:9] op_sel_hi:[0,1,1]
	v_pk_fma_f32 v[12:13], v[36:37], v[194:195], v[12:13] op_sel_hi:[0,1,1]
	v_pk_fma_f32 v[10:11], v[44:45], v[194:195], v[10:11] op_sel_hi:[0,1,1]
	v_pk_fma_f32 v[16:17], v[52:53], v[194:195], v[16:17] op_sel_hi:[0,1,1]
	v_pk_fma_f32 v[14:15], v[60:61], v[194:195], v[14:15] op_sel_hi:[0,1,1]
	v_pk_fma_f32 v[20:21], v[68:69], v[194:195], v[20:21] op_sel_hi:[0,1,1]
	v_pk_fma_f32 v[18:19], v[76:77], v[194:195], v[18:19] op_sel_hi:[0,1,1]
	v_pk_fma_f32 v[24:25], v[84:85], v[194:195], v[24:25] op_sel_hi:[0,1,1]
	v_pk_fma_f32 v[22:23], v[92:93], v[194:195], v[22:23] op_sel_hi:[0,1,1]
	s_waitcnt vmcnt(30)
	v_pk_fma_f32 v[8:9], v[28:29], v[196:197], v[8:9] op_sel:[1,0,0]
	v_pk_fma_f32 v[12:13], v[36:37], v[196:197], v[12:13] op_sel:[1,0,0]
	v_pk_fma_f32 v[10:11], v[44:45], v[196:197], v[10:11] op_sel:[1,0,0]
	v_pk_fma_f32 v[16:17], v[52:53], v[196:197], v[16:17] op_sel:[1,0,0]
	v_pk_fma_f32 v[14:15], v[60:61], v[196:197], v[14:15] op_sel:[1,0,0]
	v_pk_fma_f32 v[20:21], v[68:69], v[196:197], v[20:21] op_sel:[1,0,0]
	v_pk_fma_f32 v[18:19], v[76:77], v[196:197], v[18:19] op_sel:[1,0,0]
	v_pk_fma_f32 v[24:25], v[84:85], v[196:197], v[24:25] op_sel:[1,0,0]
	v_pk_fma_f32 v[22:23], v[92:93], v[196:197], v[22:23] op_sel:[1,0,0]
	s_waitcnt vmcnt(29)
	v_pk_fma_f32 v[8:9], v[30:31], v[198:199], v[8:9] op_sel_hi:[0,1,1]
	v_pk_fma_f32 v[12:13], v[38:39], v[198:199], v[12:13] op_sel_hi:[0,1,1]
	v_pk_fma_f32 v[10:11], v[46:47], v[198:199], v[10:11] op_sel_hi:[0,1,1]
	v_pk_fma_f32 v[16:17], v[54:55], v[198:199], v[16:17] op_sel_hi:[0,1,1]
	v_pk_fma_f32 v[14:15], v[62:63], v[198:199], v[14:15] op_sel_hi:[0,1,1]
	v_pk_fma_f32 v[20:21], v[70:71], v[198:199], v[20:21] op_sel_hi:[0,1,1]
	v_pk_fma_f32 v[18:19], v[78:79], v[198:199], v[18:19] op_sel_hi:[0,1,1]
	v_pk_fma_f32 v[24:25], v[86:87], v[198:199], v[24:25] op_sel_hi:[0,1,1]
	v_pk_fma_f32 v[22:23], v[94:95], v[198:199], v[22:23] op_sel_hi:[0,1,1]
	s_waitcnt vmcnt(28)
	v_pk_fma_f32 v[8:9], v[116:117], v[200:201], v[8:9] op_sel_hi:[0,1,1]
	v_pk_fma_f32 v[12:13], v[118:119], v[200:201], v[12:13] op_sel_hi:[0,1,1]
	v_pk_fma_f32 v[10:11], v[120:121], v[200:201], v[10:11] op_sel_hi:[0,1,1]
	v_pk_fma_f32 v[16:17], v[122:123], v[200:201], v[16:17] op_sel_hi:[0,1,1]
	v_pk_fma_f32 v[14:15], v[124:125], v[200:201], v[14:15] op_sel_hi:[0,1,1]
	v_pk_fma_f32 v[20:21], v[126:127], v[200:201], v[20:21] op_sel_hi:[0,1,1]
	v_pk_fma_f32 v[18:19], v[128:129], v[200:201], v[18:19] op_sel_hi:[0,1,1]
	v_pk_fma_f32 v[24:25], v[130:131], v[200:201], v[24:25] op_sel_hi:[0,1,1]
	v_pk_fma_f32 v[22:23], v[138:139], v[200:201], v[22:23] op_sel_hi:[0,1,1]
	s_waitcnt vmcnt(27)
	v_pk_fma_f32 v[8:9], v[32:33], v[202:203], v[8:9] op_sel_hi:[0,1,1]
	v_pk_fma_f32 v[12:13], v[40:41], v[202:203], v[12:13] op_sel_hi:[0,1,1]
	v_pk_fma_f32 v[10:11], v[48:49], v[202:203], v[10:11] op_sel_hi:[0,1,1]
	v_pk_fma_f32 v[16:17], v[56:57], v[202:203], v[16:17] op_sel_hi:[0,1,1]
	v_pk_fma_f32 v[14:15], v[64:65], v[202:203], v[14:15] op_sel_hi:[0,1,1]
	v_pk_fma_f32 v[20:21], v[72:73], v[202:203], v[20:21] op_sel_hi:[0,1,1]
	v_pk_fma_f32 v[18:19], v[80:81], v[202:203], v[18:19] op_sel_hi:[0,1,1]
	v_pk_fma_f32 v[24:25], v[88:89], v[202:203], v[24:25] op_sel_hi:[0,1,1]
	v_pk_fma_f32 v[22:23], v[96:97], v[202:203], v[22:23] op_sel_hi:[0,1,1]
	s_waitcnt vmcnt(26)
	v_pk_fma_f32 v[8:9], v[32:33], v[204:205], v[8:9] op_sel:[1,0,0]
	v_pk_fma_f32 v[12:13], v[40:41], v[204:205], v[12:13] op_sel:[1,0,0]
	v_pk_fma_f32 v[10:11], v[48:49], v[204:205], v[10:11] op_sel:[1,0,0]
	v_pk_fma_f32 v[16:17], v[56:57], v[204:205], v[16:17] op_sel:[1,0,0]
	v_pk_fma_f32 v[14:15], v[64:65], v[204:205], v[14:15] op_sel:[1,0,0]
	v_pk_fma_f32 v[20:21], v[72:73], v[204:205], v[20:21] op_sel:[1,0,0]
	v_pk_fma_f32 v[18:19], v[80:81], v[204:205], v[18:19] op_sel:[1,0,0]
	v_pk_fma_f32 v[24:25], v[88:89], v[204:205], v[24:25] op_sel:[1,0,0]
	v_pk_fma_f32 v[22:23], v[96:97], v[204:205], v[22:23] op_sel:[1,0,0]
	s_waitcnt vmcnt(25)
	v_pk_fma_f32 v[8:9], v[34:35], v[206:207], v[8:9] op_sel_hi:[0,1,1]
	v_pk_fma_f32 v[12:13], v[42:43], v[206:207], v[12:13] op_sel_hi:[0,1,1]
	v_pk_fma_f32 v[10:11], v[50:51], v[206:207], v[10:11] op_sel_hi:[0,1,1]
	v_pk_fma_f32 v[16:17], v[58:59], v[206:207], v[16:17] op_sel_hi:[0,1,1]
	v_pk_fma_f32 v[14:15], v[66:67], v[206:207], v[14:15] op_sel_hi:[0,1,1]
	v_pk_fma_f32 v[20:21], v[74:75], v[206:207], v[20:21] op_sel_hi:[0,1,1]
	v_pk_fma_f32 v[18:19], v[82:83], v[206:207], v[18:19] op_sel_hi:[0,1,1]
	v_pk_fma_f32 v[24:25], v[90:91], v[206:207], v[24:25] op_sel_hi:[0,1,1]
	v_pk_fma_f32 v[22:23], v[98:99], v[206:207], v[22:23] op_sel_hi:[0,1,1]
	s_waitcnt vmcnt(24)
; __global__ void __launch_bounds__(NTHR, 2) trunk_fwd(Args a) {
;     ...
;             for (int k0 = 0; k0 < 128; k0 += 8) { float2 wv[8];
; #pragma unroll
;                 for (int k = 0; k < 8; ++k) wv[k] = *(const float2*)(wp + (size_t)(k0 + k) * 6144);
; #pragma unroll
;                 for (int k = 0; k < 8; ++k)
; #pragma unroll
;                     for (int q = 0; q < 9; ++q) { const float sv = sS[q * 1024 + wave * 128 + k0 + k]; acc0[q] += sv * wv[k].x; acc1[q] += sv * wv[k].y; } }
	v_pk_fma_f32 v[8:9], v[132:133], v[208:209], v[8:9] op_sel_hi:[0,1,1]
	v_pk_fma_f32 v[12:13], v[134:135], v[208:209], v[12:13] op_sel_hi:[0,1,1]
	v_pk_fma_f32 v[10:11], v[136:137], v[208:209], v[10:11] op_sel_hi:[0,1,1]
	v_pk_fma_f32 v[16:17], v[140:141], v[208:209], v[16:17] op_sel_hi:[0,1,1]
	v_pk_fma_f32 v[14:15], v[142:143], v[208:209], v[14:15] op_sel_hi:[0,1,1]
	v_pk_fma_f32 v[20:21], v[144:145], v[208:209], v[20:21] op_sel_hi:[0,1,1]
	v_pk_fma_f32 v[18:19], v[146:147], v[208:209], v[18:19] op_sel_hi:[0,1,1]
	v_pk_fma_f32 v[24:25], v[148:149], v[208:209], v[24:25] op_sel_hi:[0,1,1]
	v_pk_fma_f32 v[22:23], v[150:151], v[208:209], v[22:23] op_sel_hi:[0,1,1]
	global_load_dwordx2 v[194:195], v[246:247], off
	v_lshl_add_u64 v[248:249], v[246:247], 0, s[28:29]
	global_load_dwordx2 v[196:197], v[248:249], off
	v_lshl_add_u64 v[248:249], v[248:249], 0, s[28:29]
	global_load_dwordx2 v[198:199], v[248:249], off
	v_lshl_add_u64 v[248:249], v[248:249], 0, s[28:29]
	global_load_dwordx2 v[200:201], v[248:249], off
	v_lshl_add_u64 v[248:249], v[248:249], 0, s[28:29]
	global_load_dwordx2 v[202:203], v[248:249], off
	v_lshl_add_u64 v[248:249], v[248:249], 0, s[28:29]
	global_load_dwordx2 v[204:205], v[248:249], off
	v_lshl_add_u64 v[248:249], v[248:249], 0, s[28:29]
	global_load_dwordx2 v[206:207], v[248:249], off
	v_lshl_add_u64 v[248:249], v[248:249], 0, s[28:29]
	global_load_dwordx2 v[208:209], v[248:249], off
	v_lshl_add_u64 v[246:247], v[246:247], 0, s[6:7]
	v_mov_b32_e32 v27, s9
	s_add_i32 s9, s9, 32
	ds_read_b128 v[28:31], v27
	ds_read_b128 v[32:35], v27 offset:16
	ds_read_b128 v[36:39], v27 offset:4096
	ds_read_b128 v[40:43], v27 offset:4112
	ds_read_b128 v[44:47], v27 offset:8192
	ds_read_b128 v[48:51], v27 offset:8208
	ds_read_b128 v[52:55], v27 offset:12288
	ds_read_b128 v[56:59], v27 offset:12304
	ds_read_b128 v[60:63], v27 offset:16384
	ds_read_b128 v[64:67], v27 offset:16400
	ds_read_b128 v[68:71], v27 offset:20480
	ds_read_b128 v[72:75], v27 offset:20496
	ds_read_b128 v[76:79], v27 offset:24576
	ds_read_b128 v[80:83], v27 offset:24592
	ds_read_b128 v[84:87], v27 offset:28672
	ds_read_b128 v[88:91], v27 offset:28688
	ds_read_b128 v[92:95], v27 offset:32768
	ds_read_b128 v[96:99], v27 offset:32784
	s_waitcnt lgkmcnt(14)
	v_mov_b32_e32 v116, v31
	v_mov_b32_e32 v118, v39
	s_waitcnt lgkmcnt(13)
	v_mov_b32_e32 v120, v47
	s_waitcnt lgkmcnt(11)
	v_mov_b32_e32 v122, v55
	s_waitcnt lgkmcnt(9)
	v_mov_b32_e32 v124, v63
	s_waitcnt lgkmcnt(7)
	v_mov_b32_e32 v126, v71
	s_waitcnt lgkmcnt(5)
	v_mov_b32_e32 v128, v79
	s_waitcnt lgkmcnt(3)
	v_mov_b32_e32 v130, v87
	s_waitcnt lgkmcnt(1)
	v_mov_b32_e32 v138, v95
	v_mov_b32_e32 v132, v35
	v_mov_b32_e32 v134, v43
	v_mov_b32_e32 v136, v51
	v_mov_b32_e32 v140, v59
	v_mov_b32_e32 v142, v67
	v_mov_b32_e32 v144, v75
	v_mov_b32_e32 v146, v83
	v_mov_b32_e32 v148, v91
	s_waitcnt lgkmcnt(0)
	v_mov_b32_e32 v150, v99
	s_waitcnt vmcnt(31)
	v_pk_fma_f32 v[8:9], v[28:29], v[214:215], v[8:9] op_sel_hi:[0,1,1]
	v_pk_fma_f32 v[12:13], v[36:37], v[214:215], v[12:13] op_sel_hi:[0,1,1]
	v_pk_fma_f32 v[10:11], v[44:45], v[214:215], v[10:11] op_sel_hi:[0,1,1]
	v_pk_fma_f32 v[16:17], v[52:53], v[214:215], v[16:17] op_sel_hi:[0,1,1]
	v_pk_fma_f32 v[14:15], v[60:61], v[214:215], v[14:15] op_sel_hi:[0,1,1]
	v_pk_fma_f32 v[20:21], v[68:69], v[214:215], v[20:21] op_sel_hi:[0,1,1]
	v_pk_fma_f32 v[18:19], v[76:77], v[214:215], v[18:19] op_sel_hi:[0,1,1]
	v_pk_fma_f32 v[24:25], v[84:85], v[214:215], v[24:25] op_sel_hi:[0,1,1]
	v_pk_fma_f32 v[22:23], v[92:93], v[214:215], v[22:23] op_sel_hi:[0,1,1]
	s_waitcnt vmcnt(30)
	v_pk_fma_f32 v[8:9], v[28:29], v[216:217], v[8:9] op_sel:[1,0,0]
	v_pk_fma_f32 v[12:13], v[36:37], v[216:217], v[12:13] op_sel:[1,0,0]
	v_pk_fma_f32 v[10:11], v[44:45], v[216:217], v[10:11] op_sel:[1,0,0]
	v_pk_fma_f32 v[16:17], v[52:53], v[216:217], v[16:17] op_sel:[1,0,0]
	v_pk_fma_f32 v[14:15], v[60:61], v[216:217], v[14:15] op_sel:[1,0,0]
	v_pk_fma_f32 v[20:21], v[68:69], v[216:217], v[20:21] op_sel:[1,0,0]
	v_pk_fma_f32 v[18:19], v[76:77], v[216:217], v[18:19] op_sel:[1,0,0]
	v_pk_fma_f32 v[24:25], v[84:85], v[216:217], v[24:25] op_sel:[1,0,0]
	v_pk_fma_f32 v[22:23], v[92:93], v[216:217], v[22:23] op_sel:[1,0,0]
	s_waitcnt vmcnt(29)
	v_pk_fma_f32 v[8:9], v[30:31], v[218:219], v[8:9] op_sel_hi:[0,1,1]
	v_pk_fma_f32 v[12:13], v[38:39], v[218:219], v[12:13] op_sel_hi:[0,1,1]
	v_pk_fma_f32 v[10:11], v[46:47], v[218:219], v[10:11] op_sel_hi:[0,1,1]
	v_pk_fma_f32 v[16:17], v[54:55], v[218:219], v[16:17] op_sel_hi:[0,1,1]
	v_pk_fma_f32 v[14:15], v[62:63], v[218:219], v[14:15] op_sel_hi:[0,1,1]
	v_pk_fma_f32 v[20:21], v[70:71], v[218:219], v[20:21] op_sel_hi:[0,1,1]
	v_pk_fma_f32 v[18:19], v[78:79], v[218:219], v[18:19] op_sel_hi:[0,1,1]
	v_pk_fma_f32 v[24:25], v[86:87], v[218:219], v[24:25] op_sel_hi:[0,1,1]
	v_pk_fma_f32 v[22:23], v[94:95], v[218:219], v[22:23] op_sel_hi:[0,1,1]
	s_waitcnt vmcnt(28)
	v_pk_fma_f32 v[8:9], v[116:117], v[220:221], v[8:9] op_sel_hi:[0,1,1]
	v_pk_fma_f32 v[12:13], v[118:119], v[220:221], v[12:13] op_sel_hi:[0,1,1]
	v_pk_fma_f32 v[10:11], v[120:121], v[220:221], v[10:11] op_sel_hi:[0,1,1]
	v_pk_fma_f32 v[16:17], v[122:123], v[220:221], v[16:17] op_sel_hi:[0,1,1]
	v_pk_fma_f32 v[14:15], v[124:125], v[220:221], v[14:15] op_sel_hi:[0,1,1]
	v_pk_fma_f32 v[20:21], v[126:127], v[220:221], v[20:21] op_sel_hi:[0,1,1]
	v_pk_fma_f32 v[18:19], v[128:129], v[220:221], v[18:19] op_sel_hi:[0,1,1]
	v_pk_fma_f32 v[24:25], v[130:131], v[220:221], v[24:25] op_sel_hi:[0,1,1]
	v_pk_fma_f32 v[22:23], v[138:139], v[220:221], v[22:23] op_sel_hi:[0,1,1]
	s_waitcnt vmcnt(27)
; __global__ void __launch_bounds__(NTHR, 2) trunk_fwd(Args a) {
;     ...
;             for (int k0 = 0; k0 < 128; k0 += 8) { float2 wv[8];
; #pragma unroll
;                 for (int k = 0; k < 8; ++k) wv[k] = *(const float2*)(wp + (size_t)(k0 + k) * 6144);
; #pragma unroll
;                 for (int k = 0; k < 8; ++k)
; #pragma unroll
;                     for (int q = 0; q < 9; ++q) { const float sv = sS[q * 1024 + wave * 128 + k0 + k]; acc0[q] += sv * wv[k].x; acc1[q] += sv * wv[k].y; } }
	v_pk_fma_f32 v[8:9], v[32:33], v[222:223], v[8:9] op_sel_hi:[0,1,1]
	v_pk_fma_f32 v[12:13], v[40:41], v[222:223], v[12:13] op_sel_hi:[0,1,1]
	v_pk_fma_f32 v[10:11], v[48:49], v[222:223], v[10:11] op_sel_hi:[0,1,1]
	v_pk_fma_f32 v[16:17], v[56:57], v[222:223], v[16:17] op_sel_hi:[0,1,1]
	v_pk_fma_f32 v[14:15], v[64:65], v[222:223], v[14:15] op_sel_hi:[0,1,1]
	v_pk_fma_f32 v[20:21], v[72:73], v[222:223], v[20:21] op_sel_hi:[0,1,1]
	v_pk_fma_f32 v[18:19], v[80:81], v[222:223], v[18:19] op_sel_hi:[0,1,1]
	v_pk_fma_f32 v[24:25], v[88:89], v[222:223], v[24:25] op_sel_hi:[0,1,1]
	v_pk_fma_f32 v[22:23], v[96:97], v[222:223], v[22:23] op_sel_hi:[0,1,1]
	s_waitcnt vmcnt(26)
	v_pk_fma_f32 v[8:9], v[32:33], v[224:225], v[8:9] op_sel:[1,0,0]
	v_pk_fma_f32 v[12:13], v[40:41], v[224:225], v[12:13] op_sel:[1,0,0]
	v_pk_fma_f32 v[10:11], v[48:49], v[224:225], v[10:11] op_sel:[1,0,0]
	v_pk_fma_f32 v[16:17], v[56:57], v[224:225], v[16:17] op_sel:[1,0,0]
	v_pk_fma_f32 v[14:15], v[64:65], v[224:225], v[14:15] op_sel:[1,0,0]
	v_pk_fma_f32 v[20:21], v[72:73], v[224:225], v[20:21] op_sel:[1,0,0]
	v_pk_fma_f32 v[18:19], v[80:81], v[224:225], v[18:19] op_sel:[1,0,0]
	v_pk_fma_f32 v[24:25], v[88:89], v[224:225], v[24:25] op_sel:[1,0,0]
	v_pk_fma_f32 v[22:23], v[96:97], v[224:225], v[22:23] op_sel:[1,0,0]
	s_waitcnt vmcnt(25)
	v_pk_fma_f32 v[8:9], v[34:35], v[226:227], v[8:9] op_sel_hi:[0,1,1]
	v_pk_fma_f32 v[12:13], v[42:43], v[226:227], v[12:13] op_sel_hi:[0,1,1]
	v_pk_fma_f32 v[10:11], v[50:51], v[226:227], v[10:11] op_sel_hi:[0,1,1]
	v_pk_fma_f32 v[16:17], v[58:59], v[226:227], v[16:17] op_sel_hi:[0,1,1]
	v_pk_fma_f32 v[14:15], v[66:67], v[226:227], v[14:15] op_sel_hi:[0,1,1]
	v_pk_fma_f32 v[20:21], v[74:75], v[226:227], v[20:21] op_sel_hi:[0,1,1]
	v_pk_fma_f32 v[18:19], v[82:83], v[226:227], v[18:19] op_sel_hi:[0,1,1]
	v_pk_fma_f32 v[24:25], v[90:91], v[226:227], v[24:25] op_sel_hi:[0,1,1]
	v_pk_fma_f32 v[22:23], v[98:99], v[226:227], v[22:23] op_sel_hi:[0,1,1]
	s_waitcnt vmcnt(24)
	v_pk_fma_f32 v[8:9], v[132:133], v[228:229], v[8:9] op_sel_hi:[0,1,1]
	v_pk_fma_f32 v[12:13], v[134:135], v[228:229], v[12:13] op_sel_hi:[0,1,1]
	v_pk_fma_f32 v[10:11], v[136:137], v[228:229], v[10:11] op_sel_hi:[0,1,1]
	v_pk_fma_f32 v[16:17], v[140:141], v[228:229], v[16:17] op_sel_hi:[0,1,1]
	v_pk_fma_f32 v[14:15], v[142:143], v[228:229], v[14:15] op_sel_hi:[0,1,1]
	v_pk_fma_f32 v[20:21], v[144:145], v[228:229], v[20:21] op_sel_hi:[0,1,1]
	v_pk_fma_f32 v[18:19], v[146:147], v[228:229], v[18:19] op_sel_hi:[0,1,1]
	v_pk_fma_f32 v[24:25], v[148:149], v[228:229], v[24:25] op_sel_hi:[0,1,1]
	v_pk_fma_f32 v[22:23], v[150:151], v[228:229], v[22:23] op_sel_hi:[0,1,1]
	global_load_dwordx2 v[214:215], v[246:247], off
	v_lshl_add_u64 v[248:249], v[246:247], 0, s[28:29]
	global_load_dwordx2 v[216:217], v[248:249], off
	v_lshl_add_u64 v[248:249], v[248:249], 0, s[28:29]
	global_load_dwordx2 v[218:219], v[248:249], off
	v_lshl_add_u64 v[248:249], v[248:249], 0, s[28:29]
	global_load_dwordx2 v[220:221], v[248:249], off
	v_lshl_add_u64 v[248:249], v[248:249], 0, s[28:29]
	global_load_dwordx2 v[222:223], v[248:249], off
	v_lshl_add_u64 v[248:249], v[248:249], 0, s[28:29]
	global_load_dwordx2 v[224:225], v[248:249], off
	v_lshl_add_u64 v[248:249], v[248:249], 0, s[28:29]
	global_load_dwordx2 v[226:227], v[248:249], off
	v_lshl_add_u64 v[248:249], v[248:249], 0, s[28:29]
	global_load_dwordx2 v[228:229], v[248:249], off
	v_lshl_add_u64 v[246:247], v[246:247], 0, s[6:7]
	v_mov_b32_e32 v27, s9
	s_add_i32 s9, s9, 32
	ds_read_b128 v[28:31], v27
	ds_read_b128 v[32:35], v27 offset:16
	ds_read_b128 v[36:39], v27 offset:4096
	ds_read_b128 v[40:43], v27 offset:4112
	ds_read_b128 v[44:47], v27 offset:8192
	ds_read_b128 v[48:51], v27 offset:8208
	ds_read_b128 v[52:55], v27 offset:12288
	ds_read_b128 v[56:59], v27 offset:12304
	ds_read_b128 v[60:63], v27 offset:16384
	ds_read_b128 v[64:67], v27 offset:16400
	ds_read_b128 v[68:71], v27 offset:20480
	ds_read_b128 v[72:75], v27 offset:20496
	ds_read_b128 v[76:79], v27 offset:24576
	ds_read_b128 v[80:83], v27 offset:24592
	ds_read_b128 v[84:87], v27 offset:28672
	ds_read_b128 v[88:91], v27 offset:28688
	ds_read_b128 v[92:95], v27 offset:32768
	ds_read_b128 v[96:99], v27 offset:32784
	s_waitcnt lgkmcnt(14)
	v_mov_b32_e32 v116, v31
	v_mov_b32_e32 v118, v39
	s_waitcnt lgkmcnt(13)
	v_mov_b32_e32 v120, v47
	s_waitcnt lgkmcnt(11)
	v_mov_b32_e32 v122, v55
	s_waitcnt lgkmcnt(9)
	v_mov_b32_e32 v124, v63
	s_waitcnt lgkmcnt(7)
	v_mov_b32_e32 v126, v71
	s_waitcnt lgkmcnt(5)
	v_mov_b32_e32 v128, v79
	s_waitcnt lgkmcnt(3)
	v_mov_b32_e32 v130, v87
	s_waitcnt lgkmcnt(1)
	v_mov_b32_e32 v138, v95
	v_mov_b32_e32 v132, v35
	v_mov_b32_e32 v134, v43
	v_mov_b32_e32 v136, v51
	v_mov_b32_e32 v140, v59
	v_mov_b32_e32 v142, v67
	v_mov_b32_e32 v144, v75
	v_mov_b32_e32 v146, v83
	v_mov_b32_e32 v148, v91
	s_waitcnt lgkmcnt(0)
	v_mov_b32_e32 v150, v99
	s_waitcnt vmcnt(31)
	v_pk_fma_f32 v[8:9], v[28:29], v[230:231], v[8:9] op_sel_hi:[0,1,1]
	v_pk_fma_f32 v[12:13], v[36:37], v[230:231], v[12:13] op_sel_hi:[0,1,1]
	v_pk_fma_f32 v[10:11], v[44:45], v[230:231], v[10:11] op_sel_hi:[0,1,1]
	v_pk_fma_f32 v[16:17], v[52:53], v[230:231], v[16:17] op_sel_hi:[0,1,1]
	v_pk_fma_f32 v[14:15], v[60:61], v[230:231], v[14:15] op_sel_hi:[0,1,1]
	v_pk_fma_f32 v[20:21], v[68:69], v[230:231], v[20:21] op_sel_hi:[0,1,1]
	v_pk_fma_f32 v[18:19], v[76:77], v[230:231], v[18:19] op_sel_hi:[0,1,1]
	v_pk_fma_f32 v[24:25], v[84:85], v[230:231], v[24:25] op_sel_hi:[0,1,1]
	v_pk_fma_f32 v[22:23], v[92:93], v[230:231], v[22:23] op_sel_hi:[0,1,1]
	s_waitcnt vmcnt(30)
; __global__ void __launch_bounds__(NTHR, 2) trunk_fwd(Args a) {
;     ...
;             for (int k0 = 0; k0 < 128; k0 += 8) { float2 wv[8];
; #pragma unroll
;                 for (int k = 0; k < 8; ++k) wv[k] = *(const float2*)(wp + (size_t)(k0 + k) * 6144);
; #pragma unroll
;                 for (int k = 0; k < 8; ++k)
; #pragma unroll
;                     for (int q = 0; q < 9; ++q) { const float sv = sS[q * 1024 + wave * 128 + k0 + k]; acc0[q] += sv * wv[k].x; acc1[q] += sv * wv[k].y; } }
	v_pk_fma_f32 v[8:9], v[28:29], v[232:233], v[8:9] op_sel:[1,0,0]
	v_pk_fma_f32 v[12:13], v[36:37], v[232:233], v[12:13] op_sel:[1,0,0]
	v_pk_fma_f32 v[10:11], v[44:45], v[232:233], v[10:11] op_sel:[1,0,0]
	v_pk_fma_f32 v[16:17], v[52:53], v[232:233], v[16:17] op_sel:[1,0,0]
	v_pk_fma_f32 v[14:15], v[60:61], v[232:233], v[14:15] op_sel:[1,0,0]
	v_pk_fma_f32 v[20:21], v[68:69], v[232:233], v[20:21] op_sel:[1,0,0]
	v_pk_fma_f32 v[18:19], v[76:77], v[232:233], v[18:19] op_sel:[1,0,0]
	v_pk_fma_f32 v[24:25], v[84:85], v[232:233], v[24:25] op_sel:[1,0,0]
	v_pk_fma_f32 v[22:23], v[92:93], v[232:233], v[22:23] op_sel:[1,0,0]
	s_waitcnt vmcnt(29)
	v_pk_fma_f32 v[8:9], v[30:31], v[234:235], v[8:9] op_sel_hi:[0,1,1]
	v_pk_fma_f32 v[12:13], v[38:39], v[234:235], v[12:13] op_sel_hi:[0,1,1]
	v_pk_fma_f32 v[10:11], v[46:47], v[234:235], v[10:11] op_sel_hi:[0,1,1]
	v_pk_fma_f32 v[16:17], v[54:55], v[234:235], v[16:17] op_sel_hi:[0,1,1]
	v_pk_fma_f32 v[14:15], v[62:63], v[234:235], v[14:15] op_sel_hi:[0,1,1]
	v_pk_fma_f32 v[20:21], v[70:71], v[234:235], v[20:21] op_sel_hi:[0,1,1]
	v_pk_fma_f32 v[18:19], v[78:79], v[234:235], v[18:19] op_sel_hi:[0,1,1]
	v_pk_fma_f32 v[24:25], v[86:87], v[234:235], v[24:25] op_sel_hi:[0,1,1]
	v_pk_fma_f32 v[22:23], v[94:95], v[234:235], v[22:23] op_sel_hi:[0,1,1]
	s_waitcnt vmcnt(28)
	v_pk_fma_f32 v[8:9], v[116:117], v[236:237], v[8:9] op_sel_hi:[0,1,1]
	v_pk_fma_f32 v[12:13], v[118:119], v[236:237], v[12:13] op_sel_hi:[0,1,1]
	v_pk_fma_f32 v[10:11], v[120:121], v[236:237], v[10:11] op_sel_hi:[0,1,1]
	v_pk_fma_f32 v[16:17], v[122:123], v[236:237], v[16:17] op_sel_hi:[0,1,1]
	v_pk_fma_f32 v[14:15], v[124:125], v[236:237], v[14:15] op_sel_hi:[0,1,1]
	v_pk_fma_f32 v[20:21], v[126:127], v[236:237], v[20:21] op_sel_hi:[0,1,1]
	v_pk_fma_f32 v[18:19], v[128:129], v[236:237], v[18:19] op_sel_hi:[0,1,1]
	v_pk_fma_f32 v[24:25], v[130:131], v[236:237], v[24:25] op_sel_hi:[0,1,1]
	v_pk_fma_f32 v[22:23], v[138:139], v[236:237], v[22:23] op_sel_hi:[0,1,1]
	s_waitcnt vmcnt(27)
	v_pk_fma_f32 v[8:9], v[32:33], v[238:239], v[8:9] op_sel_hi:[0,1,1]
	v_pk_fma_f32 v[12:13], v[40:41], v[238:239], v[12:13] op_sel_hi:[0,1,1]
	v_pk_fma_f32 v[10:11], v[48:49], v[238:239], v[10:11] op_sel_hi:[0,1,1]
	v_pk_fma_f32 v[16:17], v[56:57], v[238:239], v[16:17] op_sel_hi:[0,1,1]
	v_pk_fma_f32 v[14:15], v[64:65], v[238:239], v[14:15] op_sel_hi:[0,1,1]
	v_pk_fma_f32 v[20:21], v[72:73], v[238:239], v[20:21] op_sel_hi:[0,1,1]
	v_pk_fma_f32 v[18:19], v[80:81], v[238:239], v[18:19] op_sel_hi:[0,1,1]
	v_pk_fma_f32 v[24:25], v[88:89], v[238:239], v[24:25] op_sel_hi:[0,1,1]
	v_pk_fma_f32 v[22:23], v[96:97], v[238:239], v[22:23] op_sel_hi:[0,1,1]
	s_waitcnt vmcnt(26)
	v_pk_fma_f32 v[8:9], v[32:33], v[240:241], v[8:9] op_sel:[1,0,0]
	v_pk_fma_f32 v[12:13], v[40:41], v[240:241], v[12:13] op_sel:[1,0,0]
	v_pk_fma_f32 v[10:11], v[48:49], v[240:241], v[10:11] op_sel:[1,0,0]
	v_pk_fma_f32 v[16:17], v[56:57], v[240:241], v[16:17] op_sel:[1,0,0]
	v_pk_fma_f32 v[14:15], v[64:65], v[240:241], v[14:15] op_sel:[1,0,0]
	v_pk_fma_f32 v[20:21], v[72:73], v[240:241], v[20:21] op_sel:[1,0,0]
	v_pk_fma_f32 v[18:19], v[80:81], v[240:241], v[18:19] op_sel:[1,0,0]
	v_pk_fma_f32 v[24:25], v[88:89], v[240:241], v[24:25] op_sel:[1,0,0]
	v_pk_fma_f32 v[22:23], v[96:97], v[240:241], v[22:23] op_sel:[1,0,0]
	s_waitcnt vmcnt(25)
	v_pk_fma_f32 v[8:9], v[34:35], v[242:243], v[8:9] op_sel_hi:[0,1,1]
	v_pk_fma_f32 v[12:13], v[42:43], v[242:243], v[12:13] op_sel_hi:[0,1,1]
	v_pk_fma_f32 v[10:11], v[50:51], v[242:243], v[10:11] op_sel_hi:[0,1,1]
	v_pk_fma_f32 v[16:17], v[58:59], v[242:243], v[16:17] op_sel_hi:[0,1,1]
	v_pk_fma_f32 v[14:15], v[66:67], v[242:243], v[14:15] op_sel_hi:[0,1,1]
	v_pk_fma_f32 v[20:21], v[74:75], v[242:243], v[20:21] op_sel_hi:[0,1,1]
	v_pk_fma_f32 v[18:19], v[82:83], v[242:243], v[18:19] op_sel_hi:[0,1,1]
	v_pk_fma_f32 v[24:25], v[90:91], v[242:243], v[24:25] op_sel_hi:[0,1,1]
	v_pk_fma_f32 v[22:23], v[98:99], v[242:243], v[22:23] op_sel_hi:[0,1,1]
	s_waitcnt vmcnt(24)
	v_pk_fma_f32 v[8:9], v[132:133], v[244:245], v[8:9] op_sel_hi:[0,1,1]
	v_pk_fma_f32 v[12:13], v[134:135], v[244:245], v[12:13] op_sel_hi:[0,1,1]
	v_pk_fma_f32 v[10:11], v[136:137], v[244:245], v[10:11] op_sel_hi:[0,1,1]
	v_pk_fma_f32 v[16:17], v[140:141], v[244:245], v[16:17] op_sel_hi:[0,1,1]
	v_pk_fma_f32 v[14:15], v[142:143], v[244:245], v[14:15] op_sel_hi:[0,1,1]
	v_pk_fma_f32 v[20:21], v[144:145], v[244:245], v[20:21] op_sel_hi:[0,1,1]
	v_pk_fma_f32 v[18:19], v[146:147], v[244:245], v[18:19] op_sel_hi:[0,1,1]
	v_pk_fma_f32 v[24:25], v[148:149], v[244:245], v[24:25] op_sel_hi:[0,1,1]
	v_pk_fma_f32 v[22:23], v[150:151], v[244:245], v[22:23] op_sel_hi:[0,1,1]
	global_load_dwordx2 v[230:231], v[246:247], off
	v_lshl_add_u64 v[248:249], v[246:247], 0, s[28:29]
	global_load_dwordx2 v[232:233], v[248:249], off
	v_lshl_add_u64 v[248:249], v[248:249], 0, s[28:29]
	global_load_dwordx2 v[234:235], v[248:249], off
	v_lshl_add_u64 v[248:249], v[248:249], 0, s[28:29]
	global_load_dwordx2 v[236:237], v[248:249], off
	v_lshl_add_u64 v[248:249], v[248:249], 0, s[28:29]
	global_load_dwordx2 v[238:239], v[248:249], off
	v_lshl_add_u64 v[248:249], v[248:249], 0, s[28:29]
	global_load_dwordx2 v[240:241], v[248:249], off
	v_lshl_add_u64 v[248:249], v[248:249], 0, s[28:29]
	global_load_dwordx2 v[242:243], v[248:249], off
	v_lshl_add_u64 v[248:249], v[248:249], 0, s[28:29]
	global_load_dwordx2 v[244:245], v[248:249], off
	v_lshl_add_u64 v[246:247], v[246:247], 0, s[6:7]
	v_mov_b32_e32 v27, s9
	s_add_i32 s9, s9, 32
	ds_read_b128 v[28:31], v27
	ds_read_b128 v[32:35], v27 offset:16
	ds_read_b128 v[36:39], v27 offset:4096
	ds_read_b128 v[40:43], v27 offset:4112
	ds_read_b128 v[44:47], v27 offset:8192
	ds_read_b128 v[48:51], v27 offset:8208
	ds_read_b128 v[52:55], v27 offset:12288
	ds_read_b128 v[56:59], v27 offset:12304
	ds_read_b128 v[60:63], v27 offset:16384
	ds_read_b128 v[64:67], v27 offset:16400
	ds_read_b128 v[68:71], v27 offset:20480
	ds_read_b128 v[72:75], v27 offset:20496
	ds_read_b128 v[76:79], v27 offset:24576
	ds_read_b128 v[80:83], v27 offset:24592
	ds_read_b128 v[84:87], v27 offset:28672
	ds_read_b128 v[88:91], v27 offset:28688
	ds_read_b128 v[92:95], v27 offset:32768
	ds_read_b128 v[96:99], v27 offset:32784
	s_waitcnt lgkmcnt(14)
; __global__ void __launch_bounds__(NTHR, 2) trunk_fwd(Args a) {
;     ...
;             for (int k0 = 0; k0 < 128; k0 += 8) { float2 wv[8];
; #pragma unroll
;                 for (int k = 0; k < 8; ++k) wv[k] = *(const float2*)(wp + (size_t)(k0 + k) * 6144);
; #pragma unroll
;                 for (int k = 0; k < 8; ++k)
; #pragma unroll
;                     for (int q = 0; q < 9; ++q) { const float sv = sS[q * 1024 + wave * 128 + k0 + k]; acc0[q] += sv * wv[k].x; acc1[q] += sv * wv[k].y; } }
	v_mov_b32_e32 v116, v31
	v_mov_b32_e32 v118, v39
	s_waitcnt lgkmcnt(13)
	v_mov_b32_e32 v120, v47
	s_waitcnt lgkmcnt(11)
	v_mov_b32_e32 v122, v55
	s_waitcnt lgkmcnt(9)
	v_mov_b32_e32 v124, v63
	s_waitcnt lgkmcnt(7)
	v_mov_b32_e32 v126, v71
	s_waitcnt lgkmcnt(5)
	v_mov_b32_e32 v128, v79
	s_waitcnt lgkmcnt(3)
	v_mov_b32_e32 v130, v87
	s_waitcnt lgkmcnt(1)
	v_mov_b32_e32 v138, v95
	v_mov_b32_e32 v132, v35
	v_mov_b32_e32 v134, v43
	v_mov_b32_e32 v136, v51
	v_mov_b32_e32 v140, v59
	v_mov_b32_e32 v142, v67
	v_mov_b32_e32 v144, v75
	v_mov_b32_e32 v146, v83
	v_mov_b32_e32 v148, v91
	s_waitcnt lgkmcnt(0)
	v_mov_b32_e32 v150, v99
	s_waitcnt vmcnt(31)
	v_pk_fma_f32 v[8:9], v[28:29], v[100:101], v[8:9] op_sel_hi:[0,1,1]
	v_pk_fma_f32 v[12:13], v[36:37], v[100:101], v[12:13] op_sel_hi:[0,1,1]
	v_pk_fma_f32 v[10:11], v[44:45], v[100:101], v[10:11] op_sel_hi:[0,1,1]
	v_pk_fma_f32 v[16:17], v[52:53], v[100:101], v[16:17] op_sel_hi:[0,1,1]
	v_pk_fma_f32 v[14:15], v[60:61], v[100:101], v[14:15] op_sel_hi:[0,1,1]
	v_pk_fma_f32 v[20:21], v[68:69], v[100:101], v[20:21] op_sel_hi:[0,1,1]
	v_pk_fma_f32 v[18:19], v[76:77], v[100:101], v[18:19] op_sel_hi:[0,1,1]
	v_pk_fma_f32 v[24:25], v[84:85], v[100:101], v[24:25] op_sel_hi:[0,1,1]
	v_pk_fma_f32 v[22:23], v[92:93], v[100:101], v[22:23] op_sel_hi:[0,1,1]
	s_waitcnt vmcnt(30)
	v_pk_fma_f32 v[8:9], v[28:29], v[102:103], v[8:9] op_sel:[1,0,0]
	v_pk_fma_f32 v[12:13], v[36:37], v[102:103], v[12:13] op_sel:[1,0,0]
	v_pk_fma_f32 v[10:11], v[44:45], v[102:103], v[10:11] op_sel:[1,0,0]
	v_pk_fma_f32 v[16:17], v[52:53], v[102:103], v[16:17] op_sel:[1,0,0]
	v_pk_fma_f32 v[14:15], v[60:61], v[102:103], v[14:15] op_sel:[1,0,0]
	v_pk_fma_f32 v[20:21], v[68:69], v[102:103], v[20:21] op_sel:[1,0,0]
	v_pk_fma_f32 v[18:19], v[76:77], v[102:103], v[18:19] op_sel:[1,0,0]
	v_pk_fma_f32 v[24:25], v[84:85], v[102:103], v[24:25] op_sel:[1,0,0]
	v_pk_fma_f32 v[22:23], v[92:93], v[102:103], v[22:23] op_sel:[1,0,0]
	s_waitcnt vmcnt(29)
	v_pk_fma_f32 v[8:9], v[30:31], v[104:105], v[8:9] op_sel_hi:[0,1,1]
	v_pk_fma_f32 v[12:13], v[38:39], v[104:105], v[12:13] op_sel_hi:[0,1,1]
	v_pk_fma_f32 v[10:11], v[46:47], v[104:105], v[10:11] op_sel_hi:[0,1,1]
	v_pk_fma_f32 v[16:17], v[54:55], v[104:105], v[16:17] op_sel_hi:[0,1,1]
	v_pk_fma_f32 v[14:15], v[62:63], v[104:105], v[14:15] op_sel_hi:[0,1,1]
	v_pk_fma_f32 v[20:21], v[70:71], v[104:105], v[20:21] op_sel_hi:[0,1,1]
	v_pk_fma_f32 v[18:19], v[78:79], v[104:105], v[18:19] op_sel_hi:[0,1,1]
	v_pk_fma_f32 v[24:25], v[86:87], v[104:105], v[24:25] op_sel_hi:[0,1,1]
	v_pk_fma_f32 v[22:23], v[94:95], v[104:105], v[22:23] op_sel_hi:[0,1,1]
	s_waitcnt vmcnt(28)
	v_pk_fma_f32 v[8:9], v[116:117], v[106:107], v[8:9] op_sel_hi:[0,1,1]
	v_pk_fma_f32 v[12:13], v[118:119], v[106:107], v[12:13] op_sel_hi:[0,1,1]
	v_pk_fma_f32 v[10:11], v[120:121], v[106:107], v[10:11] op_sel_hi:[0,1,1]
	v_pk_fma_f32 v[16:17], v[122:123], v[106:107], v[16:17] op_sel_hi:[0,1,1]
	v_pk_fma_f32 v[14:15], v[124:125], v[106:107], v[14:15] op_sel_hi:[0,1,1]
	v_pk_fma_f32 v[20:21], v[126:127], v[106:107], v[20:21] op_sel_hi:[0,1,1]
	v_pk_fma_f32 v[18:19], v[128:129], v[106:107], v[18:19] op_sel_hi:[0,1,1]
	v_pk_fma_f32 v[24:25], v[130:131], v[106:107], v[24:25] op_sel_hi:[0,1,1]
	v_pk_fma_f32 v[22:23], v[138:139], v[106:107], v[22:23] op_sel_hi:[0,1,1]
	s_waitcnt vmcnt(27)
	v_pk_fma_f32 v[8:9], v[32:33], v[108:109], v[8:9] op_sel_hi:[0,1,1]
	v_pk_fma_f32 v[12:13], v[40:41], v[108:109], v[12:13] op_sel_hi:[0,1,1]
	v_pk_fma_f32 v[10:11], v[48:49], v[108:109], v[10:11] op_sel_hi:[0,1,1]
	v_pk_fma_f32 v[16:17], v[56:57], v[108:109], v[16:17] op_sel_hi:[0,1,1]
	v_pk_fma_f32 v[14:15], v[64:65], v[108:109], v[14:15] op_sel_hi:[0,1,1]
	v_pk_fma_f32 v[20:21], v[72:73], v[108:109], v[20:21] op_sel_hi:[0,1,1]
	v_pk_fma_f32 v[18:19], v[80:81], v[108:109], v[18:19] op_sel_hi:[0,1,1]
	v_pk_fma_f32 v[24:25], v[88:89], v[108:109], v[24:25] op_sel_hi:[0,1,1]
	v_pk_fma_f32 v[22:23], v[96:97], v[108:109], v[22:23] op_sel_hi:[0,1,1]
	s_waitcnt vmcnt(26)
	v_pk_fma_f32 v[8:9], v[32:33], v[110:111], v[8:9] op_sel:[1,0,0]
	v_pk_fma_f32 v[12:13], v[40:41], v[110:111], v[12:13] op_sel:[1,0,0]
	v_pk_fma_f32 v[10:11], v[48:49], v[110:111], v[10:11] op_sel:[1,0,0]
	v_pk_fma_f32 v[16:17], v[56:57], v[110:111], v[16:17] op_sel:[1,0,0]
	v_pk_fma_f32 v[14:15], v[64:65], v[110:111], v[14:15] op_sel:[1,0,0]
	v_pk_fma_f32 v[20:21], v[72:73], v[110:111], v[20:21] op_sel:[1,0,0]
	v_pk_fma_f32 v[18:19], v[80:81], v[110:111], v[18:19] op_sel:[1,0,0]
	v_pk_fma_f32 v[24:25], v[88:89], v[110:111], v[24:25] op_sel:[1,0,0]
	v_pk_fma_f32 v[22:23], v[96:97], v[110:111], v[22:23] op_sel:[1,0,0]
	s_waitcnt vmcnt(25)
	v_pk_fma_f32 v[8:9], v[34:35], v[112:113], v[8:9] op_sel_hi:[0,1,1]
	v_pk_fma_f32 v[12:13], v[42:43], v[112:113], v[12:13] op_sel_hi:[0,1,1]
	v_pk_fma_f32 v[10:11], v[50:51], v[112:113], v[10:11] op_sel_hi:[0,1,1]
	v_pk_fma_f32 v[16:17], v[58:59], v[112:113], v[16:17] op_sel_hi:[0,1,1]
	v_pk_fma_f32 v[14:15], v[66:67], v[112:113], v[14:15] op_sel_hi:[0,1,1]
	v_pk_fma_f32 v[20:21], v[74:75], v[112:113], v[20:21] op_sel_hi:[0,1,1]
	v_pk_fma_f32 v[18:19], v[82:83], v[112:113], v[18:19] op_sel_hi:[0,1,1]
	v_pk_fma_f32 v[24:25], v[90:91], v[112:113], v[24:25] op_sel_hi:[0,1,1]
	v_pk_fma_f32 v[22:23], v[98:99], v[112:113], v[22:23] op_sel_hi:[0,1,1]
	s_waitcnt vmcnt(24)
; __global__ void __launch_bounds__(NTHR, 2) trunk_fwd(Args a) {
;     ...
;             for (int k0 = 0; k0 < 128; k0 += 8) { float2 wv[8];
; #pragma unroll
;                 for (int k = 0; k < 8; ++k) wv[k] = *(const float2*)(wp + (size_t)(k0 + k) * 6144);
; #pragma unroll
;                 for (int k = 0; k < 8; ++k)
; #pragma unroll
;                     for (int q = 0; q < 9; ++q) { const float sv = sS[q * 1024 + wave * 128 + k0 + k]; acc0[q] += sv * wv[k].x; acc1[q] += sv * wv[k].y; } }
	v_pk_fma_f32 v[8:9], v[132:133], v[114:115], v[8:9] op_sel_hi:[0,1,1]
	v_pk_fma_f32 v[12:13], v[134:135], v[114:115], v[12:13] op_sel_hi:[0,1,1]
	v_pk_fma_f32 v[10:11], v[136:137], v[114:115], v[10:11] op_sel_hi:[0,1,1]
	v_pk_fma_f32 v[16:17], v[140:141], v[114:115], v[16:17] op_sel_hi:[0,1,1]
	v_pk_fma_f32 v[14:15], v[142:143], v[114:115], v[14:15] op_sel_hi:[0,1,1]
	v_pk_fma_f32 v[20:21], v[144:145], v[114:115], v[20:21] op_sel_hi:[0,1,1]
	v_pk_fma_f32 v[18:19], v[146:147], v[114:115], v[18:19] op_sel_hi:[0,1,1]
	v_pk_fma_f32 v[24:25], v[148:149], v[114:115], v[24:25] op_sel_hi:[0,1,1]
	v_pk_fma_f32 v[22:23], v[150:151], v[114:115], v[22:23] op_sel_hi:[0,1,1]
	v_mov_b32_e32 v27, s9
	s_add_i32 s9, s9, 32
	ds_read_b128 v[28:31], v27
	ds_read_b128 v[32:35], v27 offset:16
	ds_read_b128 v[36:39], v27 offset:4096
	ds_read_b128 v[40:43], v27 offset:4112
	ds_read_b128 v[44:47], v27 offset:8192
	ds_read_b128 v[48:51], v27 offset:8208
	ds_read_b128 v[52:55], v27 offset:12288
	ds_read_b128 v[56:59], v27 offset:12304
	ds_read_b128 v[60:63], v27 offset:16384
	ds_read_b128 v[64:67], v27 offset:16400
	ds_read_b128 v[68:71], v27 offset:20480
	ds_read_b128 v[72:75], v27 offset:20496
	ds_read_b128 v[76:79], v27 offset:24576
	ds_read_b128 v[80:83], v27 offset:24592
	ds_read_b128 v[84:87], v27 offset:28672
	ds_read_b128 v[88:91], v27 offset:28688
	ds_read_b128 v[92:95], v27 offset:32768
	ds_read_b128 v[96:99], v27 offset:32784
	s_waitcnt lgkmcnt(14)
	v_mov_b32_e32 v116, v31
	v_mov_b32_e32 v118, v39
	s_waitcnt lgkmcnt(13)
	v_mov_b32_e32 v120, v47
	s_waitcnt lgkmcnt(11)
	v_mov_b32_e32 v122, v55
	s_waitcnt lgkmcnt(9)
	v_mov_b32_e32 v124, v63
	s_waitcnt lgkmcnt(7)
	v_mov_b32_e32 v126, v71
	s_waitcnt lgkmcnt(5)
	v_mov_b32_e32 v128, v79
	s_waitcnt lgkmcnt(3)
	v_mov_b32_e32 v130, v87
	s_waitcnt lgkmcnt(1)
	v_mov_b32_e32 v138, v95
	v_mov_b32_e32 v132, v35
	v_mov_b32_e32 v134, v43
	v_mov_b32_e32 v136, v51
	v_mov_b32_e32 v140, v59
	v_mov_b32_e32 v142, v67
	v_mov_b32_e32 v144, v75
	v_mov_b32_e32 v146, v83
	v_mov_b32_e32 v148, v91
	s_waitcnt lgkmcnt(0)
	v_mov_b32_e32 v150, v99
	s_waitcnt vmcnt(23)
	v_pk_fma_f32 v[8:9], v[28:29], v[194:195], v[8:9] op_sel_hi:[0,1,1]
	v_pk_fma_f32 v[12:13], v[36:37], v[194:195], v[12:13] op_sel_hi:[0,1,1]
	v_pk_fma_f32 v[10:11], v[44:45], v[194:195], v[10:11] op_sel_hi:[0,1,1]
	v_pk_fma_f32 v[16:17], v[52:53], v[194:195], v[16:17] op_sel_hi:[0,1,1]
	v_pk_fma_f32 v[14:15], v[60:61], v[194:195], v[14:15] op_sel_hi:[0,1,1]
	v_pk_fma_f32 v[20:21], v[68:69], v[194:195], v[20:21] op_sel_hi:[0,1,1]
	v_pk_fma_f32 v[18:19], v[76:77], v[194:195], v[18:19] op_sel_hi:[0,1,1]
	v_pk_fma_f32 v[24:25], v[84:85], v[194:195], v[24:25] op_sel_hi:[0,1,1]
	v_pk_fma_f32 v[22:23], v[92:93], v[194:195], v[22:23] op_sel_hi:[0,1,1]
	s_waitcnt vmcnt(22)
	v_pk_fma_f32 v[8:9], v[28:29], v[196:197], v[8:9] op_sel:[1,0,0]
	v_pk_fma_f32 v[12:13], v[36:37], v[196:197], v[12:13] op_sel:[1,0,0]
	v_pk_fma_f32 v[10:11], v[44:45], v[196:197], v[10:11] op_sel:[1,0,0]
	v_pk_fma_f32 v[16:17], v[52:53], v[196:197], v[16:17] op_sel:[1,0,0]
	v_pk_fma_f32 v[14:15], v[60:61], v[196:197], v[14:15] op_sel:[1,0,0]
	v_pk_fma_f32 v[20:21], v[68:69], v[196:197], v[20:21] op_sel:[1,0,0]
	v_pk_fma_f32 v[18:19], v[76:77], v[196:197], v[18:19] op_sel:[1,0,0]
	v_pk_fma_f32 v[24:25], v[84:85], v[196:197], v[24:25] op_sel:[1,0,0]
	v_pk_fma_f32 v[22:23], v[92:93], v[196:197], v[22:23] op_sel:[1,0,0]
	s_waitcnt vmcnt(21)
	v_pk_fma_f32 v[8:9], v[30:31], v[198:199], v[8:9] op_sel_hi:[0,1,1]
	v_pk_fma_f32 v[12:13], v[38:39], v[198:199], v[12:13] op_sel_hi:[0,1,1]
	v_pk_fma_f32 v[10:11], v[46:47], v[198:199], v[10:11] op_sel_hi:[0,1,1]
	v_pk_fma_f32 v[16:17], v[54:55], v[198:199], v[16:17] op_sel_hi:[0,1,1]
	v_pk_fma_f32 v[14:15], v[62:63], v[198:199], v[14:15] op_sel_hi:[0,1,1]
	v_pk_fma_f32 v[20:21], v[70:71], v[198:199], v[20:21] op_sel_hi:[0,1,1]
	v_pk_fma_f32 v[18:19], v[78:79], v[198:199], v[18:19] op_sel_hi:[0,1,1]
	v_pk_fma_f32 v[24:25], v[86:87], v[198:199], v[24:25] op_sel_hi:[0,1,1]
	v_pk_fma_f32 v[22:23], v[94:95], v[198:199], v[22:23] op_sel_hi:[0,1,1]
	s_waitcnt vmcnt(20)
	v_pk_fma_f32 v[8:9], v[116:117], v[200:201], v[8:9] op_sel_hi:[0,1,1]
	v_pk_fma_f32 v[12:13], v[118:119], v[200:201], v[12:13] op_sel_hi:[0,1,1]
	v_pk_fma_f32 v[10:11], v[120:121], v[200:201], v[10:11] op_sel_hi:[0,1,1]
	v_pk_fma_f32 v[16:17], v[122:123], v[200:201], v[16:17] op_sel_hi:[0,1,1]
	v_pk_fma_f32 v[14:15], v[124:125], v[200:201], v[14:15] op_sel_hi:[0,1,1]
	v_pk_fma_f32 v[20:21], v[126:127], v[200:201], v[20:21] op_sel_hi:[0,1,1]
	v_pk_fma_f32 v[18:19], v[128:129], v[200:201], v[18:19] op_sel_hi:[0,1,1]
	v_pk_fma_f32 v[24:25], v[130:131], v[200:201], v[24:25] op_sel_hi:[0,1,1]
	v_pk_fma_f32 v[22:23], v[138:139], v[200:201], v[22:23] op_sel_hi:[0,1,1]
	s_waitcnt vmcnt(19)
	v_pk_fma_f32 v[8:9], v[32:33], v[202:203], v[8:9] op_sel_hi:[0,1,1]
	v_pk_fma_f32 v[12:13], v[40:41], v[202:203], v[12:13] op_sel_hi:[0,1,1]
	v_pk_fma_f32 v[10:11], v[48:49], v[202:203], v[10:11] op_sel_hi:[0,1,1]
	v_pk_fma_f32 v[16:17], v[56:57], v[202:203], v[16:17] op_sel_hi:[0,1,1]
	v_pk_fma_f32 v[14:15], v[64:65], v[202:203], v[14:15] op_sel_hi:[0,1,1]
	v_pk_fma_f32 v[20:21], v[72:73], v[202:203], v[20:21] op_sel_hi:[0,1,1]
	v_pk_fma_f32 v[18:19], v[80:81], v[202:203], v[18:19] op_sel_hi:[0,1,1]
	v_pk_fma_f32 v[24:25], v[88:89], v[202:203], v[24:25] op_sel_hi:[0,1,1]
	v_pk_fma_f32 v[22:23], v[96:97], v[202:203], v[22:23] op_sel_hi:[0,1,1]
	s_waitcnt vmcnt(18)
; __global__ void __launch_bounds__(NTHR, 2) trunk_fwd(Args a) {
;     ...
;             for (int k0 = 0; k0 < 128; k0 += 8) { float2 wv[8];
; #pragma unroll
;                 for (int k = 0; k < 8; ++k) wv[k] = *(const float2*)(wp + (size_t)(k0 + k) * 6144);
; #pragma unroll
;                 for (int k = 0; k < 8; ++k)
; #pragma unroll
;                     for (int q = 0; q < 9; ++q) { const float sv = sS[q * 1024 + wave * 128 + k0 + k]; acc0[q] += sv * wv[k].x; acc1[q] += sv * wv[k].y; } }
	v_pk_fma_f32 v[8:9], v[32:33], v[204:205], v[8:9] op_sel:[1,0,0]
	v_pk_fma_f32 v[12:13], v[40:41], v[204:205], v[12:13] op_sel:[1,0,0]
	v_pk_fma_f32 v[10:11], v[48:49], v[204:205], v[10:11] op_sel:[1,0,0]
	v_pk_fma_f32 v[16:17], v[56:57], v[204:205], v[16:17] op_sel:[1,0,0]
	v_pk_fma_f32 v[14:15], v[64:65], v[204:205], v[14:15] op_sel:[1,0,0]
	v_pk_fma_f32 v[20:21], v[72:73], v[204:205], v[20:21] op_sel:[1,0,0]
	v_pk_fma_f32 v[18:19], v[80:81], v[204:205], v[18:19] op_sel:[1,0,0]
	v_pk_fma_f32 v[24:25], v[88:89], v[204:205], v[24:25] op_sel:[1,0,0]
	v_pk_fma_f32 v[22:23], v[96:97], v[204:205], v[22:23] op_sel:[1,0,0]
	s_waitcnt vmcnt(17)
	v_pk_fma_f32 v[8:9], v[34:35], v[206:207], v[8:9] op_sel_hi:[0,1,1]
	v_pk_fma_f32 v[12:13], v[42:43], v[206:207], v[12:13] op_sel_hi:[0,1,1]
	v_pk_fma_f32 v[10:11], v[50:51], v[206:207], v[10:11] op_sel_hi:[0,1,1]
	v_pk_fma_f32 v[16:17], v[58:59], v[206:207], v[16:17] op_sel_hi:[0,1,1]
	v_pk_fma_f32 v[14:15], v[66:67], v[206:207], v[14:15] op_sel_hi:[0,1,1]
	v_pk_fma_f32 v[20:21], v[74:75], v[206:207], v[20:21] op_sel_hi:[0,1,1]
	v_pk_fma_f32 v[18:19], v[82:83], v[206:207], v[18:19] op_sel_hi:[0,1,1]
	v_pk_fma_f32 v[24:25], v[90:91], v[206:207], v[24:25] op_sel_hi:[0,1,1]
	v_pk_fma_f32 v[22:23], v[98:99], v[206:207], v[22:23] op_sel_hi:[0,1,1]
	s_waitcnt vmcnt(16)
	v_pk_fma_f32 v[8:9], v[132:133], v[208:209], v[8:9] op_sel_hi:[0,1,1]
	v_pk_fma_f32 v[12:13], v[134:135], v[208:209], v[12:13] op_sel_hi:[0,1,1]
	v_pk_fma_f32 v[10:11], v[136:137], v[208:209], v[10:11] op_sel_hi:[0,1,1]
	v_pk_fma_f32 v[16:17], v[140:141], v[208:209], v[16:17] op_sel_hi:[0,1,1]
	v_pk_fma_f32 v[14:15], v[142:143], v[208:209], v[14:15] op_sel_hi:[0,1,1]
	v_pk_fma_f32 v[20:21], v[144:145], v[208:209], v[20:21] op_sel_hi:[0,1,1]
	v_pk_fma_f32 v[18:19], v[146:147], v[208:209], v[18:19] op_sel_hi:[0,1,1]
	v_pk_fma_f32 v[24:25], v[148:149], v[208:209], v[24:25] op_sel_hi:[0,1,1]
	v_pk_fma_f32 v[22:23], v[150:151], v[208:209], v[22:23] op_sel_hi:[0,1,1]
	v_mov_b32_e32 v27, s9
	s_add_i32 s9, s9, 32
	ds_read_b128 v[28:31], v27
	ds_read_b128 v[32:35], v27 offset:16
	ds_read_b128 v[36:39], v27 offset:4096
	ds_read_b128 v[40:43], v27 offset:4112
	ds_read_b128 v[44:47], v27 offset:8192
	ds_read_b128 v[48:51], v27 offset:8208
	ds_read_b128 v[52:55], v27 offset:12288
	ds_read_b128 v[56:59], v27 offset:12304
	ds_read_b128 v[60:63], v27 offset:16384
	ds_read_b128 v[64:67], v27 offset:16400
	ds_read_b128 v[68:71], v27 offset:20480
	ds_read_b128 v[72:75], v27 offset:20496
	ds_read_b128 v[76:79], v27 offset:24576
	ds_read_b128 v[80:83], v27 offset:24592
	ds_read_b128 v[84:87], v27 offset:28672
	ds_read_b128 v[88:91], v27 offset:28688
	ds_read_b128 v[92:95], v27 offset:32768
	ds_read_b128 v[96:99], v27 offset:32784
	s_waitcnt lgkmcnt(14)
	v_mov_b32_e32 v116, v31
	v_mov_b32_e32 v118, v39
	s_waitcnt lgkmcnt(13)
	v_mov_b32_e32 v120, v47
	s_waitcnt lgkmcnt(11)
	v_mov_b32_e32 v122, v55
	s_waitcnt lgkmcnt(9)
	v_mov_b32_e32 v124, v63
	s_waitcnt lgkmcnt(7)
	v_mov_b32_e32 v126, v71
	s_waitcnt lgkmcnt(5)
	v_mov_b32_e32 v128, v79
	s_waitcnt lgkmcnt(3)
	v_mov_b32_e32 v130, v87
	s_waitcnt lgkmcnt(1)
	v_mov_b32_e32 v138, v95
	v_mov_b32_e32 v132, v35
	v_mov_b32_e32 v134, v43
	v_mov_b32_e32 v136, v51
	v_mov_b32_e32 v140, v59
	v_mov_b32_e32 v142, v67
	v_mov_b32_e32 v144, v75
	v_mov_b32_e32 v146, v83
	v_mov_b32_e32 v148, v91
	s_waitcnt lgkmcnt(0)
	v_mov_b32_e32 v150, v99
	s_waitcnt vmcnt(15)
	v_pk_fma_f32 v[8:9], v[28:29], v[214:215], v[8:9] op_sel_hi:[0,1,1]
	v_pk_fma_f32 v[12:13], v[36:37], v[214:215], v[12:13] op_sel_hi:[0,1,1]
	v_pk_fma_f32 v[10:11], v[44:45], v[214:215], v[10:11] op_sel_hi:[0,1,1]
	v_pk_fma_f32 v[16:17], v[52:53], v[214:215], v[16:17] op_sel_hi:[0,1,1]
	v_pk_fma_f32 v[14:15], v[60:61], v[214:215], v[14:15] op_sel_hi:[0,1,1]
	v_pk_fma_f32 v[20:21], v[68:69], v[214:215], v[20:21] op_sel_hi:[0,1,1]
	v_pk_fma_f32 v[18:19], v[76:77], v[214:215], v[18:19] op_sel_hi:[0,1,1]
	v_pk_fma_f32 v[24:25], v[84:85], v[214:215], v[24:25] op_sel_hi:[0,1,1]
	v_pk_fma_f32 v[22:23], v[92:93], v[214:215], v[22:23] op_sel_hi:[0,1,1]
	s_waitcnt vmcnt(14)
	v_pk_fma_f32 v[8:9], v[28:29], v[216:217], v[8:9] op_sel:[1,0,0]
	v_pk_fma_f32 v[12:13], v[36:37], v[216:217], v[12:13] op_sel:[1,0,0]
	v_pk_fma_f32 v[10:11], v[44:45], v[216:217], v[10:11] op_sel:[1,0,0]
	v_pk_fma_f32 v[16:17], v[52:53], v[216:217], v[16:17] op_sel:[1,0,0]
	v_pk_fma_f32 v[14:15], v[60:61], v[216:217], v[14:15] op_sel:[1,0,0]
	v_pk_fma_f32 v[20:21], v[68:69], v[216:217], v[20:21] op_sel:[1,0,0]
	v_pk_fma_f32 v[18:19], v[76:77], v[216:217], v[18:19] op_sel:[1,0,0]
	v_pk_fma_f32 v[24:25], v[84:85], v[216:217], v[24:25] op_sel:[1,0,0]
	v_pk_fma_f32 v[22:23], v[92:93], v[216:217], v[22:23] op_sel:[1,0,0]
	s_waitcnt vmcnt(13)
	v_pk_fma_f32 v[8:9], v[30:31], v[218:219], v[8:9] op_sel_hi:[0,1,1]
	v_pk_fma_f32 v[12:13], v[38:39], v[218:219], v[12:13] op_sel_hi:[0,1,1]
	v_pk_fma_f32 v[10:11], v[46:47], v[218:219], v[10:11] op_sel_hi:[0,1,1]
	v_pk_fma_f32 v[16:17], v[54:55], v[218:219], v[16:17] op_sel_hi:[0,1,1]
	v_pk_fma_f32 v[14:15], v[62:63], v[218:219], v[14:15] op_sel_hi:[0,1,1]
	v_pk_fma_f32 v[20:21], v[70:71], v[218:219], v[20:21] op_sel_hi:[0,1,1]
	v_pk_fma_f32 v[18:19], v[78:79], v[218:219], v[18:19] op_sel_hi:[0,1,1]
	v_pk_fma_f32 v[24:25], v[86:87], v[218:219], v[24:25] op_sel_hi:[0,1,1]
	v_pk_fma_f32 v[22:23], v[94:95], v[218:219], v[22:23] op_sel_hi:[0,1,1]
	s_waitcnt vmcnt(12)
; __global__ void __launch_bounds__(NTHR, 2) trunk_fwd(Args a) {
;     ...
;             for (int k0 = 0; k0 < 128; k0 += 8) { float2 wv[8];
; #pragma unroll
;                 for (int k = 0; k < 8; ++k) wv[k] = *(const float2*)(wp + (size_t)(k0 + k) * 6144);
; #pragma unroll
;                 for (int k = 0; k < 8; ++k)
; #pragma unroll
;                     for (int q = 0; q < 9; ++q) { const float sv = sS[q * 1024 + wave * 128 + k0 + k]; acc0[q] += sv * wv[k].x; acc1[q] += sv * wv[k].y; } }
	v_pk_fma_f32 v[8:9], v[116:117], v[220:221], v[8:9] op_sel_hi:[0,1,1]
	v_pk_fma_f32 v[12:13], v[118:119], v[220:221], v[12:13] op_sel_hi:[0,1,1]
	v_pk_fma_f32 v[10:11], v[120:121], v[220:221], v[10:11] op_sel_hi:[0,1,1]
	v_pk_fma_f32 v[16:17], v[122:123], v[220:221], v[16:17] op_sel_hi:[0,1,1]
	v_pk_fma_f32 v[14:15], v[124:125], v[220:221], v[14:15] op_sel_hi:[0,1,1]
	v_pk_fma_f32 v[20:21], v[126:127], v[220:221], v[20:21] op_sel_hi:[0,1,1]
	v_pk_fma_f32 v[18:19], v[128:129], v[220:221], v[18:19] op_sel_hi:[0,1,1]
	v_pk_fma_f32 v[24:25], v[130:131], v[220:221], v[24:25] op_sel_hi:[0,1,1]
	v_pk_fma_f32 v[22:23], v[138:139], v[220:221], v[22:23] op_sel_hi:[0,1,1]
	s_waitcnt vmcnt(11)
	v_pk_fma_f32 v[8:9], v[32:33], v[222:223], v[8:9] op_sel_hi:[0,1,1]
	v_pk_fma_f32 v[12:13], v[40:41], v[222:223], v[12:13] op_sel_hi:[0,1,1]
	v_pk_fma_f32 v[10:11], v[48:49], v[222:223], v[10:11] op_sel_hi:[0,1,1]
	v_pk_fma_f32 v[16:17], v[56:57], v[222:223], v[16:17] op_sel_hi:[0,1,1]
	v_pk_fma_f32 v[14:15], v[64:65], v[222:223], v[14:15] op_sel_hi:[0,1,1]
	v_pk_fma_f32 v[20:21], v[72:73], v[222:223], v[20:21] op_sel_hi:[0,1,1]
	v_pk_fma_f32 v[18:19], v[80:81], v[222:223], v[18:19] op_sel_hi:[0,1,1]
	v_pk_fma_f32 v[24:25], v[88:89], v[222:223], v[24:25] op_sel_hi:[0,1,1]
	v_pk_fma_f32 v[22:23], v[96:97], v[222:223], v[22:23] op_sel_hi:[0,1,1]
	s_waitcnt vmcnt(10)
	v_pk_fma_f32 v[8:9], v[32:33], v[224:225], v[8:9] op_sel:[1,0,0]
	v_pk_fma_f32 v[12:13], v[40:41], v[224:225], v[12:13] op_sel:[1,0,0]
	v_pk_fma_f32 v[10:11], v[48:49], v[224:225], v[10:11] op_sel:[1,0,0]
	v_pk_fma_f32 v[16:17], v[56:57], v[224:225], v[16:17] op_sel:[1,0,0]
	v_pk_fma_f32 v[14:15], v[64:65], v[224:225], v[14:15] op_sel:[1,0,0]
	v_pk_fma_f32 v[20:21], v[72:73], v[224:225], v[20:21] op_sel:[1,0,0]
	v_pk_fma_f32 v[18:19], v[80:81], v[224:225], v[18:19] op_sel:[1,0,0]
	v_pk_fma_f32 v[24:25], v[88:89], v[224:225], v[24:25] op_sel:[1,0,0]
	v_pk_fma_f32 v[22:23], v[96:97], v[224:225], v[22:23] op_sel:[1,0,0]
	s_waitcnt vmcnt(9)
	v_pk_fma_f32 v[8:9], v[34:35], v[226:227], v[8:9] op_sel_hi:[0,1,1]
	v_pk_fma_f32 v[12:13], v[42:43], v[226:227], v[12:13] op_sel_hi:[0,1,1]
	v_pk_fma_f32 v[10:11], v[50:51], v[226:227], v[10:11] op_sel_hi:[0,1,1]
	v_pk_fma_f32 v[16:17], v[58:59], v[226:227], v[16:17] op_sel_hi:[0,1,1]
	v_pk_fma_f32 v[14:15], v[66:67], v[226:227], v[14:15] op_sel_hi:[0,1,1]
	v_pk_fma_f32 v[20:21], v[74:75], v[226:227], v[20:21] op_sel_hi:[0,1,1]
	v_pk_fma_f32 v[18:19], v[82:83], v[226:227], v[18:19] op_sel_hi:[0,1,1]
	v_pk_fma_f32 v[24:25], v[90:91], v[226:227], v[24:25] op_sel_hi:[0,1,1]
	v_pk_fma_f32 v[22:23], v[98:99], v[226:227], v[22:23] op_sel_hi:[0,1,1]
	s_waitcnt vmcnt(8)
	v_pk_fma_f32 v[8:9], v[132:133], v[228:229], v[8:9] op_sel_hi:[0,1,1]
	v_pk_fma_f32 v[12:13], v[134:135], v[228:229], v[12:13] op_sel_hi:[0,1,1]
	v_pk_fma_f32 v[10:11], v[136:137], v[228:229], v[10:11] op_sel_hi:[0,1,1]
	v_pk_fma_f32 v[16:17], v[140:141], v[228:229], v[16:17] op_sel_hi:[0,1,1]
	v_pk_fma_f32 v[14:15], v[142:143], v[228:229], v[14:15] op_sel_hi:[0,1,1]
	v_pk_fma_f32 v[20:21], v[144:145], v[228:229], v[20:21] op_sel_hi:[0,1,1]
	v_pk_fma_f32 v[18:19], v[146:147], v[228:229], v[18:19] op_sel_hi:[0,1,1]
	v_pk_fma_f32 v[24:25], v[148:149], v[228:229], v[24:25] op_sel_hi:[0,1,1]
	v_pk_fma_f32 v[22:23], v[150:151], v[228:229], v[22:23] op_sel_hi:[0,1,1]
	v_mov_b32_e32 v27, s9
	s_add_i32 s9, s9, 32
	ds_read_b128 v[28:31], v27
	ds_read_b128 v[32:35], v27 offset:16
	ds_read_b128 v[36:39], v27 offset:4096
	ds_read_b128 v[40:43], v27 offset:4112
	ds_read_b128 v[44:47], v27 offset:8192
	ds_read_b128 v[48:51], v27 offset:8208
	ds_read_b128 v[52:55], v27 offset:12288
	ds_read_b128 v[56:59], v27 offset:12304
	ds_read_b128 v[60:63], v27 offset:16384
	ds_read_b128 v[64:67], v27 offset:16400
	ds_read_b128 v[68:71], v27 offset:20480
	ds_read_b128 v[72:75], v27 offset:20496
	ds_read_b128 v[76:79], v27 offset:24576
	ds_read_b128 v[80:83], v27 offset:24592
	ds_read_b128 v[84:87], v27 offset:28672
	ds_read_b128 v[88:91], v27 offset:28688
	ds_read_b128 v[92:95], v27 offset:32768
	ds_read_b128 v[96:99], v27 offset:32784
	s_waitcnt lgkmcnt(14)
	v_mov_b32_e32 v116, v31
	v_mov_b32_e32 v118, v39
	s_waitcnt lgkmcnt(13)
	v_mov_b32_e32 v120, v47
	s_waitcnt lgkmcnt(11)
	v_mov_b32_e32 v122, v55
	s_waitcnt lgkmcnt(9)
	v_mov_b32_e32 v124, v63
	s_waitcnt lgkmcnt(7)
	v_mov_b32_e32 v126, v71
	s_waitcnt lgkmcnt(5)
	v_mov_b32_e32 v128, v79
	s_waitcnt lgkmcnt(3)
	v_mov_b32_e32 v130, v87
	s_waitcnt lgkmcnt(1)
	v_mov_b32_e32 v138, v95
	v_mov_b32_e32 v132, v35
	v_mov_b32_e32 v134, v43
	v_mov_b32_e32 v136, v51
	v_mov_b32_e32 v140, v59
	v_mov_b32_e32 v142, v67
	v_mov_b32_e32 v144, v75
	v_mov_b32_e32 v146, v83
	v_mov_b32_e32 v148, v91
	s_waitcnt lgkmcnt(0)
	v_mov_b32_e32 v150, v99
	s_waitcnt vmcnt(7)
	v_pk_fma_f32 v[8:9], v[28:29], v[230:231], v[8:9] op_sel_hi:[0,1,1]
	v_pk_fma_f32 v[12:13], v[36:37], v[230:231], v[12:13] op_sel_hi:[0,1,1]
	v_pk_fma_f32 v[10:11], v[44:45], v[230:231], v[10:11] op_sel_hi:[0,1,1]
	v_pk_fma_f32 v[16:17], v[52:53], v[230:231], v[16:17] op_sel_hi:[0,1,1]
	v_pk_fma_f32 v[14:15], v[60:61], v[230:231], v[14:15] op_sel_hi:[0,1,1]
	v_pk_fma_f32 v[20:21], v[68:69], v[230:231], v[20:21] op_sel_hi:[0,1,1]
	v_pk_fma_f32 v[18:19], v[76:77], v[230:231], v[18:19] op_sel_hi:[0,1,1]
	v_pk_fma_f32 v[24:25], v[84:85], v[230:231], v[24:25] op_sel_hi:[0,1,1]
	v_pk_fma_f32 v[22:23], v[92:93], v[230:231], v[22:23] op_sel_hi:[0,1,1]
	s_waitcnt vmcnt(6)
; __global__ void __launch_bounds__(NTHR, 2) trunk_fwd(Args a) {
;     ...
;             for (int k0 = 0; k0 < 128; k0 += 8) { float2 wv[8];
; #pragma unroll
;                 for (int k = 0; k < 8; ++k) wv[k] = *(const float2*)(wp + (size_t)(k0 + k) * 6144);
; #pragma unroll
;                 for (int k = 0; k < 8; ++k)
; #pragma unroll
;                     for (int q = 0; q < 9; ++q) { const float sv = sS[q * 1024 + wave * 128 + k0 + k]; acc0[q] += sv * wv[k].x; acc1[q] += sv * wv[k].y; } }
; #pragma unroll
;             for (int q = 0; q < 9; ++q) { part[(wave * 9 + q) * 128 + 2 * lane] = acc0[q]; part[(wave * 9 + q) * 128 + 2 * lane + 1] = acc1[q]; }
;             __syncthreads();
;             for (int i = tid; i < 9 * 128; i += NTHR) { float s = 0.f;
; #pragma unroll
;                 for (int w = 0; w < 8; ++w) s += part[w * 1152 + i];
;                 const int q = i >> 7, nn = (unit % 48) * 128 + (i & 127); MOD[((size_t)l * 9 + q) * 6144 + nn] = s + a.b_ada[(size_t)l * 6144 + nn]; }
	v_pk_fma_f32 v[8:9], v[28:29], v[232:233], v[8:9] op_sel:[1,0,0]
	v_pk_fma_f32 v[12:13], v[36:37], v[232:233], v[12:13] op_sel:[1,0,0]
	v_pk_fma_f32 v[10:11], v[44:45], v[232:233], v[10:11] op_sel:[1,0,0]
	v_pk_fma_f32 v[16:17], v[52:53], v[232:233], v[16:17] op_sel:[1,0,0]
	v_pk_fma_f32 v[14:15], v[60:61], v[232:233], v[14:15] op_sel:[1,0,0]
	v_pk_fma_f32 v[20:21], v[68:69], v[232:233], v[20:21] op_sel:[1,0,0]
	v_pk_fma_f32 v[18:19], v[76:77], v[232:233], v[18:19] op_sel:[1,0,0]
	v_pk_fma_f32 v[24:25], v[84:85], v[232:233], v[24:25] op_sel:[1,0,0]
	v_pk_fma_f32 v[22:23], v[92:93], v[232:233], v[22:23] op_sel:[1,0,0]
	s_waitcnt vmcnt(5)
	v_pk_fma_f32 v[8:9], v[30:31], v[234:235], v[8:9] op_sel_hi:[0,1,1]
	v_pk_fma_f32 v[12:13], v[38:39], v[234:235], v[12:13] op_sel_hi:[0,1,1]
	v_pk_fma_f32 v[10:11], v[46:47], v[234:235], v[10:11] op_sel_hi:[0,1,1]
	v_pk_fma_f32 v[16:17], v[54:55], v[234:235], v[16:17] op_sel_hi:[0,1,1]
	v_pk_fma_f32 v[14:15], v[62:63], v[234:235], v[14:15] op_sel_hi:[0,1,1]
	v_pk_fma_f32 v[20:21], v[70:71], v[234:235], v[20:21] op_sel_hi:[0,1,1]
	v_pk_fma_f32 v[18:19], v[78:79], v[234:235], v[18:19] op_sel_hi:[0,1,1]
	v_pk_fma_f32 v[24:25], v[86:87], v[234:235], v[24:25] op_sel_hi:[0,1,1]
	v_pk_fma_f32 v[22:23], v[94:95], v[234:235], v[22:23] op_sel_hi:[0,1,1]
	s_waitcnt vmcnt(4)
	v_pk_fma_f32 v[8:9], v[116:117], v[236:237], v[8:9] op_sel_hi:[0,1,1]
	v_pk_fma_f32 v[12:13], v[118:119], v[236:237], v[12:13] op_sel_hi:[0,1,1]
	v_pk_fma_f32 v[10:11], v[120:121], v[236:237], v[10:11] op_sel_hi:[0,1,1]
	v_pk_fma_f32 v[16:17], v[122:123], v[236:237], v[16:17] op_sel_hi:[0,1,1]
	v_pk_fma_f32 v[14:15], v[124:125], v[236:237], v[14:15] op_sel_hi:[0,1,1]
	v_pk_fma_f32 v[20:21], v[126:127], v[236:237], v[20:21] op_sel_hi:[0,1,1]
	v_pk_fma_f32 v[18:19], v[128:129], v[236:237], v[18:19] op_sel_hi:[0,1,1]
	v_pk_fma_f32 v[24:25], v[130:131], v[236:237], v[24:25] op_sel_hi:[0,1,1]
	v_pk_fma_f32 v[22:23], v[138:139], v[236:237], v[22:23] op_sel_hi:[0,1,1]
	s_waitcnt vmcnt(3)
	v_pk_fma_f32 v[8:9], v[32:33], v[238:239], v[8:9] op_sel_hi:[0,1,1]
	v_pk_fma_f32 v[12:13], v[40:41], v[238:239], v[12:13] op_sel_hi:[0,1,1]
	v_pk_fma_f32 v[10:11], v[48:49], v[238:239], v[10:11] op_sel_hi:[0,1,1]
	v_pk_fma_f32 v[16:17], v[56:57], v[238:239], v[16:17] op_sel_hi:[0,1,1]
	v_pk_fma_f32 v[14:15], v[64:65], v[238:239], v[14:15] op_sel_hi:[0,1,1]
	v_pk_fma_f32 v[20:21], v[72:73], v[238:239], v[20:21] op_sel_hi:[0,1,1]
	v_pk_fma_f32 v[18:19], v[80:81], v[238:239], v[18:19] op_sel_hi:[0,1,1]
	v_pk_fma_f32 v[24:25], v[88:89], v[238:239], v[24:25] op_sel_hi:[0,1,1]
	v_pk_fma_f32 v[22:23], v[96:97], v[238:239], v[22:23] op_sel_hi:[0,1,1]
	s_waitcnt vmcnt(2)
	v_pk_fma_f32 v[8:9], v[32:33], v[240:241], v[8:9] op_sel:[1,0,0]
	v_pk_fma_f32 v[12:13], v[40:41], v[240:241], v[12:13] op_sel:[1,0,0]
	v_pk_fma_f32 v[10:11], v[48:49], v[240:241], v[10:11] op_sel:[1,0,0]
	v_pk_fma_f32 v[16:17], v[56:57], v[240:241], v[16:17] op_sel:[1,0,0]
	v_pk_fma_f32 v[14:15], v[64:65], v[240:241], v[14:15] op_sel:[1,0,0]
	v_pk_fma_f32 v[20:21], v[72:73], v[240:241], v[20:21] op_sel:[1,0,0]
	v_pk_fma_f32 v[18:19], v[80:81], v[240:241], v[18:19] op_sel:[1,0,0]
	v_pk_fma_f32 v[24:25], v[88:89], v[240:241], v[24:25] op_sel:[1,0,0]
	v_pk_fma_f32 v[22:23], v[96:97], v[240:241], v[22:23] op_sel:[1,0,0]
	s_waitcnt vmcnt(1)
	v_pk_fma_f32 v[8:9], v[34:35], v[242:243], v[8:9] op_sel_hi:[0,1,1]
	v_pk_fma_f32 v[12:13], v[42:43], v[242:243], v[12:13] op_sel_hi:[0,1,1]
	v_pk_fma_f32 v[10:11], v[50:51], v[242:243], v[10:11] op_sel_hi:[0,1,1]
	v_pk_fma_f32 v[16:17], v[58:59], v[242:243], v[16:17] op_sel_hi:[0,1,1]
	v_pk_fma_f32 v[14:15], v[66:67], v[242:243], v[14:15] op_sel_hi:[0,1,1]
	v_pk_fma_f32 v[20:21], v[74:75], v[242:243], v[20:21] op_sel_hi:[0,1,1]
	v_pk_fma_f32 v[18:19], v[82:83], v[242:243], v[18:19] op_sel_hi:[0,1,1]
	v_pk_fma_f32 v[24:25], v[90:91], v[242:243], v[24:25] op_sel_hi:[0,1,1]
	v_pk_fma_f32 v[22:23], v[98:99], v[242:243], v[22:23] op_sel_hi:[0,1,1]
	s_waitcnt vmcnt(0)
	v_pk_fma_f32 v[8:9], v[132:133], v[244:245], v[8:9] op_sel_hi:[0,1,1]
	v_pk_fma_f32 v[12:13], v[134:135], v[244:245], v[12:13] op_sel_hi:[0,1,1]
	v_pk_fma_f32 v[10:11], v[136:137], v[244:245], v[10:11] op_sel_hi:[0,1,1]
	v_pk_fma_f32 v[16:17], v[140:141], v[244:245], v[16:17] op_sel_hi:[0,1,1]
	v_pk_fma_f32 v[14:15], v[142:143], v[244:245], v[14:15] op_sel_hi:[0,1,1]
	v_pk_fma_f32 v[20:21], v[144:145], v[244:245], v[20:21] op_sel_hi:[0,1,1]
	v_pk_fma_f32 v[18:19], v[146:147], v[244:245], v[18:19] op_sel_hi:[0,1,1]
	v_pk_fma_f32 v[24:25], v[148:149], v[244:245], v[24:25] op_sel_hi:[0,1,1]
	v_pk_fma_f32 v[22:23], v[150:151], v[244:245], v[22:23] op_sel_hi:[0,1,1]
	ds_write2st64_b64 v26, v[8:9], v[12:13] offset0:72 offset1:73
	ds_write2st64_b64 v26, v[10:11], v[16:17] offset0:74 offset1:75
	ds_write2st64_b64 v26, v[14:15], v[20:21] offset0:76 offset1:77
	ds_write2st64_b64 v26, v[18:19], v[24:25] offset0:78 offset1:79
	ds_write_b64 v26, v[22:23] offset:40960
	s_waitcnt lgkmcnt(0)
	s_barrier
	s_and_saveexec_b64 s[8:9], vcc
	s_cbranch_execz .LBB0_21
	s_mul_i32 s4, s10, 48
	s_sub_i32 s12, s27, s4
	s_mul_i32 s4, s10, 0x6000
	v_lshl_or_b32 v6, s12, 7, v3
	s_mul_hi_i32 s5, s10, 0x6000
	s_add_u32 s4, s46, s4
	v_ashrrev_i32_e32 v7, 31, v6
	s_addc_u32 s5, s47, s5
	v_lshlrev_b64 v[8:9], 2, v[6:7]
	v_lshl_add_u64 v[6:7], s[4:5], 0, v[8:9]
	v_readlane_b32 s4, v252, 6
	v_readlane_b32 s5, v252, 7
	s_mul_hi_i32 s11, s10, 9
	s_mul_i32 s10, s10, 9
	v_lshl_add_u64 v[8:9], s[4:5], 0, v[8:9]
	s_mov_b64 s[12:13], 0
	v_mov_b32_e32 v10, v5
	v_mov_b32_e32 v11, v4
